# back-edge rotation (7.11) on the four peeled GEMM K-loops: loop-carried SALU moved in front of the loop-back barrier
# baseline (speedup 1.0000x reference)
; #define PG8_STAGE(bufoff, gbase, voff) do { _Pragma("unroll") for (int _i = 0; _i < 2; ++_i) \
;         __builtin_amdgcn_global_load_lds((const unsigned*)((const char*)(gbase) + (voff)[_i]), (PG8_LAS unsigned*)(lds + (bufoff) + ldsw + _i * 8192), 16, 0, 0); } while (0)
; #define PG8_LDA(dst, b, h) do { _Pragma("unroll") for (int m = 0; m < 4; ++m) _Pragma("unroll") for (int k = 0; k < 2; ++k) dst[m][k] = *(const PG8_LAS bf16x8*)(lds + PG8_SA(b, h) + aoff + m * 2048 + k * 1024); } while (0)
; #define PG8_LDB(dst, b, h) do { _Pragma("unroll") for (int n = 0; n < 2; ++n) _Pragma("unroll") for (int k = 0; k < 2; ++k) dst[n][k] = *(const PG8_LAS bf16x8*)(lds + PG8_SB(b, h) + boff + n * 2048 + k * 1024); } while (0)
; #define PG8_MMA(ai, bj, At, Bt) do { __builtin_amdgcn_s_setprio(1); _Pragma("unroll") for (int m = 0; m < 4; ++m) _Pragma("unroll") for (int n = 0; n < 2; ++n) _Pragma("unroll") for (int k = 0; k < 2; ++k) \
;         acc[ai][bj][m][n] = __builtin_amdgcn_mfma_f32_16x16x32_bf16(Bt[n][k], At[m][k], acc[ai][bj][m][n], 0, 0, 0); __builtin_amdgcn_s_setprio(0); } while (0)
; template <class Epi, class Sched, bool ALIGN_EPI = false, bool SP2 = false>
; __device__ __forceinline__ void gemm_phase(PG8_LAS unsigned char* lds, const Gemm g, const Sched& S, const Epi& E) {
;     ...
;         const bool has_next = S.next(ui + 1, nxt);
;         const char* nA = has_next ? (const char*)g.A + (size_t)nxt.pm * tstepA + (size_t)nxt.pn * pnoffA : cA; const char* nB = has_next ? (const char*)g.Bt + (size_t)nxt.pn * tstepB : cB;
;         for (int t = 0; t < nt; t += 2) {
;             const bool last = (t == nt - 2);
;             const char* a1 = cA + (size_t)(t + 1) * kstepA;
;             const char* a2 = last ? nA : cA + (size_t)(t + 2) * kstepA; const char* b2 = last ? nB : cB + (size_t)(t + 2) * kstep;
;             const char* a3 = a2 + kstepA; const char* b3 = b2 + kstep;
;             if (last && has_next) S.a_ready(nxt);
;             if constexpr (SP2) {
;             PG8_LDB(B0, 0, 0); PG8_LDB(B1, 0, 1); PG8_SCHED; PG8_LDA(At, 0, 0); PG8_STAGE(PG8_SA(1, 1), a1 + hstepA, voffA);
;             PG8_WAIT_V(8); PG8_WAIT_L(0); PG8_BAR; PG8_MMA(0, 0, At, B0); PG8_MMA(0, 1, At, B1); PG8_BAR; PG8_SCHED;
;             PG8_LDA(At, 0, 1); PG8_STAGE(PG8_SB(0, 0), b2, voffB); PG8_STAGE(PG8_SB(0, 1), b2 + hstepB, voffB); PG8_STAGE(PG8_SA(0, 0), a2, voffA);
.LBB0_34:
	s_ashr_i32 s11, s10, 31
	s_lshl_b64 s[14:15], s[10:11], 15
	s_add_u32 s14, s70, s14
	s_addc_u32 s15, s71, s15
	s_and_b64 s[0:1], s[0:1], exec
	s_cselect_b32 s11, s15, s19
	s_cselect_b32 s36, s14, s18
	s_add_u32 s0, s18, 0x404000
	s_addc_u32 s1, s19, 0
	s_add_u32 s37, s16, 0x100
	s_addc_u32 s38, s17, 0
	s_mov_b32 s39, -2
	s_add_u32 s16, s0, 0x3fc000
	s_addc_u32 s17, s1, 0
	s_cmp_eq_u32 s39, 40
	s_cselect_b32 s20, s36, s16
	s_cselect_b32 s21, s11, s17
	s_cselect_b32 s18, s12, s37
	s_cselect_b32 s19, s13, s38
	s_add_u32 s16, s20, 0x400000
	s_addc_u32 s17, s21, 0
	s_add_i32 s40, 0, 0x10000
	s_add_i32 s42, 0, 0x14000
	v_add_u32_e32 v156, s40, v153
	v_add_u32_e32 v172, s42, v153
	ds_read_b128 v[140:143], v156
	ds_read_b128 v[144:147], v156 offset:1024
	ds_read_b128 v[148:151], v156 offset:2048
	ds_read_b128 v[156:159], v156 offset:3072
	ds_read_b128 v[160:163], v172
	ds_read_b128 v[164:167], v172 offset:1024
	ds_read_b128 v[168:171], v172 offset:2048
	ds_read_b128 v[172:175], v172 offset:3072
	v_lshl_add_u64 v[192:193], s[0:1], 0, v[136:137]
	s_add_i32 m0, s23, 0xc000
	ds_read_b128 v[176:179], v155
	ds_read_b128 v[180:183], v155 offset:1024
	ds_read_b128 v[184:187], v155 offset:2048
	ds_read_b128 v[188:191], v155 offset:3072
	ds_read_b128 v[206:209], v155 offset:4096
	ds_read_b128 v[210:213], v155 offset:5120
	ds_read_b128 v[214:217], v155 offset:6144
	ds_read_b128 v[218:221], v155 offset:7168
	global_load_lds_dwordx4 v[192:193], off
	v_lshl_add_u64 v[192:193], s[0:1], 0, v[138:139]
	s_add_i32 m0, s23, 0xe000
	s_nop 0
	global_load_lds_dwordx4 v[192:193], off
	s_waitcnt vmcnt(8)
	s_waitcnt lgkmcnt(0)
	s_barrier
	s_setprio 1
	s_waitcnt lgkmcnt(0)
	v_mfma_f32_16x16x32_bf16 v[126:129], v[140:143], v[176:179], 0
	v_mfma_f32_16x16x32_bf16 v[122:125], v[148:151], v[176:179], 0
	v_mfma_f32_16x16x32_bf16 v[118:121], v[140:143], v[184:187], 0
	v_mfma_f32_16x16x32_bf16 v[114:117], v[148:151], v[184:187], 0
	v_mfma_f32_16x16x32_bf16 v[106:109], v[140:143], v[206:209], 0
	v_mfma_f32_16x16x32_bf16 v[98:101], v[148:151], v[206:209], 0
	v_mfma_f32_16x16x32_bf16 v[90:93], v[140:143], v[214:217], 0
	v_mfma_f32_16x16x32_bf16 v[82:85], v[148:151], v[214:217], 0
	v_mfma_f32_16x16x32_bf16 v[126:129], v[144:147], v[180:183], v[126:129]
	v_mfma_f32_16x16x32_bf16 v[122:125], v[156:159], v[180:183], v[122:125]
	v_mfma_f32_16x16x32_bf16 v[118:121], v[144:147], v[188:191], v[118:121]
	v_mfma_f32_16x16x32_bf16 v[114:117], v[156:159], v[188:191], v[114:117]
	v_mfma_f32_16x16x32_bf16 v[106:109], v[144:147], v[210:213], v[106:109]
	v_mfma_f32_16x16x32_bf16 v[98:101], v[156:159], v[210:213], v[98:101]
	v_mfma_f32_16x16x32_bf16 v[90:93], v[144:147], v[218:221], v[90:93]
	v_mfma_f32_16x16x32_bf16 v[82:85], v[156:159], v[218:221], v[82:85]
	s_setprio 0
	s_setprio 1
	v_mfma_f32_16x16x32_bf16 v[110:113], v[160:163], v[176:179], 0
	v_mfma_f32_16x16x32_bf16 v[102:105], v[168:171], v[176:179], 0
	v_mfma_f32_16x16x32_bf16 v[94:97], v[160:163], v[184:187], 0
	v_mfma_f32_16x16x32_bf16 v[86:89], v[168:171], v[184:187], 0
	v_mfma_f32_16x16x32_bf16 v[78:81], v[160:163], v[206:209], 0
	v_mfma_f32_16x16x32_bf16 v[74:77], v[168:171], v[206:209], 0
	v_mfma_f32_16x16x32_bf16 v[70:73], v[160:163], v[214:217], 0
	v_mfma_f32_16x16x32_bf16 v[66:69], v[168:171], v[214:217], 0
	v_mfma_f32_16x16x32_bf16 v[110:113], v[164:167], v[180:183], v[110:113]
	v_mfma_f32_16x16x32_bf16 v[102:105], v[172:175], v[180:183], v[102:105]
	v_mfma_f32_16x16x32_bf16 v[94:97], v[164:167], v[188:191], v[94:97]
	v_mfma_f32_16x16x32_bf16 v[86:89], v[172:175], v[188:191], v[86:89]
	v_mfma_f32_16x16x32_bf16 v[78:81], v[164:167], v[210:213], v[78:81]
	v_mfma_f32_16x16x32_bf16 v[74:77], v[172:175], v[210:213], v[74:77]
	v_mfma_f32_16x16x32_bf16 v[70:73], v[164:167], v[218:221], v[70:73]
	v_mfma_f32_16x16x32_bf16 v[66:69], v[172:175], v[218:221], v[66:69]
	s_setprio 0
	s_barrier
	s_add_i32 s40, s40, s22
	v_lshl_add_u64 v[192:193], s[18:19], 0, v[0:1]
	s_mov_b32 m0, s40
	ds_read_b128 v[176:179], v155 offset:16384
	ds_read_b128 v[180:183], v155 offset:17408
	ds_read_b128 v[184:187], v155 offset:18432
	ds_read_b128 v[188:191], v155 offset:19456
	ds_read_b128 v[206:209], v155 offset:20480
	ds_read_b128 v[210:213], v155 offset:21504
	ds_read_b128 v[214:217], v155 offset:22528
	ds_read_b128 v[218:221], v155 offset:23552
	global_load_lds_dwordx4 v[192:193], off
	s_add_i32 m0, s40, 0x2000
	s_add_u32 s40, s18, 0xb0000
	v_lshl_add_u64 v[222:223], s[18:19], 0, v[130:131]
	s_addc_u32 s41, s19, 0
	s_add_i32 s42, s42, s22
	global_load_lds_dwordx4 v[222:223], off
	v_lshl_add_u64 v[224:225], s[40:41], 0, v[0:1]
	s_mov_b32 m0, s42
	s_nop 0
	global_load_lds_dwordx4 v[224:225], off
	v_lshl_add_u64 v[224:225], s[40:41], 0, v[130:131]
	s_add_i32 m0, s42, 0x2000
	s_nop 0
	global_load_lds_dwordx4 v[224:225], off
	v_lshl_add_u64 v[224:225], s[20:21], 0, v[134:135]
	s_mov_b32 m0, s23
	s_nop 0
	global_load_lds_dwordx4 v[224:225], off
	v_lshl_add_u64 v[224:225], s[20:21], 0, v[132:133]
	s_mov_b32 m0, s25
	s_nop 0
	global_load_lds_dwordx4 v[224:225], off
	s_waitcnt vmcnt(8)
	s_waitcnt lgkmcnt(0)
	s_barrier
; #define PG8_STAGE(bufoff, gbase, voff) do { _Pragma("unroll") for (int _i = 0; _i < 2; ++_i) \
;         __builtin_amdgcn_global_load_lds((const unsigned*)((const char*)(gbase) + (voff)[_i]), (PG8_LAS unsigned*)(lds + (bufoff) + ldsw + _i * 8192), 16, 0, 0); } while (0)
; #define PG8_LDA(dst, b, h) do { _Pragma("unroll") for (int m = 0; m < 4; ++m) _Pragma("unroll") for (int k = 0; k < 2; ++k) dst[m][k] = *(const PG8_LAS bf16x8*)(lds + PG8_SA(b, h) + aoff + m * 2048 + k * 1024); } while (0)
; #define PG8_LDB(dst, b, h) do { _Pragma("unroll") for (int n = 0; n < 2; ++n) _Pragma("unroll") for (int k = 0; k < 2; ++k) dst[n][k] = *(const PG8_LAS bf16x8*)(lds + PG8_SB(b, h) + boff + n * 2048 + k * 1024); } while (0)
; #define PG8_MMA(ai, bj, At, Bt) do { __builtin_amdgcn_s_setprio(1); _Pragma("unroll") for (int m = 0; m < 4; ++m) _Pragma("unroll") for (int n = 0; n < 2; ++n) _Pragma("unroll") for (int k = 0; k < 2; ++k) \
;         acc[ai][bj][m][n] = __builtin_amdgcn_mfma_f32_16x16x32_bf16(Bt[n][k], At[m][k], acc[ai][bj][m][n], 0, 0, 0); __builtin_amdgcn_s_setprio(0); } while (0)
; #define PG8_WAIT_V(n) asm volatile("s_waitcnt vmcnt(" #n ")" ::: "memory")
; #define PG8_WAIT_L(n) asm volatile("s_waitcnt lgkmcnt(" #n ")" ::: "memory")
; #define PG8_BAR __builtin_amdgcn_s_barrier()
; #define PG8_SCHED __builtin_amdgcn_sched_barrier(0)
; template <class Epi, class Sched, bool ALIGN_EPI = false, bool SP2 = false>
; __device__ __forceinline__ void gemm_phase(PG8_LAS unsigned char* lds, const Gemm g, const Sched& S, const Epi& E) {
;     ...
;             PG8_WAIT_V(8); PG8_WAIT_L(0); PG8_BAR; PG8_MMA(1, 0, At, B0); PG8_MMA(1, 1, At, B1); PG8_BAR; PG8_SCHED;
;             PG8_LDB(B0, 1, 0); PG8_LDB(B1, 1, 1); PG8_SCHED; PG8_LDA(At, 1, 0); PG8_STAGE(PG8_SA(0, 1), a2 + hstepA, voffA);
;             PG8_WAIT_V(8); PG8_WAIT_L(0); PG8_BAR; PG8_MMA(0, 0, At, B0); PG8_MMA(0, 1, At, B1); PG8_BAR; PG8_SCHED;
;             PG8_LDA(At, 1, 1); PG8_STAGE(PG8_SB(1, 0), b3, voffB); PG8_STAGE(PG8_SB(1, 1), b3 + hstepB, voffB); PG8_STAGE(PG8_SA(1, 0), a3, voffA);
	s_setprio 1
	s_waitcnt lgkmcnt(0)
	v_mfma_f32_16x16x32_bf16 v[62:65], v[140:143], v[176:179], 0
	v_mfma_f32_16x16x32_bf16 v[58:61], v[148:151], v[176:179], 0
	v_mfma_f32_16x16x32_bf16 v[54:57], v[140:143], v[184:187], 0
	v_mfma_f32_16x16x32_bf16 v[46:49], v[148:151], v[184:187], 0
	v_mfma_f32_16x16x32_bf16 v[38:41], v[140:143], v[206:209], 0
	v_mfma_f32_16x16x32_bf16 v[30:33], v[148:151], v[206:209], 0
	v_mfma_f32_16x16x32_bf16 v[22:25], v[140:143], v[214:217], 0
	v_mfma_f32_16x16x32_bf16 v[14:17], v[148:151], v[214:217], 0
	v_mfma_f32_16x16x32_bf16 v[62:65], v[144:147], v[180:183], v[62:65]
	v_mfma_f32_16x16x32_bf16 v[58:61], v[156:159], v[180:183], v[58:61]
	v_mfma_f32_16x16x32_bf16 v[54:57], v[144:147], v[188:191], v[54:57]
	v_mfma_f32_16x16x32_bf16 v[46:49], v[156:159], v[188:191], v[46:49]
	v_mfma_f32_16x16x32_bf16 v[38:41], v[144:147], v[210:213], v[38:41]
	v_mfma_f32_16x16x32_bf16 v[30:33], v[156:159], v[210:213], v[30:33]
	v_mfma_f32_16x16x32_bf16 v[22:25], v[144:147], v[218:221], v[22:25]
	v_mfma_f32_16x16x32_bf16 v[14:17], v[156:159], v[218:221], v[14:17]
	s_setprio 0
	s_setprio 1
	v_mfma_f32_16x16x32_bf16 v[50:53], v[160:163], v[176:179], 0
	v_mfma_f32_16x16x32_bf16 v[42:45], v[168:171], v[176:179], 0
	v_mfma_f32_16x16x32_bf16 v[34:37], v[160:163], v[184:187], 0
	v_mfma_f32_16x16x32_bf16 v[26:29], v[168:171], v[184:187], 0
	v_mfma_f32_16x16x32_bf16 v[18:21], v[160:163], v[206:209], 0
	v_mfma_f32_16x16x32_bf16 v[10:13], v[168:171], v[206:209], 0
	v_mfma_f32_16x16x32_bf16 v[6:9], v[160:163], v[214:217], 0
	v_mfma_f32_16x16x32_bf16 v[2:5], v[168:171], v[214:217], 0
	v_mfma_f32_16x16x32_bf16 v[50:53], v[164:167], v[180:183], v[50:53]
	v_mfma_f32_16x16x32_bf16 v[42:45], v[172:175], v[180:183], v[42:45]
	v_mfma_f32_16x16x32_bf16 v[34:37], v[164:167], v[188:191], v[34:37]
	v_mfma_f32_16x16x32_bf16 v[26:29], v[172:175], v[188:191], v[26:29]
	v_mfma_f32_16x16x32_bf16 v[18:21], v[164:167], v[210:213], v[18:21]
	v_mfma_f32_16x16x32_bf16 v[10:13], v[172:175], v[210:213], v[10:13]
	v_mfma_f32_16x16x32_bf16 v[6:9], v[164:167], v[218:221], v[6:9]
	v_mfma_f32_16x16x32_bf16 v[2:5], v[172:175], v[218:221], v[2:5]
	s_setprio 0
	s_barrier
	s_add_i32 s40, 0, 0x18000
	s_add_i32 s41, 0, 0x1c000
	v_add_u32_e32 v156, s40, v153
	v_add_u32_e32 v172, s41, v153
	ds_read_b128 v[140:143], v156
	ds_read_b128 v[144:147], v156 offset:1024
	ds_read_b128 v[148:151], v156 offset:2048
	ds_read_b128 v[156:159], v156 offset:3072
	ds_read_b128 v[160:163], v172
	ds_read_b128 v[164:167], v172 offset:1024
	ds_read_b128 v[168:171], v172 offset:2048
	ds_read_b128 v[172:175], v172 offset:3072
	s_add_u32 s20, s20, 0x4000
	s_addc_u32 s21, s21, 0
	s_mov_b32 m0, s26
	v_lshl_add_u64 v[224:225], s[20:21], 0, v[134:135]
	ds_read_b128 v[176:179], v155 offset:32768
	ds_read_b128 v[180:183], v155 offset:33792
	ds_read_b128 v[184:187], v155 offset:34816
	ds_read_b128 v[188:191], v155 offset:35840
	ds_read_b128 v[206:209], v155 offset:36864
	ds_read_b128 v[210:213], v155 offset:37888
	ds_read_b128 v[214:217], v155 offset:38912
	ds_read_b128 v[218:221], v155 offset:39936
	global_load_lds_dwordx4 v[224:225], off
	v_lshl_add_u64 v[224:225], s[20:21], 0, v[132:133]
	s_mov_b32 m0, s27
	s_nop 0
	global_load_lds_dwordx4 v[224:225], off
	s_waitcnt vmcnt(8)
	s_waitcnt lgkmcnt(0)
	s_barrier
	s_setprio 1
	s_waitcnt lgkmcnt(0)
	v_mfma_f32_16x16x32_bf16 v[126:129], v[140:143], v[176:179], v[126:129]
	v_mfma_f32_16x16x32_bf16 v[122:125], v[148:151], v[176:179], v[122:125]
	v_mfma_f32_16x16x32_bf16 v[118:121], v[140:143], v[184:187], v[118:121]
	v_mfma_f32_16x16x32_bf16 v[114:117], v[148:151], v[184:187], v[114:117]
	v_mfma_f32_16x16x32_bf16 v[106:109], v[140:143], v[206:209], v[106:109]
	v_mfma_f32_16x16x32_bf16 v[98:101], v[148:151], v[206:209], v[98:101]
	v_mfma_f32_16x16x32_bf16 v[90:93], v[140:143], v[214:217], v[90:93]
	v_mfma_f32_16x16x32_bf16 v[82:85], v[148:151], v[214:217], v[82:85]
	v_mfma_f32_16x16x32_bf16 v[126:129], v[144:147], v[180:183], v[126:129]
	v_mfma_f32_16x16x32_bf16 v[122:125], v[156:159], v[180:183], v[122:125]
	v_mfma_f32_16x16x32_bf16 v[118:121], v[144:147], v[188:191], v[118:121]
	v_mfma_f32_16x16x32_bf16 v[114:117], v[156:159], v[188:191], v[114:117]
	v_mfma_f32_16x16x32_bf16 v[106:109], v[144:147], v[210:213], v[106:109]
	v_mfma_f32_16x16x32_bf16 v[98:101], v[156:159], v[210:213], v[98:101]
	v_mfma_f32_16x16x32_bf16 v[90:93], v[144:147], v[218:221], v[90:93]
	v_mfma_f32_16x16x32_bf16 v[82:85], v[156:159], v[218:221], v[82:85]
	s_setprio 0
	s_setprio 1
	v_mfma_f32_16x16x32_bf16 v[110:113], v[160:163], v[176:179], v[110:113]
	v_mfma_f32_16x16x32_bf16 v[102:105], v[168:171], v[176:179], v[102:105]
	v_mfma_f32_16x16x32_bf16 v[94:97], v[160:163], v[184:187], v[94:97]
	v_mfma_f32_16x16x32_bf16 v[86:89], v[168:171], v[184:187], v[86:89]
	v_mfma_f32_16x16x32_bf16 v[78:81], v[160:163], v[206:209], v[78:81]
	v_mfma_f32_16x16x32_bf16 v[74:77], v[168:171], v[206:209], v[74:77]
	v_mfma_f32_16x16x32_bf16 v[70:73], v[160:163], v[214:217], v[70:73]
	v_mfma_f32_16x16x32_bf16 v[66:69], v[168:171], v[214:217], v[66:69]
	v_mfma_f32_16x16x32_bf16 v[110:113], v[164:167], v[180:183], v[110:113]
	v_mfma_f32_16x16x32_bf16 v[102:105], v[172:175], v[180:183], v[102:105]
	v_mfma_f32_16x16x32_bf16 v[94:97], v[164:167], v[188:191], v[94:97]
	v_mfma_f32_16x16x32_bf16 v[86:89], v[172:175], v[188:191], v[86:89]
	v_mfma_f32_16x16x32_bf16 v[78:81], v[164:167], v[210:213], v[78:81]
	v_mfma_f32_16x16x32_bf16 v[74:77], v[172:175], v[210:213], v[74:77]
	v_mfma_f32_16x16x32_bf16 v[70:73], v[164:167], v[218:221], v[70:73]
	v_mfma_f32_16x16x32_bf16 v[66:69], v[172:175], v[218:221], v[66:69]
	s_setprio 0
	s_barrier
; #define PG8_STAGE(bufoff, gbase, voff) do { _Pragma("unroll") for (int _i = 0; _i < 2; ++_i) \
;         __builtin_amdgcn_global_load_lds((const unsigned*)((const char*)(gbase) + (voff)[_i]), (PG8_LAS unsigned*)(lds + (bufoff) + ldsw + _i * 8192), 16, 0, 0); } while (0)
; #define PG8_LDA(dst, b, h) do { _Pragma("unroll") for (int m = 0; m < 4; ++m) _Pragma("unroll") for (int k = 0; k < 2; ++k) dst[m][k] = *(const PG8_LAS bf16x8*)(lds + PG8_SA(b, h) + aoff + m * 2048 + k * 1024); } while (0)
; #define PG8_LDB(dst, b, h) do { _Pragma("unroll") for (int n = 0; n < 2; ++n) _Pragma("unroll") for (int k = 0; k < 2; ++k) dst[n][k] = *(const PG8_LAS bf16x8*)(lds + PG8_SB(b, h) + boff + n * 2048 + k * 1024); } while (0)
; #define PG8_WAIT_V(n) asm volatile("s_waitcnt vmcnt(" #n ")" ::: "memory")
; #define PG8_WAIT_L(n) asm volatile("s_waitcnt lgkmcnt(" #n ")" ::: "memory")
; #define PG8_BAR __builtin_amdgcn_s_barrier()
; #define PG8_SCHED __builtin_amdgcn_sched_barrier(0)
; template <class Epi, class Sched, bool ALIGN_EPI = false, bool SP2 = false>
; __device__ __forceinline__ void gemm_phase(PG8_LAS unsigned char* lds, const Gemm g, const Sched& S, const Epi& E) {
;     ...
;         for (int t = 0; t < nt; t += 2) {
;             const bool last = (t == nt - 2);
;             const char* a1 = cA + (size_t)(t + 1) * kstepA;
;             const char* a2 = last ? nA : cA + (size_t)(t + 2) * kstepA; const char* b2 = last ? nB : cB + (size_t)(t + 2) * kstep;
;             const char* a3 = a2 + kstepA; const char* b3 = b2 + kstep;
;             if (last && has_next) S.a_ready(nxt);
;             if constexpr (SP2) {
;             PG8_LDB(B0, 0, 0); PG8_LDB(B1, 0, 1); PG8_SCHED; PG8_LDA(At, 0, 0); PG8_STAGE(PG8_SA(1, 1), a1 + hstepA, voffA);
;             PG8_WAIT_V(8); PG8_WAIT_L(0); PG8_BAR; PG8_MMA(0, 0, At, B0); PG8_MMA(0, 1, At, B1); PG8_BAR; PG8_SCHED;
;             PG8_LDA(At, 0, 1); PG8_STAGE(PG8_SB(0, 0), b2, voffB); PG8_STAGE(PG8_SB(0, 1), b2 + hstepB, voffB); PG8_STAGE(PG8_SA(0, 0), a2, voffA);
;     ...
;             PG8_LDA(At, 1, 1); PG8_STAGE(PG8_SB(1, 0), b3, voffB); PG8_STAGE(PG8_SB(1, 1), b3 + hstepB, voffB); PG8_STAGE(PG8_SA(1, 0), a3, voffA);
;             PG8_WAIT_V(8); PG8_WAIT_L(0); PG8_BAR; PG8_MMA(1, 0, At, B0); PG8_MMA(1, 1, At, B1); PG8_BAR; PG8_SCHED;
	s_add_i32 s20, s40, s22
	v_lshl_add_u64 v[192:193], v[192:193], 0, s[78:79]
	s_mov_b32 m0, s20
	ds_read_b128 v[176:179], v155 offset:49152
	ds_read_b128 v[180:183], v155 offset:50176
	ds_read_b128 v[184:187], v155 offset:51200
	ds_read_b128 v[188:191], v155 offset:52224
	ds_read_b128 v[206:209], v155 offset:53248
	ds_read_b128 v[210:213], v155 offset:54272
	ds_read_b128 v[214:217], v155 offset:55296
	ds_read_b128 v[218:221], v155 offset:56320
	global_load_lds_dwordx4 v[192:193], off
	s_add_i32 m0, s20, 0x2000
	s_add_u32 s18, s18, 0xb0080
	v_lshl_add_u64 v[192:193], v[222:223], 0, s[78:79]
	s_addc_u32 s19, s19, 0
	s_add_i32 s20, s41, s22
	global_load_lds_dwordx4 v[192:193], off
	v_lshl_add_u64 v[192:193], s[18:19], 0, v[0:1]
	s_mov_b32 m0, s20
	s_nop 0
	global_load_lds_dwordx4 v[192:193], off
	v_lshl_add_u64 v[192:193], s[18:19], 0, v[130:131]
	s_add_i32 m0, s20, 0x2000
	s_nop 0
	global_load_lds_dwordx4 v[192:193], off
	v_lshl_add_u64 v[192:193], s[16:17], 0, v[134:135]
	s_mov_b32 m0, s28
	s_nop 0
	global_load_lds_dwordx4 v[192:193], off
	v_lshl_add_u64 v[192:193], s[16:17], 0, v[132:133]
	s_mov_b32 m0, s29
	s_nop 0
	global_load_lds_dwordx4 v[192:193], off
	s_waitcnt vmcnt(8)
	s_waitcnt lgkmcnt(0)
	s_barrier
	s_setprio 1
	s_waitcnt lgkmcnt(0)
	v_mfma_f32_16x16x32_bf16 v[62:65], v[140:143], v[176:179], v[62:65]
	v_mfma_f32_16x16x32_bf16 v[58:61], v[148:151], v[176:179], v[58:61]
	v_mfma_f32_16x16x32_bf16 v[54:57], v[140:143], v[184:187], v[54:57]
	v_mfma_f32_16x16x32_bf16 v[46:49], v[148:151], v[184:187], v[46:49]
	v_mfma_f32_16x16x32_bf16 v[38:41], v[140:143], v[206:209], v[38:41]
	v_mfma_f32_16x16x32_bf16 v[30:33], v[148:151], v[206:209], v[30:33]
	v_mfma_f32_16x16x32_bf16 v[22:25], v[140:143], v[214:217], v[22:25]
	v_mfma_f32_16x16x32_bf16 v[14:17], v[148:151], v[214:217], v[14:17]
	v_mfma_f32_16x16x32_bf16 v[62:65], v[144:147], v[180:183], v[62:65]
	v_mfma_f32_16x16x32_bf16 v[58:61], v[156:159], v[180:183], v[58:61]
	v_mfma_f32_16x16x32_bf16 v[54:57], v[144:147], v[188:191], v[54:57]
	v_mfma_f32_16x16x32_bf16 v[46:49], v[156:159], v[188:191], v[46:49]
	v_mfma_f32_16x16x32_bf16 v[38:41], v[144:147], v[210:213], v[38:41]
	v_mfma_f32_16x16x32_bf16 v[30:33], v[156:159], v[210:213], v[30:33]
	v_mfma_f32_16x16x32_bf16 v[22:25], v[144:147], v[218:221], v[22:25]
	v_mfma_f32_16x16x32_bf16 v[14:17], v[156:159], v[218:221], v[14:17]
	s_setprio 0
	s_setprio 1
	v_mfma_f32_16x16x32_bf16 v[50:53], v[160:163], v[176:179], v[50:53]
	v_mfma_f32_16x16x32_bf16 v[42:45], v[168:171], v[176:179], v[42:45]
	v_mfma_f32_16x16x32_bf16 v[34:37], v[160:163], v[184:187], v[34:37]
	v_mfma_f32_16x16x32_bf16 v[26:29], v[168:171], v[184:187], v[26:29]
	v_mfma_f32_16x16x32_bf16 v[18:21], v[160:163], v[206:209], v[18:21]
	v_mfma_f32_16x16x32_bf16 v[10:13], v[168:171], v[206:209], v[10:13]
	v_mfma_f32_16x16x32_bf16 v[6:9], v[160:163], v[214:217], v[6:9]
	v_mfma_f32_16x16x32_bf16 v[2:5], v[168:171], v[214:217], v[2:5]
	v_mfma_f32_16x16x32_bf16 v[50:53], v[164:167], v[180:183], v[50:53]
	v_mfma_f32_16x16x32_bf16 v[42:45], v[172:175], v[180:183], v[42:45]
	v_mfma_f32_16x16x32_bf16 v[34:37], v[164:167], v[188:191], v[34:37]
	v_mfma_f32_16x16x32_bf16 v[26:29], v[172:175], v[188:191], v[26:29]
	v_mfma_f32_16x16x32_bf16 v[18:21], v[164:167], v[210:213], v[18:21]
	v_mfma_f32_16x16x32_bf16 v[10:13], v[172:175], v[210:213], v[10:13]
	v_mfma_f32_16x16x32_bf16 v[6:9], v[164:167], v[218:221], v[6:9]
	v_mfma_f32_16x16x32_bf16 v[2:5], v[172:175], v[218:221], v[2:5]
	s_setprio 0
	s_add_i32 s39, s39, 2
	s_add_u32 s0, s0, 0x800000
	s_addc_u32 s1, s1, 0
	s_add_u32 s37, s37, 0x100
	s_addc_u32 s38, s38, 0
	s_add_u32 s16, s0, 0x3fc000
	s_addc_u32 s17, s1, 0
	s_cmp_eq_u32 s39, 40
	s_cselect_b32 s20, s36, s16
	s_cselect_b32 s21, s11, s17
	s_cselect_b32 s18, s12, s37
	s_cselect_b32 s19, s13, s38
	s_add_u32 s16, s20, 0x400000
	s_addc_u32 s17, s21, 0
	s_add_i32 s40, 0, 0x10000
	s_add_i32 s42, 0, 0x14000
	s_barrier
.LBB0_35:
	v_add_u32_e32 v156, s40, v153
	v_add_u32_e32 v172, s42, v153
	ds_read_b128 v[140:143], v156
	ds_read_b128 v[144:147], v156 offset:1024
	ds_read_b128 v[148:151], v156 offset:2048
	ds_read_b128 v[156:159], v156 offset:3072
	ds_read_b128 v[160:163], v172
	ds_read_b128 v[164:167], v172 offset:1024
	ds_read_b128 v[168:171], v172 offset:2048
	ds_read_b128 v[172:175], v172 offset:3072
	v_lshl_add_u64 v[192:193], s[0:1], 0, v[136:137]
	s_add_i32 m0, s23, 0xc000
	ds_read_b128 v[176:179], v155
	ds_read_b128 v[180:183], v155 offset:1024
	ds_read_b128 v[184:187], v155 offset:2048
	ds_read_b128 v[188:191], v155 offset:3072
	ds_read_b128 v[206:209], v155 offset:4096
	ds_read_b128 v[210:213], v155 offset:5120
	ds_read_b128 v[214:217], v155 offset:6144
	ds_read_b128 v[218:221], v155 offset:7168
	global_load_lds_dwordx4 v[192:193], off
	v_lshl_add_u64 v[192:193], s[0:1], 0, v[138:139]
	s_add_i32 m0, s23, 0xe000
	s_nop 0
	global_load_lds_dwordx4 v[192:193], off
	s_waitcnt vmcnt(8)
	s_waitcnt lgkmcnt(0)
	s_barrier
; #define PG8_STAGE(bufoff, gbase, voff) do { _Pragma("unroll") for (int _i = 0; _i < 2; ++_i) \
;         __builtin_amdgcn_global_load_lds((const unsigned*)((const char*)(gbase) + (voff)[_i]), (PG8_LAS unsigned*)(lds + (bufoff) + ldsw + _i * 8192), 16, 0, 0); } while (0)
; #define PG8_LDA(dst, b, h) do { _Pragma("unroll") for (int m = 0; m < 4; ++m) _Pragma("unroll") for (int k = 0; k < 2; ++k) dst[m][k] = *(const PG8_LAS bf16x8*)(lds + PG8_SA(b, h) + aoff + m * 2048 + k * 1024); } while (0)
; #define PG8_LDB(dst, b, h) do { _Pragma("unroll") for (int n = 0; n < 2; ++n) _Pragma("unroll") for (int k = 0; k < 2; ++k) dst[n][k] = *(const PG8_LAS bf16x8*)(lds + PG8_SB(b, h) + boff + n * 2048 + k * 1024); } while (0)
; #define PG8_MMA(ai, bj, At, Bt) do { __builtin_amdgcn_s_setprio(1); _Pragma("unroll") for (int m = 0; m < 4; ++m) _Pragma("unroll") for (int n = 0; n < 2; ++n) _Pragma("unroll") for (int k = 0; k < 2; ++k) \
;         acc[ai][bj][m][n] = __builtin_amdgcn_mfma_f32_16x16x32_bf16(Bt[n][k], At[m][k], acc[ai][bj][m][n], 0, 0, 0); __builtin_amdgcn_s_setprio(0); } while (0)
; #define PG8_WAIT_V(n) asm volatile("s_waitcnt vmcnt(" #n ")" ::: "memory")
; #define PG8_WAIT_L(n) asm volatile("s_waitcnt lgkmcnt(" #n ")" ::: "memory")
; template <class Epi, class Sched, bool ALIGN_EPI = false, bool SP2 = false>
; __device__ __forceinline__ void gemm_phase(PG8_LAS unsigned char* lds, const Gemm g, const Sched& S, const Epi& E) {
;     ...
;             PG8_LDB(B0, 0, 0); PG8_LDB(B1, 0, 1); PG8_SCHED; PG8_LDA(At, 0, 0); PG8_STAGE(PG8_SA(1, 1), a1 + hstepA, voffA);
;             PG8_WAIT_V(8); PG8_WAIT_L(0); PG8_BAR; PG8_MMA(0, 0, At, B0); PG8_MMA(0, 1, At, B1); PG8_BAR; PG8_SCHED;
;             PG8_LDA(At, 0, 1); PG8_STAGE(PG8_SB(0, 0), b2, voffB); PG8_STAGE(PG8_SB(0, 1), b2 + hstepB, voffB); PG8_STAGE(PG8_SA(0, 0), a2, voffA);
;             PG8_WAIT_V(8); PG8_WAIT_L(0); PG8_BAR; PG8_MMA(1, 0, At, B0); PG8_MMA(1, 1, At, B1); PG8_BAR; PG8_SCHED;
;             PG8_LDB(B0, 1, 0); PG8_LDB(B1, 1, 1); PG8_SCHED; PG8_LDA(At, 1, 0); PG8_STAGE(PG8_SA(0, 1), a2 + hstepA, voffA);
;             PG8_WAIT_V(8); PG8_WAIT_L(0); PG8_BAR; PG8_MMA(0, 0, At, B0); PG8_MMA(0, 1, At, B1); PG8_BAR; PG8_SCHED;
;             PG8_LDA(At, 1, 1); PG8_STAGE(PG8_SB(1, 0), b3, voffB); PG8_STAGE(PG8_SB(1, 1), b3 + hstepB, voffB); PG8_STAGE(PG8_SA(1, 0), a3, voffA);
	s_setprio 1
	s_waitcnt lgkmcnt(0)
	v_mfma_f32_16x16x32_bf16 v[126:129], v[140:143], v[176:179], v[126:129]
	v_mfma_f32_16x16x32_bf16 v[122:125], v[148:151], v[176:179], v[122:125]
	v_mfma_f32_16x16x32_bf16 v[118:121], v[140:143], v[184:187], v[118:121]
	v_mfma_f32_16x16x32_bf16 v[114:117], v[148:151], v[184:187], v[114:117]
	v_mfma_f32_16x16x32_bf16 v[106:109], v[140:143], v[206:209], v[106:109]
	v_mfma_f32_16x16x32_bf16 v[98:101], v[148:151], v[206:209], v[98:101]
	v_mfma_f32_16x16x32_bf16 v[90:93], v[140:143], v[214:217], v[90:93]
	v_mfma_f32_16x16x32_bf16 v[82:85], v[148:151], v[214:217], v[82:85]
	v_mfma_f32_16x16x32_bf16 v[126:129], v[144:147], v[180:183], v[126:129]
	v_mfma_f32_16x16x32_bf16 v[122:125], v[156:159], v[180:183], v[122:125]
	v_mfma_f32_16x16x32_bf16 v[118:121], v[144:147], v[188:191], v[118:121]
	v_mfma_f32_16x16x32_bf16 v[114:117], v[156:159], v[188:191], v[114:117]
	v_mfma_f32_16x16x32_bf16 v[106:109], v[144:147], v[210:213], v[106:109]
	v_mfma_f32_16x16x32_bf16 v[98:101], v[156:159], v[210:213], v[98:101]
	v_mfma_f32_16x16x32_bf16 v[90:93], v[144:147], v[218:221], v[90:93]
	v_mfma_f32_16x16x32_bf16 v[82:85], v[156:159], v[218:221], v[82:85]
	s_setprio 0
	s_setprio 1
	v_mfma_f32_16x16x32_bf16 v[110:113], v[160:163], v[176:179], v[110:113]
	v_mfma_f32_16x16x32_bf16 v[102:105], v[168:171], v[176:179], v[102:105]
	v_mfma_f32_16x16x32_bf16 v[94:97], v[160:163], v[184:187], v[94:97]
	v_mfma_f32_16x16x32_bf16 v[86:89], v[168:171], v[184:187], v[86:89]
	v_mfma_f32_16x16x32_bf16 v[78:81], v[160:163], v[206:209], v[78:81]
	v_mfma_f32_16x16x32_bf16 v[74:77], v[168:171], v[206:209], v[74:77]
	v_mfma_f32_16x16x32_bf16 v[70:73], v[160:163], v[214:217], v[70:73]
	v_mfma_f32_16x16x32_bf16 v[66:69], v[168:171], v[214:217], v[66:69]
	v_mfma_f32_16x16x32_bf16 v[110:113], v[164:167], v[180:183], v[110:113]
	v_mfma_f32_16x16x32_bf16 v[102:105], v[172:175], v[180:183], v[102:105]
	v_mfma_f32_16x16x32_bf16 v[94:97], v[164:167], v[188:191], v[94:97]
	v_mfma_f32_16x16x32_bf16 v[86:89], v[172:175], v[188:191], v[86:89]
	v_mfma_f32_16x16x32_bf16 v[78:81], v[164:167], v[210:213], v[78:81]
	v_mfma_f32_16x16x32_bf16 v[74:77], v[172:175], v[210:213], v[74:77]
	v_mfma_f32_16x16x32_bf16 v[70:73], v[164:167], v[218:221], v[70:73]
	v_mfma_f32_16x16x32_bf16 v[66:69], v[172:175], v[218:221], v[66:69]
	s_setprio 0
	s_barrier
	s_add_i32 s40, s40, s22
	v_lshl_add_u64 v[192:193], s[18:19], 0, v[0:1]
	s_mov_b32 m0, s40
	ds_read_b128 v[176:179], v155 offset:16384
	ds_read_b128 v[180:183], v155 offset:17408
	ds_read_b128 v[184:187], v155 offset:18432
	ds_read_b128 v[188:191], v155 offset:19456
	ds_read_b128 v[206:209], v155 offset:20480
	ds_read_b128 v[210:213], v155 offset:21504
	ds_read_b128 v[214:217], v155 offset:22528
	ds_read_b128 v[218:221], v155 offset:23552
	global_load_lds_dwordx4 v[192:193], off
	s_add_i32 m0, s40, 0x2000
	s_add_u32 s40, s18, 0xb0000
	v_lshl_add_u64 v[222:223], s[18:19], 0, v[130:131]
	s_addc_u32 s41, s19, 0
	s_add_i32 s42, s42, s22
	global_load_lds_dwordx4 v[222:223], off
	v_lshl_add_u64 v[224:225], s[40:41], 0, v[0:1]
	s_mov_b32 m0, s42
	s_nop 0
	global_load_lds_dwordx4 v[224:225], off
	v_lshl_add_u64 v[224:225], s[40:41], 0, v[130:131]
	s_add_i32 m0, s42, 0x2000
	s_nop 0
	global_load_lds_dwordx4 v[224:225], off
	v_lshl_add_u64 v[224:225], s[20:21], 0, v[134:135]
	s_mov_b32 m0, s23
	s_nop 0
	global_load_lds_dwordx4 v[224:225], off
	v_lshl_add_u64 v[224:225], s[20:21], 0, v[132:133]
	s_mov_b32 m0, s25
	s_nop 0
	global_load_lds_dwordx4 v[224:225], off
	s_waitcnt vmcnt(8)
	s_waitcnt lgkmcnt(0)
	s_barrier
	s_setprio 1
	s_waitcnt lgkmcnt(0)
	v_mfma_f32_16x16x32_bf16 v[62:65], v[140:143], v[176:179], v[62:65]
	v_mfma_f32_16x16x32_bf16 v[58:61], v[148:151], v[176:179], v[58:61]
	v_mfma_f32_16x16x32_bf16 v[54:57], v[140:143], v[184:187], v[54:57]
	v_mfma_f32_16x16x32_bf16 v[46:49], v[148:151], v[184:187], v[46:49]
	v_mfma_f32_16x16x32_bf16 v[38:41], v[140:143], v[206:209], v[38:41]
	v_mfma_f32_16x16x32_bf16 v[30:33], v[148:151], v[206:209], v[30:33]
	v_mfma_f32_16x16x32_bf16 v[22:25], v[140:143], v[214:217], v[22:25]
	v_mfma_f32_16x16x32_bf16 v[14:17], v[148:151], v[214:217], v[14:17]
	v_mfma_f32_16x16x32_bf16 v[62:65], v[144:147], v[180:183], v[62:65]
	v_mfma_f32_16x16x32_bf16 v[58:61], v[156:159], v[180:183], v[58:61]
	v_mfma_f32_16x16x32_bf16 v[54:57], v[144:147], v[188:191], v[54:57]
	v_mfma_f32_16x16x32_bf16 v[46:49], v[156:159], v[188:191], v[46:49]
	v_mfma_f32_16x16x32_bf16 v[38:41], v[144:147], v[210:213], v[38:41]
	v_mfma_f32_16x16x32_bf16 v[30:33], v[156:159], v[210:213], v[30:33]
	v_mfma_f32_16x16x32_bf16 v[22:25], v[144:147], v[218:221], v[22:25]
	v_mfma_f32_16x16x32_bf16 v[14:17], v[156:159], v[218:221], v[14:17]
	s_setprio 0
	s_setprio 1
	v_mfma_f32_16x16x32_bf16 v[50:53], v[160:163], v[176:179], v[50:53]
	v_mfma_f32_16x16x32_bf16 v[42:45], v[168:171], v[176:179], v[42:45]
	v_mfma_f32_16x16x32_bf16 v[34:37], v[160:163], v[184:187], v[34:37]
	v_mfma_f32_16x16x32_bf16 v[26:29], v[168:171], v[184:187], v[26:29]
	v_mfma_f32_16x16x32_bf16 v[18:21], v[160:163], v[206:209], v[18:21]
	v_mfma_f32_16x16x32_bf16 v[10:13], v[168:171], v[206:209], v[10:13]
	v_mfma_f32_16x16x32_bf16 v[6:9], v[160:163], v[214:217], v[6:9]
	v_mfma_f32_16x16x32_bf16 v[2:5], v[168:171], v[214:217], v[2:5]
	v_mfma_f32_16x16x32_bf16 v[50:53], v[164:167], v[180:183], v[50:53]
	v_mfma_f32_16x16x32_bf16 v[42:45], v[172:175], v[180:183], v[42:45]
	v_mfma_f32_16x16x32_bf16 v[34:37], v[164:167], v[188:191], v[34:37]
	v_mfma_f32_16x16x32_bf16 v[26:29], v[172:175], v[188:191], v[26:29]
	v_mfma_f32_16x16x32_bf16 v[18:21], v[164:167], v[210:213], v[18:21]
	v_mfma_f32_16x16x32_bf16 v[10:13], v[172:175], v[210:213], v[10:13]
	v_mfma_f32_16x16x32_bf16 v[6:9], v[164:167], v[218:221], v[6:9]
	v_mfma_f32_16x16x32_bf16 v[2:5], v[172:175], v[218:221], v[2:5]
	s_setprio 0
	s_barrier
; #define PG8_STAGE(bufoff, gbase, voff) do { _Pragma("unroll") for (int _i = 0; _i < 2; ++_i) \
;         __builtin_amdgcn_global_load_lds((const unsigned*)((const char*)(gbase) + (voff)[_i]), (PG8_LAS unsigned*)(lds + (bufoff) + ldsw + _i * 8192), 16, 0, 0); } while (0)
; #define PG8_LDA(dst, b, h) do { _Pragma("unroll") for (int m = 0; m < 4; ++m) _Pragma("unroll") for (int k = 0; k < 2; ++k) dst[m][k] = *(const PG8_LAS bf16x8*)(lds + PG8_SA(b, h) + aoff + m * 2048 + k * 1024); } while (0)
; #define PG8_LDB(dst, b, h) do { _Pragma("unroll") for (int n = 0; n < 2; ++n) _Pragma("unroll") for (int k = 0; k < 2; ++k) dst[n][k] = *(const PG8_LAS bf16x8*)(lds + PG8_SB(b, h) + boff + n * 2048 + k * 1024); } while (0)
; #define PG8_MMA(ai, bj, At, Bt) do { __builtin_amdgcn_s_setprio(1); _Pragma("unroll") for (int m = 0; m < 4; ++m) _Pragma("unroll") for (int n = 0; n < 2; ++n) _Pragma("unroll") for (int k = 0; k < 2; ++k) \
;         acc[ai][bj][m][n] = __builtin_amdgcn_mfma_f32_16x16x32_bf16(Bt[n][k], At[m][k], acc[ai][bj][m][n], 0, 0, 0); __builtin_amdgcn_s_setprio(0); } while (0)
; #define PG8_WAIT_V(n) asm volatile("s_waitcnt vmcnt(" #n ")" ::: "memory")
; #define PG8_WAIT_L(n) asm volatile("s_waitcnt lgkmcnt(" #n ")" ::: "memory")
; #define PG8_BAR __builtin_amdgcn_s_barrier()
; #define PG8_SCHED __builtin_amdgcn_sched_barrier(0)
; template <class Epi, class Sched, bool ALIGN_EPI = false, bool SP2 = false>
; __device__ __forceinline__ void gemm_phase(PG8_LAS unsigned char* lds, const Gemm g, const Sched& S, const Epi& E) {
;     ...
;             PG8_LDB(B0, 1, 0); PG8_LDB(B1, 1, 1); PG8_SCHED; PG8_LDA(At, 1, 0); PG8_STAGE(PG8_SA(0, 1), a2 + hstepA, voffA);
;             PG8_WAIT_V(8); PG8_WAIT_L(0); PG8_BAR; PG8_MMA(0, 0, At, B0); PG8_MMA(0, 1, At, B1); PG8_BAR; PG8_SCHED;
	s_add_i32 s40, 0, 0x18000
	s_add_i32 s41, 0, 0x1c000
	v_add_u32_e32 v156, s40, v153
	v_add_u32_e32 v172, s41, v153
	ds_read_b128 v[140:143], v156
	ds_read_b128 v[144:147], v156 offset:1024
	ds_read_b128 v[148:151], v156 offset:2048
	ds_read_b128 v[156:159], v156 offset:3072
	ds_read_b128 v[160:163], v172
	ds_read_b128 v[164:167], v172 offset:1024
	ds_read_b128 v[168:171], v172 offset:2048
	ds_read_b128 v[172:175], v172 offset:3072
	s_add_u32 s20, s20, 0x4000
	s_addc_u32 s21, s21, 0
	s_mov_b32 m0, s26
	v_lshl_add_u64 v[224:225], s[20:21], 0, v[134:135]
	ds_read_b128 v[176:179], v155 offset:32768
	ds_read_b128 v[180:183], v155 offset:33792
	ds_read_b128 v[184:187], v155 offset:34816
	ds_read_b128 v[188:191], v155 offset:35840
	ds_read_b128 v[206:209], v155 offset:36864
	ds_read_b128 v[210:213], v155 offset:37888
	ds_read_b128 v[214:217], v155 offset:38912
	ds_read_b128 v[218:221], v155 offset:39936
	global_load_lds_dwordx4 v[224:225], off
	v_lshl_add_u64 v[224:225], s[20:21], 0, v[132:133]
	s_mov_b32 m0, s27
	s_nop 0
	global_load_lds_dwordx4 v[224:225], off
	s_waitcnt vmcnt(8)
	s_waitcnt lgkmcnt(0)
	s_barrier
	s_setprio 1
	s_waitcnt lgkmcnt(0)
	v_mfma_f32_16x16x32_bf16 v[126:129], v[140:143], v[176:179], v[126:129]
	v_mfma_f32_16x16x32_bf16 v[122:125], v[148:151], v[176:179], v[122:125]
	v_mfma_f32_16x16x32_bf16 v[118:121], v[140:143], v[184:187], v[118:121]
	v_mfma_f32_16x16x32_bf16 v[114:117], v[148:151], v[184:187], v[114:117]
	v_mfma_f32_16x16x32_bf16 v[106:109], v[140:143], v[206:209], v[106:109]
	v_mfma_f32_16x16x32_bf16 v[98:101], v[148:151], v[206:209], v[98:101]
	v_mfma_f32_16x16x32_bf16 v[90:93], v[140:143], v[214:217], v[90:93]
	v_mfma_f32_16x16x32_bf16 v[82:85], v[148:151], v[214:217], v[82:85]
	v_mfma_f32_16x16x32_bf16 v[126:129], v[144:147], v[180:183], v[126:129]
	v_mfma_f32_16x16x32_bf16 v[122:125], v[156:159], v[180:183], v[122:125]
	v_mfma_f32_16x16x32_bf16 v[118:121], v[144:147], v[188:191], v[118:121]
	v_mfma_f32_16x16x32_bf16 v[114:117], v[156:159], v[188:191], v[114:117]
	v_mfma_f32_16x16x32_bf16 v[106:109], v[144:147], v[210:213], v[106:109]
	v_mfma_f32_16x16x32_bf16 v[98:101], v[156:159], v[210:213], v[98:101]
	v_mfma_f32_16x16x32_bf16 v[90:93], v[144:147], v[218:221], v[90:93]
	v_mfma_f32_16x16x32_bf16 v[82:85], v[156:159], v[218:221], v[82:85]
	s_setprio 0
	s_setprio 1
	v_mfma_f32_16x16x32_bf16 v[110:113], v[160:163], v[176:179], v[110:113]
	v_mfma_f32_16x16x32_bf16 v[102:105], v[168:171], v[176:179], v[102:105]
	v_mfma_f32_16x16x32_bf16 v[94:97], v[160:163], v[184:187], v[94:97]
	v_mfma_f32_16x16x32_bf16 v[86:89], v[168:171], v[184:187], v[86:89]
	v_mfma_f32_16x16x32_bf16 v[78:81], v[160:163], v[206:209], v[78:81]
	v_mfma_f32_16x16x32_bf16 v[74:77], v[168:171], v[206:209], v[74:77]
	v_mfma_f32_16x16x32_bf16 v[70:73], v[160:163], v[214:217], v[70:73]
	v_mfma_f32_16x16x32_bf16 v[66:69], v[168:171], v[214:217], v[66:69]
	v_mfma_f32_16x16x32_bf16 v[110:113], v[164:167], v[180:183], v[110:113]
	v_mfma_f32_16x16x32_bf16 v[102:105], v[172:175], v[180:183], v[102:105]
	v_mfma_f32_16x16x32_bf16 v[94:97], v[164:167], v[188:191], v[94:97]
	v_mfma_f32_16x16x32_bf16 v[86:89], v[172:175], v[188:191], v[86:89]
	v_mfma_f32_16x16x32_bf16 v[78:81], v[164:167], v[210:213], v[78:81]
	v_mfma_f32_16x16x32_bf16 v[74:77], v[172:175], v[210:213], v[74:77]
	v_mfma_f32_16x16x32_bf16 v[70:73], v[164:167], v[218:221], v[70:73]
	v_mfma_f32_16x16x32_bf16 v[66:69], v[172:175], v[218:221], v[66:69]
	s_setprio 0
	s_barrier
; #define PG8_STAGE(bufoff, gbase, voff) do { _Pragma("unroll") for (int _i = 0; _i < 2; ++_i) \
;         __builtin_amdgcn_global_load_lds((const unsigned*)((const char*)(gbase) + (voff)[_i]), (PG8_LAS unsigned*)(lds + (bufoff) + ldsw + _i * 8192), 16, 0, 0); } while (0)
; #define PG8_LDA(dst, b, h) do { _Pragma("unroll") for (int m = 0; m < 4; ++m) _Pragma("unroll") for (int k = 0; k < 2; ++k) dst[m][k] = *(const PG8_LAS bf16x8*)(lds + PG8_SA(b, h) + aoff + m * 2048 + k * 1024); } while (0)
; #define PG8_MMA(ai, bj, At, Bt) do { __builtin_amdgcn_s_setprio(1); _Pragma("unroll") for (int m = 0; m < 4; ++m) _Pragma("unroll") for (int n = 0; n < 2; ++n) _Pragma("unroll") for (int k = 0; k < 2; ++k) \
;         acc[ai][bj][m][n] = __builtin_amdgcn_mfma_f32_16x16x32_bf16(Bt[n][k], At[m][k], acc[ai][bj][m][n], 0, 0, 0); __builtin_amdgcn_s_setprio(0); } while (0)
; #define PG8_WAIT_V(n) asm volatile("s_waitcnt vmcnt(" #n ")" ::: "memory")
; #define PG8_WAIT_L(n) asm volatile("s_waitcnt lgkmcnt(" #n ")" ::: "memory")
; #define PG8_BAR __builtin_amdgcn_s_barrier()
; #define PG8_SCHED __builtin_amdgcn_sched_barrier(0)
; template <class Epi, class Sched, bool ALIGN_EPI = false, bool SP2 = false>
; __device__ __forceinline__ void gemm_phase(PG8_LAS unsigned char* lds, const Gemm g, const Sched& S, const Epi& E) {
;     ...
;         for (int t = 0; t < nt; t += 2) {
;             const bool last = (t == nt - 2);
;             const char* a1 = cA + (size_t)(t + 1) * kstepA;
;             const char* a2 = last ? nA : cA + (size_t)(t + 2) * kstepA; const char* b2 = last ? nB : cB + (size_t)(t + 2) * kstep;
;     ...
;             PG8_LDA(At, 1, 1); PG8_STAGE(PG8_SB(1, 0), b3, voffB); PG8_STAGE(PG8_SB(1, 1), b3 + hstepB, voffB); PG8_STAGE(PG8_SA(1, 0), a3, voffA);
;             PG8_WAIT_V(8); PG8_WAIT_L(0); PG8_BAR; PG8_MMA(1, 0, At, B0); PG8_MMA(1, 1, At, B1); PG8_BAR; PG8_SCHED;
	s_add_i32 s20, s40, s22
	v_lshl_add_u64 v[192:193], v[192:193], 0, s[78:79]
	s_mov_b32 m0, s20
	ds_read_b128 v[176:179], v155 offset:49152
	ds_read_b128 v[180:183], v155 offset:50176
	ds_read_b128 v[184:187], v155 offset:51200
	ds_read_b128 v[188:191], v155 offset:52224
	ds_read_b128 v[206:209], v155 offset:53248
	ds_read_b128 v[210:213], v155 offset:54272
	ds_read_b128 v[214:217], v155 offset:55296
	ds_read_b128 v[218:221], v155 offset:56320
	global_load_lds_dwordx4 v[192:193], off
	s_add_i32 m0, s20, 0x2000
	s_add_u32 s18, s18, 0xb0080
	v_lshl_add_u64 v[192:193], v[222:223], 0, s[78:79]
	s_addc_u32 s19, s19, 0
	s_add_i32 s20, s41, s22
	global_load_lds_dwordx4 v[192:193], off
	v_lshl_add_u64 v[192:193], s[18:19], 0, v[0:1]
	s_mov_b32 m0, s20
	s_nop 0
	global_load_lds_dwordx4 v[192:193], off
	v_lshl_add_u64 v[192:193], s[18:19], 0, v[130:131]
	s_add_i32 m0, s20, 0x2000
	s_nop 0
	global_load_lds_dwordx4 v[192:193], off
	v_lshl_add_u64 v[192:193], s[16:17], 0, v[134:135]
	s_mov_b32 m0, s28
	s_nop 0
	global_load_lds_dwordx4 v[192:193], off
	v_lshl_add_u64 v[192:193], s[16:17], 0, v[132:133]
	s_mov_b32 m0, s29
	s_nop 0
	global_load_lds_dwordx4 v[192:193], off
	s_waitcnt vmcnt(8)
	s_waitcnt lgkmcnt(0)
	s_barrier
	s_setprio 1
	s_waitcnt lgkmcnt(0)
	v_mfma_f32_16x16x32_bf16 v[62:65], v[140:143], v[176:179], v[62:65]
	v_mfma_f32_16x16x32_bf16 v[58:61], v[148:151], v[176:179], v[58:61]
	v_mfma_f32_16x16x32_bf16 v[54:57], v[140:143], v[184:187], v[54:57]
	v_mfma_f32_16x16x32_bf16 v[46:49], v[148:151], v[184:187], v[46:49]
	v_mfma_f32_16x16x32_bf16 v[38:41], v[140:143], v[206:209], v[38:41]
	v_mfma_f32_16x16x32_bf16 v[30:33], v[148:151], v[206:209], v[30:33]
	v_mfma_f32_16x16x32_bf16 v[22:25], v[140:143], v[214:217], v[22:25]
	v_mfma_f32_16x16x32_bf16 v[14:17], v[148:151], v[214:217], v[14:17]
	v_mfma_f32_16x16x32_bf16 v[62:65], v[144:147], v[180:183], v[62:65]
	v_mfma_f32_16x16x32_bf16 v[58:61], v[156:159], v[180:183], v[58:61]
	v_mfma_f32_16x16x32_bf16 v[54:57], v[144:147], v[188:191], v[54:57]
	v_mfma_f32_16x16x32_bf16 v[46:49], v[156:159], v[188:191], v[46:49]
	v_mfma_f32_16x16x32_bf16 v[38:41], v[144:147], v[210:213], v[38:41]
	v_mfma_f32_16x16x32_bf16 v[30:33], v[156:159], v[210:213], v[30:33]
	v_mfma_f32_16x16x32_bf16 v[22:25], v[144:147], v[218:221], v[22:25]
	v_mfma_f32_16x16x32_bf16 v[14:17], v[156:159], v[218:221], v[14:17]
	s_setprio 0
	s_setprio 1
	v_mfma_f32_16x16x32_bf16 v[50:53], v[160:163], v[176:179], v[50:53]
	v_mfma_f32_16x16x32_bf16 v[42:45], v[168:171], v[176:179], v[42:45]
	v_mfma_f32_16x16x32_bf16 v[34:37], v[160:163], v[184:187], v[34:37]
	v_mfma_f32_16x16x32_bf16 v[26:29], v[168:171], v[184:187], v[26:29]
	v_mfma_f32_16x16x32_bf16 v[18:21], v[160:163], v[206:209], v[18:21]
	v_mfma_f32_16x16x32_bf16 v[10:13], v[168:171], v[206:209], v[10:13]
	v_mfma_f32_16x16x32_bf16 v[6:9], v[160:163], v[214:217], v[6:9]
	v_mfma_f32_16x16x32_bf16 v[2:5], v[168:171], v[214:217], v[2:5]
	v_mfma_f32_16x16x32_bf16 v[50:53], v[164:167], v[180:183], v[50:53]
	v_mfma_f32_16x16x32_bf16 v[42:45], v[172:175], v[180:183], v[42:45]
	v_mfma_f32_16x16x32_bf16 v[34:37], v[164:167], v[188:191], v[34:37]
	v_mfma_f32_16x16x32_bf16 v[26:29], v[172:175], v[188:191], v[26:29]
	v_mfma_f32_16x16x32_bf16 v[18:21], v[164:167], v[210:213], v[18:21]
	v_mfma_f32_16x16x32_bf16 v[10:13], v[172:175], v[210:213], v[10:13]
	v_mfma_f32_16x16x32_bf16 v[6:9], v[164:167], v[218:221], v[6:9]
	v_mfma_f32_16x16x32_bf16 v[2:5], v[172:175], v[218:221], v[2:5]
	s_setprio 0
	s_add_i32 s39, s39, 2
	s_add_u32 s0, s0, 0x800000
	s_addc_u32 s1, s1, 0
	s_add_u32 s37, s37, 0x100
	s_addc_u32 s38, s38, 0
	s_add_u32 s16, s0, 0x3fc000
	s_addc_u32 s17, s1, 0
	s_cmp_eq_u32 s39, 40
	s_cselect_b32 s20, s36, s16
	s_cselect_b32 s21, s11, s17
	s_cselect_b32 s18, s12, s37
	s_cselect_b32 s19, s13, s38
	s_add_u32 s16, s20, 0x400000
	s_addc_u32 s17, s21, 0
	s_add_i32 s40, 0, 0x10000
	s_add_i32 s42, 0, 0x14000
	s_cmp_gt_u32 s39, 41
	s_barrier
	s_cbranch_scc0 .LBB0_35
	s_and_b64 vcc, exec, s[8:9]
	s_cbranch_vccz .LBB0_38
	s_barrier

; #define PG8_STAGE(bufoff, gbase, voff) do { _Pragma("unroll") for (int _i = 0; _i < 2; ++_i) \
;         __builtin_amdgcn_global_load_lds((const unsigned*)((const char*)(gbase) + (voff)[_i]), (PG8_LAS unsigned*)(lds + (bufoff) + ldsw + _i * 8192), 16, 0, 0); } while (0)
; #define PG8_LDA(dst, b, h) do { _Pragma("unroll") for (int m = 0; m < 4; ++m) _Pragma("unroll") for (int k = 0; k < 2; ++k) dst[m][k] = *(const PG8_LAS bf16x8*)(lds + PG8_SA(b, h) + aoff + m * 2048 + k * 1024); } while (0)
; #define PG8_LDB(dst, b, h) do { _Pragma("unroll") for (int n = 0; n < 2; ++n) _Pragma("unroll") for (int k = 0; k < 2; ++k) dst[n][k] = *(const PG8_LAS bf16x8*)(lds + PG8_SB(b, h) + boff + n * 2048 + k * 1024); } while (0)
; #define PG8_MMA(ai, bj, At, Bt) do { __builtin_amdgcn_s_setprio(1); _Pragma("unroll") for (int m = 0; m < 4; ++m) _Pragma("unroll") for (int n = 0; n < 2; ++n) _Pragma("unroll") for (int k = 0; k < 2; ++k) \
;         acc[ai][bj][m][n] = __builtin_amdgcn_mfma_f32_16x16x32_bf16(Bt[n][k], At[m][k], acc[ai][bj][m][n], 0, 0, 0); __builtin_amdgcn_s_setprio(0); } while (0)
; template <class Epi, class Sched, bool ALIGN_EPI = false, bool SP2 = false>
; __device__ __forceinline__ void gemm_phase(PG8_LAS unsigned char* lds, const Gemm g, const Sched& S, const Epi& E) {
;     ...
;         const bool has_next = S.next(ui + 1, nxt);
;         const char* nA = has_next ? (const char*)g.A + (size_t)nxt.pm * tstepA + (size_t)nxt.pn * pnoffA : cA; const char* nB = has_next ? (const char*)g.Bt + (size_t)nxt.pn * tstepB : cB;
;         for (int t = 0; t < nt; t += 2) {
;             const bool last = (t == nt - 2);
;             const char* a1 = cA + (size_t)(t + 1) * kstepA;
;             const char* a2 = last ? nA : cA + (size_t)(t + 2) * kstepA; const char* b2 = last ? nB : cB + (size_t)(t + 2) * kstep;
;             const char* a3 = a2 + kstepA; const char* b3 = b2 + kstep;
;             if (last && has_next) S.a_ready(nxt);
;             if constexpr (SP2) {
;             PG8_LDB(B0, 0, 0); PG8_LDB(B1, 0, 1); PG8_SCHED; PG8_LDA(At, 0, 0); PG8_STAGE(PG8_SA(1, 1), a1 + hstepA, voffA);
;             PG8_WAIT_V(8); PG8_WAIT_L(0); PG8_BAR; PG8_MMA(0, 0, At, B0); PG8_MMA(0, 1, At, B1); PG8_BAR; PG8_SCHED;
;             PG8_LDA(At, 0, 1); PG8_STAGE(PG8_SB(0, 0), b2, voffB); PG8_STAGE(PG8_SB(0, 1), b2 + hstepB, voffB); PG8_STAGE(PG8_SA(0, 0), a2, voffA);
.LBB0_52:
	s_ashr_i32 s11, s10, 31
	s_lshl_b64 s[12:13], s[10:11], 15
	s_add_u32 s12, s72, s12
	s_addc_u32 s13, s73, s13
	s_and_b64 s[14:15], s[4:5], exec
	s_cselect_b32 s11, s13, s17
	s_cselect_b32 s38, s12, s16
	s_ashr_i32 s9, s8, 31
	s_lshl_b64 s[14:15], s[8:9], 19
	s_add_u32 s14, s66, s14
	s_addc_u32 s15, s67, s15
	s_and_b64 s[20:21], s[4:5], exec
	s_cselect_b32 s9, s15, s19
	s_cselect_b32 s39, s14, s18
	s_add_u32 s40, s18, 0x100
	s_addc_u32 s41, s19, 0
	s_add_u32 s16, s16, 0x404000
	s_addc_u32 s17, s17, 0
	s_mov_b32 s42, -2
	s_add_u32 s18, s16, 0x3fc000
	s_addc_u32 s19, s17, 0
	s_cmp_eq_u32 s42, 12
	s_cselect_b32 s22, s38, s18
	s_cselect_b32 s23, s11, s19
	s_cselect_b32 s20, s39, s40
	s_cselect_b32 s21, s9, s41
	s_add_u32 s18, s22, 0x400000
	s_addc_u32 s19, s23, 0
	s_add_i32 s43, 0, 0x10000
	v_add_u32_e32 v149, s43, v147
	s_add_i32 s46, 0, 0x14000
	ds_read_b128 v[142:145], v149
	ds_read_b128 v[150:153], v149 offset:1024
	ds_read_b128 v[154:157], v149 offset:2048
	ds_read_b128 v[158:161], v149 offset:3072
	v_add_u32_e32 v149, s46, v147
	ds_read_b128 v[162:165], v149
	ds_read_b128 v[166:169], v149 offset:1024
	ds_read_b128 v[170:173], v149 offset:2048
	ds_read_b128 v[174:177], v149 offset:3072
	v_lshl_add_u64 v[222:223], s[16:17], 0, v[138:139]
	s_add_i32 m0, s26, 0xc000
	ds_read_b128 v[178:181], v148
	ds_read_b128 v[182:185], v148 offset:1024
	ds_read_b128 v[186:189], v148 offset:2048
	ds_read_b128 v[190:193], v148 offset:3072
	ds_read_b128 v[206:209], v148 offset:4096
	ds_read_b128 v[210:213], v148 offset:5120
	ds_read_b128 v[214:217], v148 offset:6144
	ds_read_b128 v[218:221], v148 offset:7168
	global_load_lds_dwordx4 v[222:223], off
	v_lshl_add_u64 v[222:223], s[16:17], 0, v[140:141]
	s_add_i32 m0, s26, 0xe000
	s_nop 0
	global_load_lds_dwordx4 v[222:223], off
	s_waitcnt vmcnt(8)
	s_waitcnt lgkmcnt(0)
	s_barrier
	s_setprio 1
	s_waitcnt lgkmcnt(0)
	v_mfma_f32_16x16x32_bf16 v[126:129], v[142:145], v[178:181], 0
	v_mfma_f32_16x16x32_bf16 v[122:125], v[154:157], v[178:181], 0
	v_mfma_f32_16x16x32_bf16 v[110:113], v[142:145], v[186:189], 0
	v_mfma_f32_16x16x32_bf16 v[106:109], v[154:157], v[186:189], 0
	v_mfma_f32_16x16x32_bf16 v[94:97], v[142:145], v[206:209], 0
	v_mfma_f32_16x16x32_bf16 v[90:93], v[154:157], v[206:209], 0
	v_mfma_f32_16x16x32_bf16 v[78:81], v[142:145], v[214:217], 0
	v_mfma_f32_16x16x32_bf16 v[74:77], v[154:157], v[214:217], 0
	v_mfma_f32_16x16x32_bf16 v[126:129], v[150:153], v[182:185], v[126:129]
	v_mfma_f32_16x16x32_bf16 v[122:125], v[158:161], v[182:185], v[122:125]
	v_mfma_f32_16x16x32_bf16 v[110:113], v[150:153], v[190:193], v[110:113]
	v_mfma_f32_16x16x32_bf16 v[106:109], v[158:161], v[190:193], v[106:109]
	v_mfma_f32_16x16x32_bf16 v[94:97], v[150:153], v[210:213], v[94:97]
	v_mfma_f32_16x16x32_bf16 v[90:93], v[158:161], v[210:213], v[90:93]
	v_mfma_f32_16x16x32_bf16 v[78:81], v[150:153], v[218:221], v[78:81]
	v_mfma_f32_16x16x32_bf16 v[74:77], v[158:161], v[218:221], v[74:77]
	s_setprio 0
	s_setprio 1
	v_mfma_f32_16x16x32_bf16 v[118:121], v[162:165], v[178:181], 0
	v_mfma_f32_16x16x32_bf16 v[114:117], v[170:173], v[178:181], 0
	v_mfma_f32_16x16x32_bf16 v[102:105], v[162:165], v[186:189], 0
	v_mfma_f32_16x16x32_bf16 v[98:101], v[170:173], v[186:189], 0
	v_mfma_f32_16x16x32_bf16 v[86:89], v[162:165], v[206:209], 0
	v_mfma_f32_16x16x32_bf16 v[82:85], v[170:173], v[206:209], 0
	v_mfma_f32_16x16x32_bf16 v[70:73], v[162:165], v[214:217], 0
	v_mfma_f32_16x16x32_bf16 v[66:69], v[170:173], v[214:217], 0
	v_mfma_f32_16x16x32_bf16 v[118:121], v[166:169], v[182:185], v[118:121]
	v_mfma_f32_16x16x32_bf16 v[114:117], v[174:177], v[182:185], v[114:117]
	v_mfma_f32_16x16x32_bf16 v[102:105], v[166:169], v[190:193], v[102:105]
	v_mfma_f32_16x16x32_bf16 v[98:101], v[174:177], v[190:193], v[98:101]
	v_mfma_f32_16x16x32_bf16 v[86:89], v[166:169], v[210:213], v[86:89]
	v_mfma_f32_16x16x32_bf16 v[82:85], v[174:177], v[210:213], v[82:85]
	v_mfma_f32_16x16x32_bf16 v[70:73], v[166:169], v[218:221], v[70:73]
	v_mfma_f32_16x16x32_bf16 v[66:69], v[174:177], v[218:221], v[66:69]
	s_setprio 0
	s_barrier
	s_add_i32 s43, s43, s25
	v_lshl_add_u64 v[222:223], s[20:21], 0, v[0:1]
	s_mov_b32 m0, s43
	ds_read_b128 v[178:181], v148 offset:16384
	ds_read_b128 v[182:185], v148 offset:17408
	ds_read_b128 v[186:189], v148 offset:18432
	ds_read_b128 v[190:193], v148 offset:19456
	ds_read_b128 v[206:209], v148 offset:20480
	ds_read_b128 v[210:213], v148 offset:21504
	ds_read_b128 v[214:217], v148 offset:22528
	ds_read_b128 v[218:221], v148 offset:23552
	global_load_lds_dwordx4 v[222:223], off
	s_add_i32 m0, s43, 0x2000
	s_add_u32 s44, s20, 0x40000
	v_lshl_add_u64 v[224:225], s[20:21], 0, v[130:131]
	s_addc_u32 s45, s21, 0
	s_add_i32 s43, s46, s25
	global_load_lds_dwordx4 v[224:225], off
	v_lshl_add_u64 v[226:227], s[44:45], 0, v[0:1]
	s_mov_b32 m0, s43
	s_nop 0
	global_load_lds_dwordx4 v[226:227], off
	v_lshl_add_u64 v[226:227], s[44:45], 0, v[130:131]
	s_add_i32 m0, s43, 0x2000
	s_nop 0
	global_load_lds_dwordx4 v[226:227], off
	v_lshl_add_u64 v[226:227], s[22:23], 0, v[134:135]
	s_mov_b32 m0, s26
	s_nop 0
	global_load_lds_dwordx4 v[226:227], off
	v_lshl_add_u64 v[226:227], s[22:23], 0, v[132:133]
	s_mov_b32 m0, s27
	s_nop 0
	global_load_lds_dwordx4 v[226:227], off
	s_waitcnt vmcnt(8)
	s_waitcnt lgkmcnt(0)
	s_barrier
; #define PG8_STAGE(bufoff, gbase, voff) do { _Pragma("unroll") for (int _i = 0; _i < 2; ++_i) \
;         __builtin_amdgcn_global_load_lds((const unsigned*)((const char*)(gbase) + (voff)[_i]), (PG8_LAS unsigned*)(lds + (bufoff) + ldsw + _i * 8192), 16, 0, 0); } while (0)
; #define PG8_LDA(dst, b, h) do { _Pragma("unroll") for (int m = 0; m < 4; ++m) _Pragma("unroll") for (int k = 0; k < 2; ++k) dst[m][k] = *(const PG8_LAS bf16x8*)(lds + PG8_SA(b, h) + aoff + m * 2048 + k * 1024); } while (0)
; #define PG8_LDB(dst, b, h) do { _Pragma("unroll") for (int n = 0; n < 2; ++n) _Pragma("unroll") for (int k = 0; k < 2; ++k) dst[n][k] = *(const PG8_LAS bf16x8*)(lds + PG8_SB(b, h) + boff + n * 2048 + k * 1024); } while (0)
; #define PG8_MMA(ai, bj, At, Bt) do { __builtin_amdgcn_s_setprio(1); _Pragma("unroll") for (int m = 0; m < 4; ++m) _Pragma("unroll") for (int n = 0; n < 2; ++n) _Pragma("unroll") for (int k = 0; k < 2; ++k) \
;         acc[ai][bj][m][n] = __builtin_amdgcn_mfma_f32_16x16x32_bf16(Bt[n][k], At[m][k], acc[ai][bj][m][n], 0, 0, 0); __builtin_amdgcn_s_setprio(0); } while (0)
; #define PG8_WAIT_V(n) asm volatile("s_waitcnt vmcnt(" #n ")" ::: "memory")
; #define PG8_WAIT_L(n) asm volatile("s_waitcnt lgkmcnt(" #n ")" ::: "memory")
; #define PG8_BAR __builtin_amdgcn_s_barrier()
; #define PG8_SCHED __builtin_amdgcn_sched_barrier(0)
; template <class Epi, class Sched, bool ALIGN_EPI = false, bool SP2 = false>
; __device__ __forceinline__ void gemm_phase(PG8_LAS unsigned char* lds, const Gemm g, const Sched& S, const Epi& E) {
;     ...
;             PG8_WAIT_V(8); PG8_WAIT_L(0); PG8_BAR; PG8_MMA(1, 0, At, B0); PG8_MMA(1, 1, At, B1); PG8_BAR; PG8_SCHED;
;             PG8_LDB(B0, 1, 0); PG8_LDB(B1, 1, 1); PG8_SCHED; PG8_LDA(At, 1, 0); PG8_STAGE(PG8_SA(0, 1), a2 + hstepA, voffA);
;             PG8_WAIT_V(8); PG8_WAIT_L(0); PG8_BAR; PG8_MMA(0, 0, At, B0); PG8_MMA(0, 1, At, B1); PG8_BAR; PG8_SCHED;
;             PG8_LDA(At, 1, 1); PG8_STAGE(PG8_SB(1, 0), b3, voffB); PG8_STAGE(PG8_SB(1, 1), b3 + hstepB, voffB); PG8_STAGE(PG8_SA(1, 0), a3, voffA);
	s_setprio 1
	s_waitcnt lgkmcnt(0)
	v_mfma_f32_16x16x32_bf16 v[62:65], v[142:145], v[178:181], 0
	v_mfma_f32_16x16x32_bf16 v[58:61], v[154:157], v[178:181], 0
	v_mfma_f32_16x16x32_bf16 v[46:49], v[142:145], v[186:189], 0
	v_mfma_f32_16x16x32_bf16 v[42:45], v[154:157], v[186:189], 0
	v_mfma_f32_16x16x32_bf16 v[30:33], v[142:145], v[206:209], 0
	v_mfma_f32_16x16x32_bf16 v[26:29], v[154:157], v[206:209], 0
	v_mfma_f32_16x16x32_bf16 v[14:17], v[142:145], v[214:217], 0
	v_mfma_f32_16x16x32_bf16 v[10:13], v[154:157], v[214:217], 0
	v_mfma_f32_16x16x32_bf16 v[62:65], v[150:153], v[182:185], v[62:65]
	v_mfma_f32_16x16x32_bf16 v[58:61], v[158:161], v[182:185], v[58:61]
	v_mfma_f32_16x16x32_bf16 v[46:49], v[150:153], v[190:193], v[46:49]
	v_mfma_f32_16x16x32_bf16 v[42:45], v[158:161], v[190:193], v[42:45]
	v_mfma_f32_16x16x32_bf16 v[30:33], v[150:153], v[210:213], v[30:33]
	v_mfma_f32_16x16x32_bf16 v[26:29], v[158:161], v[210:213], v[26:29]
	v_mfma_f32_16x16x32_bf16 v[14:17], v[150:153], v[218:221], v[14:17]
	v_mfma_f32_16x16x32_bf16 v[10:13], v[158:161], v[218:221], v[10:13]
	s_setprio 0
	s_setprio 1
	v_mfma_f32_16x16x32_bf16 v[54:57], v[162:165], v[178:181], 0
	v_mfma_f32_16x16x32_bf16 v[50:53], v[170:173], v[178:181], 0
	v_mfma_f32_16x16x32_bf16 v[38:41], v[162:165], v[186:189], 0
	v_mfma_f32_16x16x32_bf16 v[34:37], v[170:173], v[186:189], 0
	v_mfma_f32_16x16x32_bf16 v[22:25], v[162:165], v[206:209], 0
	v_mfma_f32_16x16x32_bf16 v[18:21], v[170:173], v[206:209], 0
	v_mfma_f32_16x16x32_bf16 v[6:9], v[162:165], v[214:217], 0
	v_mfma_f32_16x16x32_bf16 v[2:5], v[170:173], v[214:217], 0
	v_mfma_f32_16x16x32_bf16 v[54:57], v[166:169], v[182:185], v[54:57]
	v_mfma_f32_16x16x32_bf16 v[50:53], v[174:177], v[182:185], v[50:53]
	v_mfma_f32_16x16x32_bf16 v[38:41], v[166:169], v[190:193], v[38:41]
	v_mfma_f32_16x16x32_bf16 v[34:37], v[174:177], v[190:193], v[34:37]
	v_mfma_f32_16x16x32_bf16 v[22:25], v[166:169], v[210:213], v[22:25]
	v_mfma_f32_16x16x32_bf16 v[18:21], v[174:177], v[210:213], v[18:21]
	v_mfma_f32_16x16x32_bf16 v[6:9], v[166:169], v[218:221], v[6:9]
	v_mfma_f32_16x16x32_bf16 v[2:5], v[174:177], v[218:221], v[2:5]
	s_setprio 0
	s_barrier
	s_add_i32 s43, 0, 0x18000
	v_add_u32_e32 v149, s43, v147
	s_add_i32 s44, 0, 0x1c000
	ds_read_b128 v[142:145], v149
	ds_read_b128 v[150:153], v149 offset:1024
	ds_read_b128 v[154:157], v149 offset:2048
	ds_read_b128 v[158:161], v149 offset:3072
	v_add_u32_e32 v149, s44, v147
	ds_read_b128 v[162:165], v149
	ds_read_b128 v[166:169], v149 offset:1024
	ds_read_b128 v[170:173], v149 offset:2048
	ds_read_b128 v[174:177], v149 offset:3072
	s_add_u32 s22, s22, 0x4000
	s_addc_u32 s23, s23, 0
	s_mov_b32 m0, s28
	v_lshl_add_u64 v[226:227], s[22:23], 0, v[134:135]
	ds_read_b128 v[178:181], v148 offset:32768
	ds_read_b128 v[182:185], v148 offset:33792
	ds_read_b128 v[186:189], v148 offset:34816
	ds_read_b128 v[190:193], v148 offset:35840
	ds_read_b128 v[206:209], v148 offset:36864
	ds_read_b128 v[210:213], v148 offset:37888
	ds_read_b128 v[214:217], v148 offset:38912
	ds_read_b128 v[218:221], v148 offset:39936
	global_load_lds_dwordx4 v[226:227], off
	v_lshl_add_u64 v[226:227], s[22:23], 0, v[132:133]
	s_mov_b32 m0, s29
	s_nop 0
	global_load_lds_dwordx4 v[226:227], off
	s_waitcnt vmcnt(8)
	s_waitcnt lgkmcnt(0)
	s_barrier
	s_setprio 1
	s_waitcnt lgkmcnt(0)
	v_mfma_f32_16x16x32_bf16 v[126:129], v[142:145], v[178:181], v[126:129]
	v_mfma_f32_16x16x32_bf16 v[122:125], v[154:157], v[178:181], v[122:125]
	v_mfma_f32_16x16x32_bf16 v[110:113], v[142:145], v[186:189], v[110:113]
	v_mfma_f32_16x16x32_bf16 v[106:109], v[154:157], v[186:189], v[106:109]
	v_mfma_f32_16x16x32_bf16 v[94:97], v[142:145], v[206:209], v[94:97]
	v_mfma_f32_16x16x32_bf16 v[90:93], v[154:157], v[206:209], v[90:93]
	v_mfma_f32_16x16x32_bf16 v[78:81], v[142:145], v[214:217], v[78:81]
	v_mfma_f32_16x16x32_bf16 v[74:77], v[154:157], v[214:217], v[74:77]
	v_mfma_f32_16x16x32_bf16 v[126:129], v[150:153], v[182:185], v[126:129]
	v_mfma_f32_16x16x32_bf16 v[122:125], v[158:161], v[182:185], v[122:125]
	v_mfma_f32_16x16x32_bf16 v[110:113], v[150:153], v[190:193], v[110:113]
	v_mfma_f32_16x16x32_bf16 v[106:109], v[158:161], v[190:193], v[106:109]
	v_mfma_f32_16x16x32_bf16 v[94:97], v[150:153], v[210:213], v[94:97]
	v_mfma_f32_16x16x32_bf16 v[90:93], v[158:161], v[210:213], v[90:93]
	v_mfma_f32_16x16x32_bf16 v[78:81], v[150:153], v[218:221], v[78:81]
	v_mfma_f32_16x16x32_bf16 v[74:77], v[158:161], v[218:221], v[74:77]
	s_setprio 0
	s_setprio 1
	v_mfma_f32_16x16x32_bf16 v[118:121], v[162:165], v[178:181], v[118:121]
	v_mfma_f32_16x16x32_bf16 v[114:117], v[170:173], v[178:181], v[114:117]
	v_mfma_f32_16x16x32_bf16 v[102:105], v[162:165], v[186:189], v[102:105]
	v_mfma_f32_16x16x32_bf16 v[98:101], v[170:173], v[186:189], v[98:101]
	v_mfma_f32_16x16x32_bf16 v[86:89], v[162:165], v[206:209], v[86:89]
	v_mfma_f32_16x16x32_bf16 v[82:85], v[170:173], v[206:209], v[82:85]
	v_mfma_f32_16x16x32_bf16 v[70:73], v[162:165], v[214:217], v[70:73]
	v_mfma_f32_16x16x32_bf16 v[66:69], v[170:173], v[214:217], v[66:69]
	v_mfma_f32_16x16x32_bf16 v[118:121], v[166:169], v[182:185], v[118:121]
	v_mfma_f32_16x16x32_bf16 v[114:117], v[174:177], v[182:185], v[114:117]
	v_mfma_f32_16x16x32_bf16 v[102:105], v[166:169], v[190:193], v[102:105]
	v_mfma_f32_16x16x32_bf16 v[98:101], v[174:177], v[190:193], v[98:101]
	v_mfma_f32_16x16x32_bf16 v[86:89], v[166:169], v[210:213], v[86:89]
	v_mfma_f32_16x16x32_bf16 v[82:85], v[174:177], v[210:213], v[82:85]
	v_mfma_f32_16x16x32_bf16 v[70:73], v[166:169], v[218:221], v[70:73]
	v_mfma_f32_16x16x32_bf16 v[66:69], v[174:177], v[218:221], v[66:69]
	s_setprio 0
	s_barrier
; #define PG8_STAGE(bufoff, gbase, voff) do { _Pragma("unroll") for (int _i = 0; _i < 2; ++_i) \
;         __builtin_amdgcn_global_load_lds((const unsigned*)((const char*)(gbase) + (voff)[_i]), (PG8_LAS unsigned*)(lds + (bufoff) + ldsw + _i * 8192), 16, 0, 0); } while (0)
; #define PG8_LDA(dst, b, h) do { _Pragma("unroll") for (int m = 0; m < 4; ++m) _Pragma("unroll") for (int k = 0; k < 2; ++k) dst[m][k] = *(const PG8_LAS bf16x8*)(lds + PG8_SA(b, h) + aoff + m * 2048 + k * 1024); } while (0)
; #define PG8_LDB(dst, b, h) do { _Pragma("unroll") for (int n = 0; n < 2; ++n) _Pragma("unroll") for (int k = 0; k < 2; ++k) dst[n][k] = *(const PG8_LAS bf16x8*)(lds + PG8_SB(b, h) + boff + n * 2048 + k * 1024); } while (0)
; template <class Epi, class Sched, bool ALIGN_EPI = false, bool SP2 = false>
; __device__ __forceinline__ void gemm_phase(PG8_LAS unsigned char* lds, const Gemm g, const Sched& S, const Epi& E) {
;     ...
;         for (int t = 0; t < nt; t += 2) {
;             const bool last = (t == nt - 2);
;             const char* a1 = cA + (size_t)(t + 1) * kstepA;
;             const char* a2 = last ? nA : cA + (size_t)(t + 2) * kstepA; const char* b2 = last ? nB : cB + (size_t)(t + 2) * kstep;
;             const char* a3 = a2 + kstepA; const char* b3 = b2 + kstep;
;             if (last && has_next) S.a_ready(nxt);
;             if constexpr (SP2) {
;             PG8_LDB(B0, 0, 0); PG8_LDB(B1, 0, 1); PG8_SCHED; PG8_LDA(At, 0, 0); PG8_STAGE(PG8_SA(1, 1), a1 + hstepA, voffA);
;             PG8_WAIT_V(8); PG8_WAIT_L(0); PG8_BAR; PG8_MMA(0, 0, At, B0); PG8_MMA(0, 1, At, B1); PG8_BAR; PG8_SCHED;
;             PG8_LDA(At, 0, 1); PG8_STAGE(PG8_SB(0, 0), b2, voffB); PG8_STAGE(PG8_SB(0, 1), b2 + hstepB, voffB); PG8_STAGE(PG8_SA(0, 0), a2, voffA);
;             PG8_WAIT_V(8); PG8_WAIT_L(0); PG8_BAR; PG8_MMA(1, 0, At, B0); PG8_MMA(1, 1, At, B1); PG8_BAR; PG8_SCHED;
;             PG8_LDB(B0, 1, 0); PG8_LDB(B1, 1, 1); PG8_SCHED; PG8_LDA(At, 1, 0); PG8_STAGE(PG8_SA(0, 1), a2 + hstepA, voffA);
;             PG8_WAIT_V(8); PG8_WAIT_L(0); PG8_BAR; PG8_MMA(0, 0, At, B0); PG8_MMA(0, 1, At, B1); PG8_BAR; PG8_SCHED;
;             PG8_LDA(At, 1, 1); PG8_STAGE(PG8_SB(1, 0), b3, voffB); PG8_STAGE(PG8_SB(1, 1), b3 + hstepB, voffB); PG8_STAGE(PG8_SA(1, 0), a3, voffA);
;             PG8_WAIT_V(8); PG8_WAIT_L(0); PG8_BAR; PG8_MMA(1, 0, At, B0); PG8_MMA(1, 1, At, B1); PG8_BAR; PG8_SCHED;
	s_add_i32 s22, s43, s25
	v_lshl_add_u64 v[222:223], v[222:223], 0, s[78:79]
	s_mov_b32 m0, s22
	ds_read_b128 v[178:181], v148 offset:49152
	ds_read_b128 v[182:185], v148 offset:50176
	ds_read_b128 v[186:189], v148 offset:51200
	ds_read_b128 v[190:193], v148 offset:52224
	ds_read_b128 v[206:209], v148 offset:53248
	ds_read_b128 v[210:213], v148 offset:54272
	ds_read_b128 v[214:217], v148 offset:55296
	ds_read_b128 v[218:221], v148 offset:56320
	global_load_lds_dwordx4 v[222:223], off
	s_add_i32 m0, s22, 0x2000
	s_add_u32 s20, s20, 0x40080
	v_lshl_add_u64 v[222:223], v[224:225], 0, s[78:79]
	s_addc_u32 s21, s21, 0
	s_add_i32 s22, s44, s25
	global_load_lds_dwordx4 v[222:223], off
	v_lshl_add_u64 v[222:223], s[20:21], 0, v[0:1]
	s_mov_b32 m0, s22
	s_nop 0
	global_load_lds_dwordx4 v[222:223], off
	v_lshl_add_u64 v[222:223], s[20:21], 0, v[130:131]
	s_add_i32 m0, s22, 0x2000
	s_nop 0
	global_load_lds_dwordx4 v[222:223], off
	v_lshl_add_u64 v[222:223], s[18:19], 0, v[134:135]
	s_mov_b32 m0, s30
	s_nop 0
	global_load_lds_dwordx4 v[222:223], off
	v_lshl_add_u64 v[222:223], s[18:19], 0, v[132:133]
	s_mov_b32 m0, s31
	s_nop 0
	global_load_lds_dwordx4 v[222:223], off
	s_waitcnt vmcnt(8)
	s_waitcnt lgkmcnt(0)
	s_barrier
	s_setprio 1
	s_waitcnt lgkmcnt(0)
	v_mfma_f32_16x16x32_bf16 v[62:65], v[142:145], v[178:181], v[62:65]
	v_mfma_f32_16x16x32_bf16 v[58:61], v[154:157], v[178:181], v[58:61]
	v_mfma_f32_16x16x32_bf16 v[46:49], v[142:145], v[186:189], v[46:49]
	v_mfma_f32_16x16x32_bf16 v[42:45], v[154:157], v[186:189], v[42:45]
	v_mfma_f32_16x16x32_bf16 v[30:33], v[142:145], v[206:209], v[30:33]
	v_mfma_f32_16x16x32_bf16 v[26:29], v[154:157], v[206:209], v[26:29]
	v_mfma_f32_16x16x32_bf16 v[14:17], v[142:145], v[214:217], v[14:17]
	v_mfma_f32_16x16x32_bf16 v[10:13], v[154:157], v[214:217], v[10:13]
	v_mfma_f32_16x16x32_bf16 v[62:65], v[150:153], v[182:185], v[62:65]
	v_mfma_f32_16x16x32_bf16 v[58:61], v[158:161], v[182:185], v[58:61]
	v_mfma_f32_16x16x32_bf16 v[46:49], v[150:153], v[190:193], v[46:49]
	v_mfma_f32_16x16x32_bf16 v[42:45], v[158:161], v[190:193], v[42:45]
	v_mfma_f32_16x16x32_bf16 v[30:33], v[150:153], v[210:213], v[30:33]
	v_mfma_f32_16x16x32_bf16 v[26:29], v[158:161], v[210:213], v[26:29]
	v_mfma_f32_16x16x32_bf16 v[14:17], v[150:153], v[218:221], v[14:17]
	v_mfma_f32_16x16x32_bf16 v[10:13], v[158:161], v[218:221], v[10:13]
	s_setprio 0
	s_setprio 1
	v_mfma_f32_16x16x32_bf16 v[54:57], v[162:165], v[178:181], v[54:57]
	v_mfma_f32_16x16x32_bf16 v[50:53], v[170:173], v[178:181], v[50:53]
	v_mfma_f32_16x16x32_bf16 v[38:41], v[162:165], v[186:189], v[38:41]
	v_mfma_f32_16x16x32_bf16 v[34:37], v[170:173], v[186:189], v[34:37]
	v_mfma_f32_16x16x32_bf16 v[22:25], v[162:165], v[206:209], v[22:25]
	v_mfma_f32_16x16x32_bf16 v[18:21], v[170:173], v[206:209], v[18:21]
	v_mfma_f32_16x16x32_bf16 v[6:9], v[162:165], v[214:217], v[6:9]
	v_mfma_f32_16x16x32_bf16 v[2:5], v[170:173], v[214:217], v[2:5]
	v_mfma_f32_16x16x32_bf16 v[54:57], v[166:169], v[182:185], v[54:57]
	v_mfma_f32_16x16x32_bf16 v[50:53], v[174:177], v[182:185], v[50:53]
	v_mfma_f32_16x16x32_bf16 v[38:41], v[166:169], v[190:193], v[38:41]
	v_mfma_f32_16x16x32_bf16 v[34:37], v[174:177], v[190:193], v[34:37]
	v_mfma_f32_16x16x32_bf16 v[22:25], v[166:169], v[210:213], v[22:25]
	v_mfma_f32_16x16x32_bf16 v[18:21], v[174:177], v[210:213], v[18:21]
	v_mfma_f32_16x16x32_bf16 v[6:9], v[166:169], v[218:221], v[6:9]
	v_mfma_f32_16x16x32_bf16 v[2:5], v[174:177], v[218:221], v[2:5]
	s_setprio 0
	s_add_i32 s42, s42, 2
	s_add_u32 s40, s40, 0x100
	s_addc_u32 s41, s41, 0
	s_add_u32 s16, s16, 0x800000
	s_addc_u32 s17, s17, 0
	s_add_u32 s18, s16, 0x3fc000
	s_addc_u32 s19, s17, 0
	s_cmp_eq_u32 s42, 12
	s_cselect_b32 s22, s38, s18
	s_cselect_b32 s23, s11, s19
	s_cselect_b32 s20, s39, s40
	s_cselect_b32 s21, s9, s41
	s_add_u32 s18, s22, 0x400000
	s_addc_u32 s19, s23, 0
	s_add_i32 s43, 0, 0x10000
	s_barrier
.LBB0_53:
	v_add_u32_e32 v149, s43, v147
	s_add_i32 s46, 0, 0x14000
	ds_read_b128 v[142:145], v149
	ds_read_b128 v[150:153], v149 offset:1024
	ds_read_b128 v[154:157], v149 offset:2048
	ds_read_b128 v[158:161], v149 offset:3072
	v_add_u32_e32 v149, s46, v147
	ds_read_b128 v[162:165], v149
	ds_read_b128 v[166:169], v149 offset:1024
	ds_read_b128 v[170:173], v149 offset:2048
	ds_read_b128 v[174:177], v149 offset:3072
	v_lshl_add_u64 v[222:223], s[16:17], 0, v[138:139]
	s_add_i32 m0, s26, 0xc000
	ds_read_b128 v[178:181], v148
	ds_read_b128 v[182:185], v148 offset:1024
	ds_read_b128 v[186:189], v148 offset:2048
	ds_read_b128 v[190:193], v148 offset:3072
	ds_read_b128 v[206:209], v148 offset:4096
	ds_read_b128 v[210:213], v148 offset:5120
	ds_read_b128 v[214:217], v148 offset:6144
	ds_read_b128 v[218:221], v148 offset:7168
	global_load_lds_dwordx4 v[222:223], off
	v_lshl_add_u64 v[222:223], s[16:17], 0, v[140:141]
	s_add_i32 m0, s26, 0xe000
	s_nop 0
	global_load_lds_dwordx4 v[222:223], off
	s_waitcnt vmcnt(8)
	s_waitcnt lgkmcnt(0)
	s_barrier
; #define PG8_STAGE(bufoff, gbase, voff) do { _Pragma("unroll") for (int _i = 0; _i < 2; ++_i) \
;         __builtin_amdgcn_global_load_lds((const unsigned*)((const char*)(gbase) + (voff)[_i]), (PG8_LAS unsigned*)(lds + (bufoff) + ldsw + _i * 8192), 16, 0, 0); } while (0)
; #define PG8_LDA(dst, b, h) do { _Pragma("unroll") for (int m = 0; m < 4; ++m) _Pragma("unroll") for (int k = 0; k < 2; ++k) dst[m][k] = *(const PG8_LAS bf16x8*)(lds + PG8_SA(b, h) + aoff + m * 2048 + k * 1024); } while (0)
; #define PG8_LDB(dst, b, h) do { _Pragma("unroll") for (int n = 0; n < 2; ++n) _Pragma("unroll") for (int k = 0; k < 2; ++k) dst[n][k] = *(const PG8_LAS bf16x8*)(lds + PG8_SB(b, h) + boff + n * 2048 + k * 1024); } while (0)
; #define PG8_MMA(ai, bj, At, Bt) do { __builtin_amdgcn_s_setprio(1); _Pragma("unroll") for (int m = 0; m < 4; ++m) _Pragma("unroll") for (int n = 0; n < 2; ++n) _Pragma("unroll") for (int k = 0; k < 2; ++k) \
;         acc[ai][bj][m][n] = __builtin_amdgcn_mfma_f32_16x16x32_bf16(Bt[n][k], At[m][k], acc[ai][bj][m][n], 0, 0, 0); __builtin_amdgcn_s_setprio(0); } while (0)
; #define PG8_WAIT_V(n) asm volatile("s_waitcnt vmcnt(" #n ")" ::: "memory")
; #define PG8_WAIT_L(n) asm volatile("s_waitcnt lgkmcnt(" #n ")" ::: "memory")
; #define PG8_BAR __builtin_amdgcn_s_barrier()
; #define PG8_SCHED __builtin_amdgcn_sched_barrier(0)
; template <class Epi, class Sched, bool ALIGN_EPI = false, bool SP2 = false>
; __device__ __forceinline__ void gemm_phase(PG8_LAS unsigned char* lds, const Gemm g, const Sched& S, const Epi& E) {
;     ...
;             PG8_LDB(B0, 0, 0); PG8_LDB(B1, 0, 1); PG8_SCHED; PG8_LDA(At, 0, 0); PG8_STAGE(PG8_SA(1, 1), a1 + hstepA, voffA);
;             PG8_WAIT_V(8); PG8_WAIT_L(0); PG8_BAR; PG8_MMA(0, 0, At, B0); PG8_MMA(0, 1, At, B1); PG8_BAR; PG8_SCHED;
;             PG8_LDA(At, 0, 1); PG8_STAGE(PG8_SB(0, 0), b2, voffB); PG8_STAGE(PG8_SB(0, 1), b2 + hstepB, voffB); PG8_STAGE(PG8_SA(0, 0), a2, voffA);
;             PG8_WAIT_V(8); PG8_WAIT_L(0); PG8_BAR; PG8_MMA(1, 0, At, B0); PG8_MMA(1, 1, At, B1); PG8_BAR; PG8_SCHED;
	s_setprio 1
	s_waitcnt lgkmcnt(0)
	v_mfma_f32_16x16x32_bf16 v[126:129], v[142:145], v[178:181], v[126:129]
	v_mfma_f32_16x16x32_bf16 v[122:125], v[154:157], v[178:181], v[122:125]
	v_mfma_f32_16x16x32_bf16 v[110:113], v[142:145], v[186:189], v[110:113]
	v_mfma_f32_16x16x32_bf16 v[106:109], v[154:157], v[186:189], v[106:109]
	v_mfma_f32_16x16x32_bf16 v[94:97], v[142:145], v[206:209], v[94:97]
	v_mfma_f32_16x16x32_bf16 v[90:93], v[154:157], v[206:209], v[90:93]
	v_mfma_f32_16x16x32_bf16 v[78:81], v[142:145], v[214:217], v[78:81]
	v_mfma_f32_16x16x32_bf16 v[74:77], v[154:157], v[214:217], v[74:77]
	v_mfma_f32_16x16x32_bf16 v[126:129], v[150:153], v[182:185], v[126:129]
	v_mfma_f32_16x16x32_bf16 v[122:125], v[158:161], v[182:185], v[122:125]
	v_mfma_f32_16x16x32_bf16 v[110:113], v[150:153], v[190:193], v[110:113]
	v_mfma_f32_16x16x32_bf16 v[106:109], v[158:161], v[190:193], v[106:109]
	v_mfma_f32_16x16x32_bf16 v[94:97], v[150:153], v[210:213], v[94:97]
	v_mfma_f32_16x16x32_bf16 v[90:93], v[158:161], v[210:213], v[90:93]
	v_mfma_f32_16x16x32_bf16 v[78:81], v[150:153], v[218:221], v[78:81]
	v_mfma_f32_16x16x32_bf16 v[74:77], v[158:161], v[218:221], v[74:77]
	s_setprio 0
	s_setprio 1
	v_mfma_f32_16x16x32_bf16 v[118:121], v[162:165], v[178:181], v[118:121]
	v_mfma_f32_16x16x32_bf16 v[114:117], v[170:173], v[178:181], v[114:117]
	v_mfma_f32_16x16x32_bf16 v[102:105], v[162:165], v[186:189], v[102:105]
	v_mfma_f32_16x16x32_bf16 v[98:101], v[170:173], v[186:189], v[98:101]
	v_mfma_f32_16x16x32_bf16 v[86:89], v[162:165], v[206:209], v[86:89]
	v_mfma_f32_16x16x32_bf16 v[82:85], v[170:173], v[206:209], v[82:85]
	v_mfma_f32_16x16x32_bf16 v[70:73], v[162:165], v[214:217], v[70:73]
	v_mfma_f32_16x16x32_bf16 v[66:69], v[170:173], v[214:217], v[66:69]
	v_mfma_f32_16x16x32_bf16 v[118:121], v[166:169], v[182:185], v[118:121]
	v_mfma_f32_16x16x32_bf16 v[114:117], v[174:177], v[182:185], v[114:117]
	v_mfma_f32_16x16x32_bf16 v[102:105], v[166:169], v[190:193], v[102:105]
	v_mfma_f32_16x16x32_bf16 v[98:101], v[174:177], v[190:193], v[98:101]
	v_mfma_f32_16x16x32_bf16 v[86:89], v[166:169], v[210:213], v[86:89]
	v_mfma_f32_16x16x32_bf16 v[82:85], v[174:177], v[210:213], v[82:85]
	v_mfma_f32_16x16x32_bf16 v[70:73], v[166:169], v[218:221], v[70:73]
	v_mfma_f32_16x16x32_bf16 v[66:69], v[174:177], v[218:221], v[66:69]
	s_setprio 0
	s_barrier
	s_add_i32 s43, s43, s25
	v_lshl_add_u64 v[222:223], s[20:21], 0, v[0:1]
	s_mov_b32 m0, s43
	ds_read_b128 v[178:181], v148 offset:16384
	ds_read_b128 v[182:185], v148 offset:17408
	ds_read_b128 v[186:189], v148 offset:18432
	ds_read_b128 v[190:193], v148 offset:19456
	ds_read_b128 v[206:209], v148 offset:20480
	ds_read_b128 v[210:213], v148 offset:21504
	ds_read_b128 v[214:217], v148 offset:22528
	ds_read_b128 v[218:221], v148 offset:23552
	global_load_lds_dwordx4 v[222:223], off
	s_add_i32 m0, s43, 0x2000
	s_add_u32 s44, s20, 0x40000
	v_lshl_add_u64 v[224:225], s[20:21], 0, v[130:131]
	s_addc_u32 s45, s21, 0
	s_add_i32 s43, s46, s25
	global_load_lds_dwordx4 v[224:225], off
	v_lshl_add_u64 v[226:227], s[44:45], 0, v[0:1]
	s_mov_b32 m0, s43
	s_nop 0
	global_load_lds_dwordx4 v[226:227], off
	v_lshl_add_u64 v[226:227], s[44:45], 0, v[130:131]
	s_add_i32 m0, s43, 0x2000
	s_nop 0
	global_load_lds_dwordx4 v[226:227], off
	v_lshl_add_u64 v[226:227], s[22:23], 0, v[134:135]
	s_mov_b32 m0, s26
	s_nop 0
	global_load_lds_dwordx4 v[226:227], off
	v_lshl_add_u64 v[226:227], s[22:23], 0, v[132:133]
	s_mov_b32 m0, s27
	s_nop 0
	global_load_lds_dwordx4 v[226:227], off
	s_waitcnt vmcnt(8)
	s_waitcnt lgkmcnt(0)
	s_barrier
	s_setprio 1
	s_waitcnt lgkmcnt(0)
	v_mfma_f32_16x16x32_bf16 v[62:65], v[142:145], v[178:181], v[62:65]
	v_mfma_f32_16x16x32_bf16 v[58:61], v[154:157], v[178:181], v[58:61]
	v_mfma_f32_16x16x32_bf16 v[46:49], v[142:145], v[186:189], v[46:49]
	v_mfma_f32_16x16x32_bf16 v[42:45], v[154:157], v[186:189], v[42:45]
	v_mfma_f32_16x16x32_bf16 v[30:33], v[142:145], v[206:209], v[30:33]
	v_mfma_f32_16x16x32_bf16 v[26:29], v[154:157], v[206:209], v[26:29]
	v_mfma_f32_16x16x32_bf16 v[14:17], v[142:145], v[214:217], v[14:17]
	v_mfma_f32_16x16x32_bf16 v[10:13], v[154:157], v[214:217], v[10:13]
	v_mfma_f32_16x16x32_bf16 v[62:65], v[150:153], v[182:185], v[62:65]
	v_mfma_f32_16x16x32_bf16 v[58:61], v[158:161], v[182:185], v[58:61]
	v_mfma_f32_16x16x32_bf16 v[46:49], v[150:153], v[190:193], v[46:49]
	v_mfma_f32_16x16x32_bf16 v[42:45], v[158:161], v[190:193], v[42:45]
	v_mfma_f32_16x16x32_bf16 v[30:33], v[150:153], v[210:213], v[30:33]
	v_mfma_f32_16x16x32_bf16 v[26:29], v[158:161], v[210:213], v[26:29]
	v_mfma_f32_16x16x32_bf16 v[14:17], v[150:153], v[218:221], v[14:17]
	v_mfma_f32_16x16x32_bf16 v[10:13], v[158:161], v[218:221], v[10:13]
	s_setprio 0
	s_setprio 1
	v_mfma_f32_16x16x32_bf16 v[54:57], v[162:165], v[178:181], v[54:57]
	v_mfma_f32_16x16x32_bf16 v[50:53], v[170:173], v[178:181], v[50:53]
	v_mfma_f32_16x16x32_bf16 v[38:41], v[162:165], v[186:189], v[38:41]
	v_mfma_f32_16x16x32_bf16 v[34:37], v[170:173], v[186:189], v[34:37]
	v_mfma_f32_16x16x32_bf16 v[22:25], v[162:165], v[206:209], v[22:25]
	v_mfma_f32_16x16x32_bf16 v[18:21], v[170:173], v[206:209], v[18:21]
	v_mfma_f32_16x16x32_bf16 v[6:9], v[162:165], v[214:217], v[6:9]
	v_mfma_f32_16x16x32_bf16 v[2:5], v[170:173], v[214:217], v[2:5]
	v_mfma_f32_16x16x32_bf16 v[54:57], v[166:169], v[182:185], v[54:57]
	v_mfma_f32_16x16x32_bf16 v[50:53], v[174:177], v[182:185], v[50:53]
	v_mfma_f32_16x16x32_bf16 v[38:41], v[166:169], v[190:193], v[38:41]
	v_mfma_f32_16x16x32_bf16 v[34:37], v[174:177], v[190:193], v[34:37]
	v_mfma_f32_16x16x32_bf16 v[22:25], v[166:169], v[210:213], v[22:25]
	v_mfma_f32_16x16x32_bf16 v[18:21], v[174:177], v[210:213], v[18:21]
	v_mfma_f32_16x16x32_bf16 v[6:9], v[166:169], v[218:221], v[6:9]
	v_mfma_f32_16x16x32_bf16 v[2:5], v[174:177], v[218:221], v[2:5]
	s_setprio 0
	s_barrier
; #define PG8_STAGE(bufoff, gbase, voff) do { _Pragma("unroll") for (int _i = 0; _i < 2; ++_i) \
;         __builtin_amdgcn_global_load_lds((const unsigned*)((const char*)(gbase) + (voff)[_i]), (PG8_LAS unsigned*)(lds + (bufoff) + ldsw + _i * 8192), 16, 0, 0); } while (0)
; #define PG8_LDA(dst, b, h) do { _Pragma("unroll") for (int m = 0; m < 4; ++m) _Pragma("unroll") for (int k = 0; k < 2; ++k) dst[m][k] = *(const PG8_LAS bf16x8*)(lds + PG8_SA(b, h) + aoff + m * 2048 + k * 1024); } while (0)
; #define PG8_LDB(dst, b, h) do { _Pragma("unroll") for (int n = 0; n < 2; ++n) _Pragma("unroll") for (int k = 0; k < 2; ++k) dst[n][k] = *(const PG8_LAS bf16x8*)(lds + PG8_SB(b, h) + boff + n * 2048 + k * 1024); } while (0)
; #define PG8_MMA(ai, bj, At, Bt) do { __builtin_amdgcn_s_setprio(1); _Pragma("unroll") for (int m = 0; m < 4; ++m) _Pragma("unroll") for (int n = 0; n < 2; ++n) _Pragma("unroll") for (int k = 0; k < 2; ++k) \
;         acc[ai][bj][m][n] = __builtin_amdgcn_mfma_f32_16x16x32_bf16(Bt[n][k], At[m][k], acc[ai][bj][m][n], 0, 0, 0); __builtin_amdgcn_s_setprio(0); } while (0)
; #define PG8_WAIT_V(n) asm volatile("s_waitcnt vmcnt(" #n ")" ::: "memory")
; #define PG8_WAIT_L(n) asm volatile("s_waitcnt lgkmcnt(" #n ")" ::: "memory")
; #define PG8_BAR __builtin_amdgcn_s_barrier()
; #define PG8_SCHED __builtin_amdgcn_sched_barrier(0)
; template <class Epi, class Sched, bool ALIGN_EPI = false, bool SP2 = false>
; __device__ __forceinline__ void gemm_phase(PG8_LAS unsigned char* lds, const Gemm g, const Sched& S, const Epi& E) {
;     ...
;             PG8_LDB(B0, 1, 0); PG8_LDB(B1, 1, 1); PG8_SCHED; PG8_LDA(At, 1, 0); PG8_STAGE(PG8_SA(0, 1), a2 + hstepA, voffA);
;             PG8_WAIT_V(8); PG8_WAIT_L(0); PG8_BAR; PG8_MMA(0, 0, At, B0); PG8_MMA(0, 1, At, B1); PG8_BAR; PG8_SCHED;
	s_add_i32 s43, 0, 0x18000
	v_add_u32_e32 v149, s43, v147
	s_add_i32 s44, 0, 0x1c000
	ds_read_b128 v[142:145], v149
	ds_read_b128 v[150:153], v149 offset:1024
	ds_read_b128 v[154:157], v149 offset:2048
	ds_read_b128 v[158:161], v149 offset:3072
	v_add_u32_e32 v149, s44, v147
	ds_read_b128 v[162:165], v149
	ds_read_b128 v[166:169], v149 offset:1024
	ds_read_b128 v[170:173], v149 offset:2048
	ds_read_b128 v[174:177], v149 offset:3072
	s_add_u32 s22, s22, 0x4000
	s_addc_u32 s23, s23, 0
	s_mov_b32 m0, s28
	v_lshl_add_u64 v[226:227], s[22:23], 0, v[134:135]
	ds_read_b128 v[178:181], v148 offset:32768
	ds_read_b128 v[182:185], v148 offset:33792
	ds_read_b128 v[186:189], v148 offset:34816
	ds_read_b128 v[190:193], v148 offset:35840
	ds_read_b128 v[206:209], v148 offset:36864
	ds_read_b128 v[210:213], v148 offset:37888
	ds_read_b128 v[214:217], v148 offset:38912
	ds_read_b128 v[218:221], v148 offset:39936
	global_load_lds_dwordx4 v[226:227], off
	v_lshl_add_u64 v[226:227], s[22:23], 0, v[132:133]
	s_mov_b32 m0, s29
	s_nop 0
	global_load_lds_dwordx4 v[226:227], off
	s_waitcnt vmcnt(8)
	s_waitcnt lgkmcnt(0)
	s_barrier
	s_setprio 1
	s_waitcnt lgkmcnt(0)
	v_mfma_f32_16x16x32_bf16 v[126:129], v[142:145], v[178:181], v[126:129]
	v_mfma_f32_16x16x32_bf16 v[122:125], v[154:157], v[178:181], v[122:125]
	v_mfma_f32_16x16x32_bf16 v[110:113], v[142:145], v[186:189], v[110:113]
	v_mfma_f32_16x16x32_bf16 v[106:109], v[154:157], v[186:189], v[106:109]
	v_mfma_f32_16x16x32_bf16 v[94:97], v[142:145], v[206:209], v[94:97]
	v_mfma_f32_16x16x32_bf16 v[90:93], v[154:157], v[206:209], v[90:93]
	v_mfma_f32_16x16x32_bf16 v[78:81], v[142:145], v[214:217], v[78:81]
	v_mfma_f32_16x16x32_bf16 v[74:77], v[154:157], v[214:217], v[74:77]
	v_mfma_f32_16x16x32_bf16 v[126:129], v[150:153], v[182:185], v[126:129]
	v_mfma_f32_16x16x32_bf16 v[122:125], v[158:161], v[182:185], v[122:125]
	v_mfma_f32_16x16x32_bf16 v[110:113], v[150:153], v[190:193], v[110:113]
	v_mfma_f32_16x16x32_bf16 v[106:109], v[158:161], v[190:193], v[106:109]
	v_mfma_f32_16x16x32_bf16 v[94:97], v[150:153], v[210:213], v[94:97]
	v_mfma_f32_16x16x32_bf16 v[90:93], v[158:161], v[210:213], v[90:93]
	v_mfma_f32_16x16x32_bf16 v[78:81], v[150:153], v[218:221], v[78:81]
	v_mfma_f32_16x16x32_bf16 v[74:77], v[158:161], v[218:221], v[74:77]
	s_setprio 0
	s_setprio 1
	v_mfma_f32_16x16x32_bf16 v[118:121], v[162:165], v[178:181], v[118:121]
	v_mfma_f32_16x16x32_bf16 v[114:117], v[170:173], v[178:181], v[114:117]
	v_mfma_f32_16x16x32_bf16 v[102:105], v[162:165], v[186:189], v[102:105]
	v_mfma_f32_16x16x32_bf16 v[98:101], v[170:173], v[186:189], v[98:101]
	v_mfma_f32_16x16x32_bf16 v[86:89], v[162:165], v[206:209], v[86:89]
	v_mfma_f32_16x16x32_bf16 v[82:85], v[170:173], v[206:209], v[82:85]
	v_mfma_f32_16x16x32_bf16 v[70:73], v[162:165], v[214:217], v[70:73]
	v_mfma_f32_16x16x32_bf16 v[66:69], v[170:173], v[214:217], v[66:69]
	v_mfma_f32_16x16x32_bf16 v[118:121], v[166:169], v[182:185], v[118:121]
	v_mfma_f32_16x16x32_bf16 v[114:117], v[174:177], v[182:185], v[114:117]
	v_mfma_f32_16x16x32_bf16 v[102:105], v[166:169], v[190:193], v[102:105]
	v_mfma_f32_16x16x32_bf16 v[98:101], v[174:177], v[190:193], v[98:101]
	v_mfma_f32_16x16x32_bf16 v[86:89], v[166:169], v[210:213], v[86:89]
	v_mfma_f32_16x16x32_bf16 v[82:85], v[174:177], v[210:213], v[82:85]
	v_mfma_f32_16x16x32_bf16 v[70:73], v[166:169], v[218:221], v[70:73]
	v_mfma_f32_16x16x32_bf16 v[66:69], v[174:177], v[218:221], v[66:69]
	s_setprio 0
	s_barrier
; #define PG8_STAGE(bufoff, gbase, voff) do { _Pragma("unroll") for (int _i = 0; _i < 2; ++_i) \
;         __builtin_amdgcn_global_load_lds((const unsigned*)((const char*)(gbase) + (voff)[_i]), (PG8_LAS unsigned*)(lds + (bufoff) + ldsw + _i * 8192), 16, 0, 0); } while (0)
; #define PG8_LDA(dst, b, h) do { _Pragma("unroll") for (int m = 0; m < 4; ++m) _Pragma("unroll") for (int k = 0; k < 2; ++k) dst[m][k] = *(const PG8_LAS bf16x8*)(lds + PG8_SA(b, h) + aoff + m * 2048 + k * 1024); } while (0)
; #define PG8_LDB(dst, b, h) do { _Pragma("unroll") for (int n = 0; n < 2; ++n) _Pragma("unroll") for (int k = 0; k < 2; ++k) dst[n][k] = *(const PG8_LAS bf16x8*)(lds + PG8_SB(b, h) + boff + n * 2048 + k * 1024); } while (0)
; template <class Epi, class Sched, bool ALIGN_EPI = false, bool SP2 = false>
; __device__ __forceinline__ void gemm_phase(PG8_LAS unsigned char* lds, const Gemm g, const Sched& S, const Epi& E) {
;     ...
;         for (int t = 0; t < nt; t += 2) {
;             const bool last = (t == nt - 2);
;             const char* a1 = cA + (size_t)(t + 1) * kstepA;
;             const char* a2 = last ? nA : cA + (size_t)(t + 2) * kstepA; const char* b2 = last ? nB : cB + (size_t)(t + 2) * kstep;
;             const char* a3 = a2 + kstepA; const char* b3 = b2 + kstep;
;             if (last && has_next) S.a_ready(nxt);
;             if constexpr (SP2) {
;             PG8_LDB(B0, 0, 0); PG8_LDB(B1, 0, 1); PG8_SCHED; PG8_LDA(At, 0, 0); PG8_STAGE(PG8_SA(1, 1), a1 + hstepA, voffA);
;             PG8_WAIT_V(8); PG8_WAIT_L(0); PG8_BAR; PG8_MMA(0, 0, At, B0); PG8_MMA(0, 1, At, B1); PG8_BAR; PG8_SCHED;
;             PG8_LDA(At, 0, 1); PG8_STAGE(PG8_SB(0, 0), b2, voffB); PG8_STAGE(PG8_SB(0, 1), b2 + hstepB, voffB); PG8_STAGE(PG8_SA(0, 0), a2, voffA);
;             PG8_WAIT_V(8); PG8_WAIT_L(0); PG8_BAR; PG8_MMA(1, 0, At, B0); PG8_MMA(1, 1, At, B1); PG8_BAR; PG8_SCHED;
;             PG8_LDB(B0, 1, 0); PG8_LDB(B1, 1, 1); PG8_SCHED; PG8_LDA(At, 1, 0); PG8_STAGE(PG8_SA(0, 1), a2 + hstepA, voffA);
;             PG8_WAIT_V(8); PG8_WAIT_L(0); PG8_BAR; PG8_MMA(0, 0, At, B0); PG8_MMA(0, 1, At, B1); PG8_BAR; PG8_SCHED;
;             PG8_LDA(At, 1, 1); PG8_STAGE(PG8_SB(1, 0), b3, voffB); PG8_STAGE(PG8_SB(1, 1), b3 + hstepB, voffB); PG8_STAGE(PG8_SA(1, 0), a3, voffA);
;             PG8_WAIT_V(8); PG8_WAIT_L(0); PG8_BAR; PG8_MMA(1, 0, At, B0); PG8_MMA(1, 1, At, B1); PG8_BAR; PG8_SCHED;
	s_add_i32 s22, s43, s25
	v_lshl_add_u64 v[222:223], v[222:223], 0, s[78:79]
	s_mov_b32 m0, s22
	ds_read_b128 v[178:181], v148 offset:49152
	ds_read_b128 v[182:185], v148 offset:50176
	ds_read_b128 v[186:189], v148 offset:51200
	ds_read_b128 v[190:193], v148 offset:52224
	ds_read_b128 v[206:209], v148 offset:53248
	ds_read_b128 v[210:213], v148 offset:54272
	ds_read_b128 v[214:217], v148 offset:55296
	ds_read_b128 v[218:221], v148 offset:56320
	global_load_lds_dwordx4 v[222:223], off
	s_add_i32 m0, s22, 0x2000
	s_add_u32 s20, s20, 0x40080
	v_lshl_add_u64 v[222:223], v[224:225], 0, s[78:79]
	s_addc_u32 s21, s21, 0
	s_add_i32 s22, s44, s25
	global_load_lds_dwordx4 v[222:223], off
	v_lshl_add_u64 v[222:223], s[20:21], 0, v[0:1]
	s_mov_b32 m0, s22
	s_nop 0
	global_load_lds_dwordx4 v[222:223], off
	v_lshl_add_u64 v[222:223], s[20:21], 0, v[130:131]
	s_add_i32 m0, s22, 0x2000
	s_nop 0
	global_load_lds_dwordx4 v[222:223], off
	v_lshl_add_u64 v[222:223], s[18:19], 0, v[134:135]
	s_mov_b32 m0, s30
	s_nop 0
	global_load_lds_dwordx4 v[222:223], off
	v_lshl_add_u64 v[222:223], s[18:19], 0, v[132:133]
	s_mov_b32 m0, s31
	s_nop 0
	global_load_lds_dwordx4 v[222:223], off
	s_waitcnt vmcnt(8)
	s_waitcnt lgkmcnt(0)
	s_barrier
	s_setprio 1
	s_waitcnt lgkmcnt(0)
	v_mfma_f32_16x16x32_bf16 v[62:65], v[142:145], v[178:181], v[62:65]
	v_mfma_f32_16x16x32_bf16 v[58:61], v[154:157], v[178:181], v[58:61]
	v_mfma_f32_16x16x32_bf16 v[46:49], v[142:145], v[186:189], v[46:49]
	v_mfma_f32_16x16x32_bf16 v[42:45], v[154:157], v[186:189], v[42:45]
	v_mfma_f32_16x16x32_bf16 v[30:33], v[142:145], v[206:209], v[30:33]
	v_mfma_f32_16x16x32_bf16 v[26:29], v[154:157], v[206:209], v[26:29]
	v_mfma_f32_16x16x32_bf16 v[14:17], v[142:145], v[214:217], v[14:17]
	v_mfma_f32_16x16x32_bf16 v[10:13], v[154:157], v[214:217], v[10:13]
	v_mfma_f32_16x16x32_bf16 v[62:65], v[150:153], v[182:185], v[62:65]
	v_mfma_f32_16x16x32_bf16 v[58:61], v[158:161], v[182:185], v[58:61]
	v_mfma_f32_16x16x32_bf16 v[46:49], v[150:153], v[190:193], v[46:49]
	v_mfma_f32_16x16x32_bf16 v[42:45], v[158:161], v[190:193], v[42:45]
	v_mfma_f32_16x16x32_bf16 v[30:33], v[150:153], v[210:213], v[30:33]
	v_mfma_f32_16x16x32_bf16 v[26:29], v[158:161], v[210:213], v[26:29]
	v_mfma_f32_16x16x32_bf16 v[14:17], v[150:153], v[218:221], v[14:17]
	v_mfma_f32_16x16x32_bf16 v[10:13], v[158:161], v[218:221], v[10:13]
	s_setprio 0
	s_setprio 1
	v_mfma_f32_16x16x32_bf16 v[54:57], v[162:165], v[178:181], v[54:57]
	v_mfma_f32_16x16x32_bf16 v[50:53], v[170:173], v[178:181], v[50:53]
	v_mfma_f32_16x16x32_bf16 v[38:41], v[162:165], v[186:189], v[38:41]
	v_mfma_f32_16x16x32_bf16 v[34:37], v[170:173], v[186:189], v[34:37]
	v_mfma_f32_16x16x32_bf16 v[22:25], v[162:165], v[206:209], v[22:25]
	v_mfma_f32_16x16x32_bf16 v[18:21], v[170:173], v[206:209], v[18:21]
	v_mfma_f32_16x16x32_bf16 v[6:9], v[162:165], v[214:217], v[6:9]
	v_mfma_f32_16x16x32_bf16 v[2:5], v[170:173], v[214:217], v[2:5]
	v_mfma_f32_16x16x32_bf16 v[54:57], v[166:169], v[182:185], v[54:57]
	v_mfma_f32_16x16x32_bf16 v[50:53], v[174:177], v[182:185], v[50:53]
	v_mfma_f32_16x16x32_bf16 v[38:41], v[166:169], v[190:193], v[38:41]
	v_mfma_f32_16x16x32_bf16 v[34:37], v[174:177], v[190:193], v[34:37]
	v_mfma_f32_16x16x32_bf16 v[22:25], v[166:169], v[210:213], v[22:25]
	v_mfma_f32_16x16x32_bf16 v[18:21], v[174:177], v[210:213], v[18:21]
	v_mfma_f32_16x16x32_bf16 v[6:9], v[166:169], v[218:221], v[6:9]
	v_mfma_f32_16x16x32_bf16 v[2:5], v[174:177], v[218:221], v[2:5]
	s_setprio 0
	s_add_i32 s42, s42, 2
	s_add_u32 s40, s40, 0x100
	s_addc_u32 s41, s41, 0
	s_add_u32 s16, s16, 0x800000
	s_addc_u32 s17, s17, 0
	s_add_u32 s18, s16, 0x3fc000
	s_addc_u32 s19, s17, 0
	s_cmp_eq_u32 s42, 12
	s_cselect_b32 s22, s38, s18
	s_cselect_b32 s23, s11, s19
	s_cselect_b32 s20, s39, s40
	s_cselect_b32 s21, s9, s41
	s_add_u32 s18, s22, 0x400000
	s_addc_u32 s19, s23, 0
	s_add_i32 s43, 0, 0x10000
	s_cmp_gt_u32 s42, 13
	s_barrier
	s_cbranch_scc0 .LBB0_53
	s_and_b64 vcc, exec, s[6:7]
	s_cbranch_vccz .LBB0_56
	s_barrier

; #define PG8_STAGE(bufoff, gbase, voff) do { _Pragma("unroll") for (int _i = 0; _i < 2; ++_i) \
;         __builtin_amdgcn_global_load_lds((const unsigned*)((const char*)(gbase) + (voff)[_i]), (PG8_LAS unsigned*)(lds + (bufoff) + ldsw + _i * 8192), 16, 0, 0); } while (0)
; #define PG8_LDA(dst, b, h) do { _Pragma("unroll") for (int m = 0; m < 4; ++m) _Pragma("unroll") for (int k = 0; k < 2; ++k) dst[m][k] = *(const PG8_LAS bf16x8*)(lds + PG8_SA(b, h) + aoff + m * 2048 + k * 1024); } while (0)
; #define PG8_LDB(dst, b, h) do { _Pragma("unroll") for (int n = 0; n < 2; ++n) _Pragma("unroll") for (int k = 0; k < 2; ++k) dst[n][k] = *(const PG8_LAS bf16x8*)(lds + PG8_SB(b, h) + boff + n * 2048 + k * 1024); } while (0)
; #define PG8_WAIT_V(n) asm volatile("s_waitcnt vmcnt(" #n ")" ::: "memory")
; #define PG8_WAIT_L(n) asm volatile("s_waitcnt lgkmcnt(" #n ")" ::: "memory")
; #define PG8_BAR __builtin_amdgcn_s_barrier()
; #define PG8_SCHED __builtin_amdgcn_sched_barrier(0)
; template <class Epi, class Sched, bool ALIGN_EPI = false, bool SP2 = false>
; __device__ __forceinline__ void gemm_phase(PG8_LAS unsigned char* lds, const Gemm g, const Sched& S, const Epi& E) {
;     ...
;     for (;;) {
;         const bool has_next = S.next(ui + 1, nxt);
;         const char* nA = has_next ? (const char*)g.A + (size_t)nxt.pm * tstepA + (size_t)nxt.pn * pnoffA : cA; const char* nB = has_next ? (const char*)g.Bt + (size_t)nxt.pn * tstepB : cB;
;         for (int t = 0; t < nt; t += 2) {
;             const bool last = (t == nt - 2);
;             const char* a1 = cA + (size_t)(t + 1) * kstepA;
;             const char* a2 = last ? nA : cA + (size_t)(t + 2) * kstepA; const char* b2 = last ? nB : cB + (size_t)(t + 2) * kstep;
;             const char* a3 = a2 + kstepA; const char* b3 = b2 + kstep;
;             if (last && has_next) S.a_ready(nxt);
;             if constexpr (SP2) {
;             PG8_LDB(B0, 0, 0); PG8_LDB(B1, 0, 1); PG8_SCHED; PG8_LDA(At, 0, 0); PG8_STAGE(PG8_SA(1, 1), a1 + hstepA, voffA);
;             PG8_WAIT_V(8); PG8_WAIT_L(0); PG8_BAR; PG8_MMA(0, 0, At, B0); PG8_MMA(0, 1, At, B1); PG8_BAR; PG8_SCHED;
;             PG8_LDA(At, 0, 1); PG8_STAGE(PG8_SB(0, 0), b2, voffB); PG8_STAGE(PG8_SB(0, 1), b2 + hstepB, voffB); PG8_STAGE(PG8_SA(0, 0), a2, voffA);
;             PG8_WAIT_V(8); PG8_WAIT_L(0); PG8_BAR; PG8_MMA(1, 0, At, B0); PG8_MMA(1, 1, At, B1); PG8_BAR; PG8_SCHED;
.LBB0_86:
	s_ashr_i32 s17, s16, 31
	s_lshl_b64 s[18:19], s[16:17], 15
	s_add_u32 s18, s70, s18
	s_addc_u32 s19, s71, s19
	s_and_b64 s[20:21], s[6:7], exec
	s_cselect_b32 s17, s19, s23
	s_cselect_b32 s42, s18, s22
	s_ashr_i32 s15, s14, 31
	s_lshl_b64 s[20:21], s[14:15], 19
	v_readlane_b32 s26, v253, 55
	v_readlane_b32 s27, v253, 56
	s_add_u32 s20, s26, s20
	s_addc_u32 s21, s27, s21
	s_and_b64 s[26:27], s[6:7], exec
	s_cselect_b32 s15, s21, s25
	s_cselect_b32 s43, s20, s24
	s_add_u32 s22, s22, 0x204000
	s_addc_u32 s23, s23, 0
	s_add_u32 s44, s24, 0x100
	s_addc_u32 s45, s25, 0
	s_mov_b32 s46, -2
	s_add_u32 s24, s22, 0x1fc000
	s_addc_u32 s25, s23, 0
	s_cmp_eq_u32 s46, 12
	s_cselect_b32 s28, s42, s24
	s_cselect_b32 s29, s17, s25
	s_cselect_b32 s26, s43, s44
	s_cselect_b32 s27, s15, s45
	s_add_u32 s24, s28, 0x200000
	s_addc_u32 s25, s29, 0
	s_add_i32 s47, 0, 0x10000
	s_add_i32 s50, 0, 0x14000
	v_add_u32_e32 v152, s47, v161
	v_add_u32_e32 v172, s50, v161
	ds_read_b128 v[130:133], v152
	ds_read_b128 v[134:137], v152 offset:1024
	ds_read_b128 v[138:141], v152 offset:2048
	ds_read_b128 v[152:155], v152 offset:3072
	ds_read_b128 v[156:159], v172
	ds_read_b128 v[164:167], v172 offset:1024
	ds_read_b128 v[168:171], v172 offset:2048
	ds_read_b128 v[172:175], v172 offset:3072
	v_lshl_add_u64 v[192:193], s[22:23], 0, v[148:149]
	s_add_i32 m0, s31, 0xc000
	ds_read_b128 v[176:179], v163
	ds_read_b128 v[180:183], v163 offset:1024
	ds_read_b128 v[184:187], v163 offset:2048
	ds_read_b128 v[188:191], v163 offset:3072
	ds_read_b128 v[206:209], v163 offset:4096
	ds_read_b128 v[210:213], v163 offset:5120
	ds_read_b128 v[214:217], v163 offset:6144
	ds_read_b128 v[218:221], v163 offset:7168
	global_load_lds_dwordx4 v[192:193], off
	v_lshl_add_u64 v[192:193], s[22:23], 0, v[150:151]
	s_add_i32 m0, s31, 0xe000
	s_nop 0
	global_load_lds_dwordx4 v[192:193], off
	s_waitcnt vmcnt(8)
	s_waitcnt lgkmcnt(0)
	s_barrier
	s_setprio 1
	s_waitcnt lgkmcnt(0)
	v_mfma_f32_16x16x32_bf16 v[126:129], v[130:133], v[176:179], 0
	v_mfma_f32_16x16x32_bf16 v[122:125], v[138:141], v[176:179], 0
	v_mfma_f32_16x16x32_bf16 v[118:121], v[130:133], v[184:187], 0
	v_mfma_f32_16x16x32_bf16 v[106:109], v[138:141], v[184:187], 0
	v_mfma_f32_16x16x32_bf16 v[102:105], v[130:133], v[206:209], 0
	v_mfma_f32_16x16x32_bf16 v[90:93], v[138:141], v[206:209], 0
	v_mfma_f32_16x16x32_bf16 v[86:89], v[130:133], v[214:217], 0
	v_mfma_f32_16x16x32_bf16 v[74:77], v[138:141], v[214:217], 0
	v_mfma_f32_16x16x32_bf16 v[126:129], v[134:137], v[180:183], v[126:129]
	v_mfma_f32_16x16x32_bf16 v[122:125], v[152:155], v[180:183], v[122:125]
	v_mfma_f32_16x16x32_bf16 v[118:121], v[134:137], v[188:191], v[118:121]
	v_mfma_f32_16x16x32_bf16 v[106:109], v[152:155], v[188:191], v[106:109]
	v_mfma_f32_16x16x32_bf16 v[102:105], v[134:137], v[210:213], v[102:105]
	v_mfma_f32_16x16x32_bf16 v[90:93], v[152:155], v[210:213], v[90:93]
	v_mfma_f32_16x16x32_bf16 v[86:89], v[134:137], v[218:221], v[86:89]
	v_mfma_f32_16x16x32_bf16 v[74:77], v[152:155], v[218:221], v[74:77]
	s_setprio 0
	s_setprio 1
	v_mfma_f32_16x16x32_bf16 v[114:117], v[156:159], v[176:179], 0
	v_mfma_f32_16x16x32_bf16 v[110:113], v[168:171], v[176:179], 0
	v_mfma_f32_16x16x32_bf16 v[98:101], v[156:159], v[184:187], 0
	v_mfma_f32_16x16x32_bf16 v[94:97], v[168:171], v[184:187], 0
	v_mfma_f32_16x16x32_bf16 v[82:85], v[156:159], v[206:209], 0
	v_mfma_f32_16x16x32_bf16 v[78:81], v[168:171], v[206:209], 0
	v_mfma_f32_16x16x32_bf16 v[70:73], v[156:159], v[214:217], 0
	v_mfma_f32_16x16x32_bf16 v[66:69], v[168:171], v[214:217], 0
	v_mfma_f32_16x16x32_bf16 v[114:117], v[164:167], v[180:183], v[114:117]
	v_mfma_f32_16x16x32_bf16 v[110:113], v[172:175], v[180:183], v[110:113]
	v_mfma_f32_16x16x32_bf16 v[98:101], v[164:167], v[188:191], v[98:101]
	v_mfma_f32_16x16x32_bf16 v[94:97], v[172:175], v[188:191], v[94:97]
	v_mfma_f32_16x16x32_bf16 v[82:85], v[164:167], v[210:213], v[82:85]
	v_mfma_f32_16x16x32_bf16 v[78:81], v[172:175], v[210:213], v[78:81]
	v_mfma_f32_16x16x32_bf16 v[70:73], v[164:167], v[218:221], v[70:73]
	v_mfma_f32_16x16x32_bf16 v[66:69], v[172:175], v[218:221], v[66:69]
	s_setprio 0
	s_barrier
	s_add_i32 s47, s47, s30
	v_lshl_add_u64 v[192:193], s[26:27], 0, v[0:1]
	s_mov_b32 m0, s47
	ds_read_b128 v[176:179], v163 offset:16384
	ds_read_b128 v[180:183], v163 offset:17408
	ds_read_b128 v[184:187], v163 offset:18432
	ds_read_b128 v[188:191], v163 offset:19456
	ds_read_b128 v[206:209], v163 offset:20480
	ds_read_b128 v[210:213], v163 offset:21504
	ds_read_b128 v[214:217], v163 offset:22528
	ds_read_b128 v[218:221], v163 offset:23552
	global_load_lds_dwordx4 v[192:193], off
	s_add_i32 m0, s47, 0x2000
	s_add_u32 s48, s26, 0x40000
	v_lshl_add_u64 v[222:223], s[26:27], 0, v[142:143]
	s_addc_u32 s49, s27, 0
	s_add_i32 s47, s50, s30
	global_load_lds_dwordx4 v[222:223], off
	v_lshl_add_u64 v[224:225], s[48:49], 0, v[0:1]
	s_mov_b32 m0, s47
	s_nop 0
	global_load_lds_dwordx4 v[224:225], off
	v_lshl_add_u64 v[224:225], s[48:49], 0, v[142:143]
	s_add_i32 m0, s47, 0x2000
	s_nop 0
	global_load_lds_dwordx4 v[224:225], off
	v_lshl_add_u64 v[224:225], s[28:29], 0, v[146:147]
	s_mov_b32 m0, s31
	s_nop 0
	global_load_lds_dwordx4 v[224:225], off
	v_lshl_add_u64 v[224:225], s[28:29], 0, v[144:145]
	s_mov_b32 m0, s34
	s_nop 0
	global_load_lds_dwordx4 v[224:225], off
	s_waitcnt vmcnt(8)
	s_waitcnt lgkmcnt(0)
	s_barrier
; #define PG8_STAGE(bufoff, gbase, voff) do { _Pragma("unroll") for (int _i = 0; _i < 2; ++_i) \
;         __builtin_amdgcn_global_load_lds((const unsigned*)((const char*)(gbase) + (voff)[_i]), (PG8_LAS unsigned*)(lds + (bufoff) + ldsw + _i * 8192), 16, 0, 0); } while (0)
; #define PG8_LDA(dst, b, h) do { _Pragma("unroll") for (int m = 0; m < 4; ++m) _Pragma("unroll") for (int k = 0; k < 2; ++k) dst[m][k] = *(const PG8_LAS bf16x8*)(lds + PG8_SA(b, h) + aoff + m * 2048 + k * 1024); } while (0)
; #define PG8_LDB(dst, b, h) do { _Pragma("unroll") for (int n = 0; n < 2; ++n) _Pragma("unroll") for (int k = 0; k < 2; ++k) dst[n][k] = *(const PG8_LAS bf16x8*)(lds + PG8_SB(b, h) + boff + n * 2048 + k * 1024); } while (0)
; #define PG8_MMA(ai, bj, At, Bt) do { __builtin_amdgcn_s_setprio(1); _Pragma("unroll") for (int m = 0; m < 4; ++m) _Pragma("unroll") for (int n = 0; n < 2; ++n) _Pragma("unroll") for (int k = 0; k < 2; ++k) \
;         acc[ai][bj][m][n] = __builtin_amdgcn_mfma_f32_16x16x32_bf16(Bt[n][k], At[m][k], acc[ai][bj][m][n], 0, 0, 0); __builtin_amdgcn_s_setprio(0); } while (0)
; #define PG8_WAIT_V(n) asm volatile("s_waitcnt vmcnt(" #n ")" ::: "memory")
; #define PG8_WAIT_L(n) asm volatile("s_waitcnt lgkmcnt(" #n ")" ::: "memory")
; #define PG8_BAR __builtin_amdgcn_s_barrier()
; #define PG8_SCHED __builtin_amdgcn_sched_barrier(0)
; template <class Epi, class Sched, bool ALIGN_EPI = false, bool SP2 = false>
; __device__ __forceinline__ void gemm_phase(PG8_LAS unsigned char* lds, const Gemm g, const Sched& S, const Epi& E) {
;     ...
;             PG8_WAIT_V(8); PG8_WAIT_L(0); PG8_BAR; PG8_MMA(1, 0, At, B0); PG8_MMA(1, 1, At, B1); PG8_BAR; PG8_SCHED;
;             PG8_LDB(B0, 1, 0); PG8_LDB(B1, 1, 1); PG8_SCHED; PG8_LDA(At, 1, 0); PG8_STAGE(PG8_SA(0, 1), a2 + hstepA, voffA);
;             PG8_WAIT_V(8); PG8_WAIT_L(0); PG8_BAR; PG8_MMA(0, 0, At, B0); PG8_MMA(0, 1, At, B1); PG8_BAR; PG8_SCHED;
	s_setprio 1
	s_waitcnt lgkmcnt(0)
	v_mfma_f32_16x16x32_bf16 v[62:65], v[130:133], v[176:179], 0
	v_mfma_f32_16x16x32_bf16 v[58:61], v[138:141], v[176:179], 0
	v_mfma_f32_16x16x32_bf16 v[54:57], v[130:133], v[184:187], 0
	v_mfma_f32_16x16x32_bf16 v[42:45], v[138:141], v[184:187], 0
	v_mfma_f32_16x16x32_bf16 v[38:41], v[130:133], v[206:209], 0
	v_mfma_f32_16x16x32_bf16 v[26:29], v[138:141], v[206:209], 0
	v_mfma_f32_16x16x32_bf16 v[22:25], v[130:133], v[214:217], 0
	v_mfma_f32_16x16x32_bf16 v[10:13], v[138:141], v[214:217], 0
	v_mfma_f32_16x16x32_bf16 v[62:65], v[134:137], v[180:183], v[62:65]
	v_mfma_f32_16x16x32_bf16 v[58:61], v[152:155], v[180:183], v[58:61]
	v_mfma_f32_16x16x32_bf16 v[54:57], v[134:137], v[188:191], v[54:57]
	v_mfma_f32_16x16x32_bf16 v[42:45], v[152:155], v[188:191], v[42:45]
	v_mfma_f32_16x16x32_bf16 v[38:41], v[134:137], v[210:213], v[38:41]
	v_mfma_f32_16x16x32_bf16 v[26:29], v[152:155], v[210:213], v[26:29]
	v_mfma_f32_16x16x32_bf16 v[22:25], v[134:137], v[218:221], v[22:25]
	v_mfma_f32_16x16x32_bf16 v[10:13], v[152:155], v[218:221], v[10:13]
	s_setprio 0
	s_setprio 1
	v_mfma_f32_16x16x32_bf16 v[50:53], v[156:159], v[176:179], 0
	v_mfma_f32_16x16x32_bf16 v[46:49], v[168:171], v[176:179], 0
	v_mfma_f32_16x16x32_bf16 v[34:37], v[156:159], v[184:187], 0
	v_mfma_f32_16x16x32_bf16 v[30:33], v[168:171], v[184:187], 0
	v_mfma_f32_16x16x32_bf16 v[18:21], v[156:159], v[206:209], 0
	v_mfma_f32_16x16x32_bf16 v[14:17], v[168:171], v[206:209], 0
	v_mfma_f32_16x16x32_bf16 v[6:9], v[156:159], v[214:217], 0
	v_mfma_f32_16x16x32_bf16 v[2:5], v[168:171], v[214:217], 0
	v_mfma_f32_16x16x32_bf16 v[50:53], v[164:167], v[180:183], v[50:53]
	v_mfma_f32_16x16x32_bf16 v[46:49], v[172:175], v[180:183], v[46:49]
	v_mfma_f32_16x16x32_bf16 v[34:37], v[164:167], v[188:191], v[34:37]
	v_mfma_f32_16x16x32_bf16 v[30:33], v[172:175], v[188:191], v[30:33]
	v_mfma_f32_16x16x32_bf16 v[18:21], v[164:167], v[210:213], v[18:21]
	v_mfma_f32_16x16x32_bf16 v[14:17], v[172:175], v[210:213], v[14:17]
	v_mfma_f32_16x16x32_bf16 v[6:9], v[164:167], v[218:221], v[6:9]
	v_mfma_f32_16x16x32_bf16 v[2:5], v[172:175], v[218:221], v[2:5]
	s_setprio 0
	s_barrier
	s_add_i32 s47, 0, 0x18000
	s_add_i32 s48, 0, 0x1c000
	v_add_u32_e32 v152, s47, v161
	v_add_u32_e32 v172, s48, v161
	ds_read_b128 v[130:133], v152
	ds_read_b128 v[134:137], v152 offset:1024
	ds_read_b128 v[138:141], v152 offset:2048
	ds_read_b128 v[152:155], v152 offset:3072
	ds_read_b128 v[156:159], v172
	ds_read_b128 v[164:167], v172 offset:1024
	ds_read_b128 v[168:171], v172 offset:2048
	ds_read_b128 v[172:175], v172 offset:3072
	s_add_u32 s28, s28, 0x4000
	s_addc_u32 s29, s29, 0
	s_mov_b32 m0, s35
	v_lshl_add_u64 v[224:225], s[28:29], 0, v[146:147]
	ds_read_b128 v[176:179], v163 offset:32768
	ds_read_b128 v[180:183], v163 offset:33792
	ds_read_b128 v[184:187], v163 offset:34816
	ds_read_b128 v[188:191], v163 offset:35840
	ds_read_b128 v[206:209], v163 offset:36864
	ds_read_b128 v[210:213], v163 offset:37888
	ds_read_b128 v[214:217], v163 offset:38912
	ds_read_b128 v[218:221], v163 offset:39936
	global_load_lds_dwordx4 v[224:225], off
	v_lshl_add_u64 v[224:225], s[28:29], 0, v[144:145]
	s_mov_b32 m0, s36
	s_nop 0
	global_load_lds_dwordx4 v[224:225], off
	s_waitcnt vmcnt(8)
	s_waitcnt lgkmcnt(0)
	s_barrier
	s_setprio 1
	s_waitcnt lgkmcnt(0)
	v_mfma_f32_16x16x32_bf16 v[126:129], v[130:133], v[176:179], v[126:129]
	v_mfma_f32_16x16x32_bf16 v[122:125], v[138:141], v[176:179], v[122:125]
	v_mfma_f32_16x16x32_bf16 v[118:121], v[130:133], v[184:187], v[118:121]
	v_mfma_f32_16x16x32_bf16 v[106:109], v[138:141], v[184:187], v[106:109]
	v_mfma_f32_16x16x32_bf16 v[102:105], v[130:133], v[206:209], v[102:105]
	v_mfma_f32_16x16x32_bf16 v[90:93], v[138:141], v[206:209], v[90:93]
	v_mfma_f32_16x16x32_bf16 v[86:89], v[130:133], v[214:217], v[86:89]
	v_mfma_f32_16x16x32_bf16 v[74:77], v[138:141], v[214:217], v[74:77]
	v_mfma_f32_16x16x32_bf16 v[126:129], v[134:137], v[180:183], v[126:129]
	v_mfma_f32_16x16x32_bf16 v[122:125], v[152:155], v[180:183], v[122:125]
	v_mfma_f32_16x16x32_bf16 v[118:121], v[134:137], v[188:191], v[118:121]
	v_mfma_f32_16x16x32_bf16 v[106:109], v[152:155], v[188:191], v[106:109]
	v_mfma_f32_16x16x32_bf16 v[102:105], v[134:137], v[210:213], v[102:105]
	v_mfma_f32_16x16x32_bf16 v[90:93], v[152:155], v[210:213], v[90:93]
	v_mfma_f32_16x16x32_bf16 v[86:89], v[134:137], v[218:221], v[86:89]
	v_mfma_f32_16x16x32_bf16 v[74:77], v[152:155], v[218:221], v[74:77]
	s_setprio 0
	s_setprio 1
	v_mfma_f32_16x16x32_bf16 v[114:117], v[156:159], v[176:179], v[114:117]
	v_mfma_f32_16x16x32_bf16 v[110:113], v[168:171], v[176:179], v[110:113]
	v_mfma_f32_16x16x32_bf16 v[98:101], v[156:159], v[184:187], v[98:101]
	v_mfma_f32_16x16x32_bf16 v[94:97], v[168:171], v[184:187], v[94:97]
	v_mfma_f32_16x16x32_bf16 v[82:85], v[156:159], v[206:209], v[82:85]
	v_mfma_f32_16x16x32_bf16 v[78:81], v[168:171], v[206:209], v[78:81]
	v_mfma_f32_16x16x32_bf16 v[70:73], v[156:159], v[214:217], v[70:73]
	v_mfma_f32_16x16x32_bf16 v[66:69], v[168:171], v[214:217], v[66:69]
	v_mfma_f32_16x16x32_bf16 v[114:117], v[164:167], v[180:183], v[114:117]
	v_mfma_f32_16x16x32_bf16 v[110:113], v[172:175], v[180:183], v[110:113]
	v_mfma_f32_16x16x32_bf16 v[98:101], v[164:167], v[188:191], v[98:101]
	v_mfma_f32_16x16x32_bf16 v[94:97], v[172:175], v[188:191], v[94:97]
	v_mfma_f32_16x16x32_bf16 v[82:85], v[164:167], v[210:213], v[82:85]
	v_mfma_f32_16x16x32_bf16 v[78:81], v[172:175], v[210:213], v[78:81]
	v_mfma_f32_16x16x32_bf16 v[70:73], v[164:167], v[218:221], v[70:73]
	v_mfma_f32_16x16x32_bf16 v[66:69], v[172:175], v[218:221], v[66:69]
	s_setprio 0
	s_barrier
; #define PG8_STAGE(bufoff, gbase, voff) do { _Pragma("unroll") for (int _i = 0; _i < 2; ++_i) \
;         __builtin_amdgcn_global_load_lds((const unsigned*)((const char*)(gbase) + (voff)[_i]), (PG8_LAS unsigned*)(lds + (bufoff) + ldsw + _i * 8192), 16, 0, 0); } while (0)
; #define PG8_LDA(dst, b, h) do { _Pragma("unroll") for (int m = 0; m < 4; ++m) _Pragma("unroll") for (int k = 0; k < 2; ++k) dst[m][k] = *(const PG8_LAS bf16x8*)(lds + PG8_SA(b, h) + aoff + m * 2048 + k * 1024); } while (0)
; #define PG8_LDB(dst, b, h) do { _Pragma("unroll") for (int n = 0; n < 2; ++n) _Pragma("unroll") for (int k = 0; k < 2; ++k) dst[n][k] = *(const PG8_LAS bf16x8*)(lds + PG8_SB(b, h) + boff + n * 2048 + k * 1024); } while (0)
; template <class Epi, class Sched, bool ALIGN_EPI = false, bool SP2 = false>
; __device__ __forceinline__ void gemm_phase(PG8_LAS unsigned char* lds, const Gemm g, const Sched& S, const Epi& E) {
;     ...
;         for (int t = 0; t < nt; t += 2) {
;             const bool last = (t == nt - 2);
;             const char* a1 = cA + (size_t)(t + 1) * kstepA;
;             const char* a2 = last ? nA : cA + (size_t)(t + 2) * kstepA; const char* b2 = last ? nB : cB + (size_t)(t + 2) * kstep;
;             const char* a3 = a2 + kstepA; const char* b3 = b2 + kstep;
;             if (last && has_next) S.a_ready(nxt);
;             if constexpr (SP2) {
;             PG8_LDB(B0, 0, 0); PG8_LDB(B1, 0, 1); PG8_SCHED; PG8_LDA(At, 0, 0); PG8_STAGE(PG8_SA(1, 1), a1 + hstepA, voffA);
;             PG8_WAIT_V(8); PG8_WAIT_L(0); PG8_BAR; PG8_MMA(0, 0, At, B0); PG8_MMA(0, 1, At, B1); PG8_BAR; PG8_SCHED;
;             PG8_LDA(At, 0, 1); PG8_STAGE(PG8_SB(0, 0), b2, voffB); PG8_STAGE(PG8_SB(0, 1), b2 + hstepB, voffB); PG8_STAGE(PG8_SA(0, 0), a2, voffA);
;             PG8_WAIT_V(8); PG8_WAIT_L(0); PG8_BAR; PG8_MMA(1, 0, At, B0); PG8_MMA(1, 1, At, B1); PG8_BAR; PG8_SCHED;
;             PG8_LDB(B0, 1, 0); PG8_LDB(B1, 1, 1); PG8_SCHED; PG8_LDA(At, 1, 0); PG8_STAGE(PG8_SA(0, 1), a2 + hstepA, voffA);
;             PG8_WAIT_V(8); PG8_WAIT_L(0); PG8_BAR; PG8_MMA(0, 0, At, B0); PG8_MMA(0, 1, At, B1); PG8_BAR; PG8_SCHED;
;             PG8_LDA(At, 1, 1); PG8_STAGE(PG8_SB(1, 0), b3, voffB); PG8_STAGE(PG8_SB(1, 1), b3 + hstepB, voffB); PG8_STAGE(PG8_SA(1, 0), a3, voffA);
;             PG8_WAIT_V(8); PG8_WAIT_L(0); PG8_BAR; PG8_MMA(1, 0, At, B0); PG8_MMA(1, 1, At, B1); PG8_BAR; PG8_SCHED;
	s_add_i32 s28, s47, s30
	v_lshl_add_u64 v[192:193], v[192:193], 0, s[78:79]
	s_mov_b32 m0, s28
	ds_read_b128 v[176:179], v163 offset:49152
	ds_read_b128 v[180:183], v163 offset:50176
	ds_read_b128 v[184:187], v163 offset:51200
	ds_read_b128 v[188:191], v163 offset:52224
	ds_read_b128 v[206:209], v163 offset:53248
	ds_read_b128 v[210:213], v163 offset:54272
	ds_read_b128 v[214:217], v163 offset:55296
	ds_read_b128 v[218:221], v163 offset:56320
	global_load_lds_dwordx4 v[192:193], off
	s_add_i32 m0, s28, 0x2000
	s_add_u32 s26, s26, 0x40080
	v_lshl_add_u64 v[192:193], v[222:223], 0, s[78:79]
	s_addc_u32 s27, s27, 0
	s_add_i32 s28, s48, s30
	global_load_lds_dwordx4 v[192:193], off
	v_lshl_add_u64 v[192:193], s[26:27], 0, v[0:1]
	s_mov_b32 m0, s28
	s_nop 0
	global_load_lds_dwordx4 v[192:193], off
	v_lshl_add_u64 v[192:193], s[26:27], 0, v[142:143]
	s_add_i32 m0, s28, 0x2000
	s_nop 0
	global_load_lds_dwordx4 v[192:193], off
	v_lshl_add_u64 v[192:193], s[24:25], 0, v[146:147]
	s_mov_b32 m0, s37
	s_nop 0
	global_load_lds_dwordx4 v[192:193], off
	v_lshl_add_u64 v[192:193], s[24:25], 0, v[144:145]
	s_mov_b32 m0, s38
	s_nop 0
	global_load_lds_dwordx4 v[192:193], off
	s_waitcnt vmcnt(8)
	s_waitcnt lgkmcnt(0)
	s_barrier
	s_setprio 1
	s_waitcnt lgkmcnt(0)
	v_mfma_f32_16x16x32_bf16 v[62:65], v[130:133], v[176:179], v[62:65]
	v_mfma_f32_16x16x32_bf16 v[58:61], v[138:141], v[176:179], v[58:61]
	v_mfma_f32_16x16x32_bf16 v[54:57], v[130:133], v[184:187], v[54:57]
	v_mfma_f32_16x16x32_bf16 v[42:45], v[138:141], v[184:187], v[42:45]
	v_mfma_f32_16x16x32_bf16 v[38:41], v[130:133], v[206:209], v[38:41]
	v_mfma_f32_16x16x32_bf16 v[26:29], v[138:141], v[206:209], v[26:29]
	v_mfma_f32_16x16x32_bf16 v[22:25], v[130:133], v[214:217], v[22:25]
	v_mfma_f32_16x16x32_bf16 v[10:13], v[138:141], v[214:217], v[10:13]
	v_mfma_f32_16x16x32_bf16 v[62:65], v[134:137], v[180:183], v[62:65]
	v_mfma_f32_16x16x32_bf16 v[58:61], v[152:155], v[180:183], v[58:61]
	v_mfma_f32_16x16x32_bf16 v[54:57], v[134:137], v[188:191], v[54:57]
	v_mfma_f32_16x16x32_bf16 v[42:45], v[152:155], v[188:191], v[42:45]
	v_mfma_f32_16x16x32_bf16 v[38:41], v[134:137], v[210:213], v[38:41]
	v_mfma_f32_16x16x32_bf16 v[26:29], v[152:155], v[210:213], v[26:29]
	v_mfma_f32_16x16x32_bf16 v[22:25], v[134:137], v[218:221], v[22:25]
	v_mfma_f32_16x16x32_bf16 v[10:13], v[152:155], v[218:221], v[10:13]
	s_setprio 0
	s_setprio 1
	v_mfma_f32_16x16x32_bf16 v[50:53], v[156:159], v[176:179], v[50:53]
	v_mfma_f32_16x16x32_bf16 v[46:49], v[168:171], v[176:179], v[46:49]
	v_mfma_f32_16x16x32_bf16 v[34:37], v[156:159], v[184:187], v[34:37]
	v_mfma_f32_16x16x32_bf16 v[30:33], v[168:171], v[184:187], v[30:33]
	v_mfma_f32_16x16x32_bf16 v[18:21], v[156:159], v[206:209], v[18:21]
	v_mfma_f32_16x16x32_bf16 v[14:17], v[168:171], v[206:209], v[14:17]
	v_mfma_f32_16x16x32_bf16 v[6:9], v[156:159], v[214:217], v[6:9]
	v_mfma_f32_16x16x32_bf16 v[2:5], v[168:171], v[214:217], v[2:5]
	v_mfma_f32_16x16x32_bf16 v[50:53], v[164:167], v[180:183], v[50:53]
	v_mfma_f32_16x16x32_bf16 v[46:49], v[172:175], v[180:183], v[46:49]
	v_mfma_f32_16x16x32_bf16 v[34:37], v[164:167], v[188:191], v[34:37]
	v_mfma_f32_16x16x32_bf16 v[30:33], v[172:175], v[188:191], v[30:33]
	v_mfma_f32_16x16x32_bf16 v[18:21], v[164:167], v[210:213], v[18:21]
	v_mfma_f32_16x16x32_bf16 v[14:17], v[172:175], v[210:213], v[14:17]
	v_mfma_f32_16x16x32_bf16 v[6:9], v[164:167], v[218:221], v[6:9]
	v_mfma_f32_16x16x32_bf16 v[2:5], v[172:175], v[218:221], v[2:5]
	s_setprio 0
	s_add_i32 s46, s46, 2
	s_add_u32 s22, s22, 0x400000
	s_addc_u32 s23, s23, 0
	s_add_u32 s44, s44, 0x100
	s_addc_u32 s45, s45, 0
	s_add_u32 s24, s22, 0x1fc000
	s_addc_u32 s25, s23, 0
	s_cmp_eq_u32 s46, 12
	s_cselect_b32 s28, s42, s24
	s_cselect_b32 s29, s17, s25
	s_cselect_b32 s26, s43, s44
	s_cselect_b32 s27, s15, s45
	s_add_u32 s24, s28, 0x200000
	s_addc_u32 s25, s29, 0
	s_add_i32 s47, 0, 0x10000
	s_add_i32 s50, 0, 0x14000
	s_barrier
.LBB0_87:
	v_add_u32_e32 v152, s47, v161
	v_add_u32_e32 v172, s50, v161
	ds_read_b128 v[130:133], v152
	ds_read_b128 v[134:137], v152 offset:1024
	ds_read_b128 v[138:141], v152 offset:2048
	ds_read_b128 v[152:155], v152 offset:3072
	ds_read_b128 v[156:159], v172
	ds_read_b128 v[164:167], v172 offset:1024
	ds_read_b128 v[168:171], v172 offset:2048
	ds_read_b128 v[172:175], v172 offset:3072
	v_lshl_add_u64 v[192:193], s[22:23], 0, v[148:149]
	s_add_i32 m0, s31, 0xc000
	ds_read_b128 v[176:179], v163
	ds_read_b128 v[180:183], v163 offset:1024
	ds_read_b128 v[184:187], v163 offset:2048
	ds_read_b128 v[188:191], v163 offset:3072
	ds_read_b128 v[206:209], v163 offset:4096
	ds_read_b128 v[210:213], v163 offset:5120
	ds_read_b128 v[214:217], v163 offset:6144
	ds_read_b128 v[218:221], v163 offset:7168
	global_load_lds_dwordx4 v[192:193], off
	v_lshl_add_u64 v[192:193], s[22:23], 0, v[150:151]
	s_add_i32 m0, s31, 0xe000
	s_nop 0
	global_load_lds_dwordx4 v[192:193], off
	s_waitcnt vmcnt(8)
	s_waitcnt lgkmcnt(0)
	s_barrier
; #define PG8_STAGE(bufoff, gbase, voff) do { _Pragma("unroll") for (int _i = 0; _i < 2; ++_i) \
;         __builtin_amdgcn_global_load_lds((const unsigned*)((const char*)(gbase) + (voff)[_i]), (PG8_LAS unsigned*)(lds + (bufoff) + ldsw + _i * 8192), 16, 0, 0); } while (0)
; #define PG8_LDA(dst, b, h) do { _Pragma("unroll") for (int m = 0; m < 4; ++m) _Pragma("unroll") for (int k = 0; k < 2; ++k) dst[m][k] = *(const PG8_LAS bf16x8*)(lds + PG8_SA(b, h) + aoff + m * 2048 + k * 1024); } while (0)
; #define PG8_LDB(dst, b, h) do { _Pragma("unroll") for (int n = 0; n < 2; ++n) _Pragma("unroll") for (int k = 0; k < 2; ++k) dst[n][k] = *(const PG8_LAS bf16x8*)(lds + PG8_SB(b, h) + boff + n * 2048 + k * 1024); } while (0)
; #define PG8_MMA(ai, bj, At, Bt) do { __builtin_amdgcn_s_setprio(1); _Pragma("unroll") for (int m = 0; m < 4; ++m) _Pragma("unroll") for (int n = 0; n < 2; ++n) _Pragma("unroll") for (int k = 0; k < 2; ++k) \
;         acc[ai][bj][m][n] = __builtin_amdgcn_mfma_f32_16x16x32_bf16(Bt[n][k], At[m][k], acc[ai][bj][m][n], 0, 0, 0); __builtin_amdgcn_s_setprio(0); } while (0)
; #define PG8_WAIT_V(n) asm volatile("s_waitcnt vmcnt(" #n ")" ::: "memory")
; #define PG8_WAIT_L(n) asm volatile("s_waitcnt lgkmcnt(" #n ")" ::: "memory")
; #define PG8_BAR __builtin_amdgcn_s_barrier()
; #define PG8_SCHED __builtin_amdgcn_sched_barrier(0)
; template <class Epi, class Sched, bool ALIGN_EPI = false, bool SP2 = false>
; __device__ __forceinline__ void gemm_phase(PG8_LAS unsigned char* lds, const Gemm g, const Sched& S, const Epi& E) {
;     ...
;             PG8_LDB(B0, 0, 0); PG8_LDB(B1, 0, 1); PG8_SCHED; PG8_LDA(At, 0, 0); PG8_STAGE(PG8_SA(1, 1), a1 + hstepA, voffA);
;             PG8_WAIT_V(8); PG8_WAIT_L(0); PG8_BAR; PG8_MMA(0, 0, At, B0); PG8_MMA(0, 1, At, B1); PG8_BAR; PG8_SCHED;
;             PG8_LDA(At, 0, 1); PG8_STAGE(PG8_SB(0, 0), b2, voffB); PG8_STAGE(PG8_SB(0, 1), b2 + hstepB, voffB); PG8_STAGE(PG8_SA(0, 0), a2, voffA);
;             PG8_WAIT_V(8); PG8_WAIT_L(0); PG8_BAR; PG8_MMA(1, 0, At, B0); PG8_MMA(1, 1, At, B1); PG8_BAR; PG8_SCHED;
	s_setprio 1
	s_waitcnt lgkmcnt(0)
	v_mfma_f32_16x16x32_bf16 v[126:129], v[130:133], v[176:179], v[126:129]
	v_mfma_f32_16x16x32_bf16 v[122:125], v[138:141], v[176:179], v[122:125]
	v_mfma_f32_16x16x32_bf16 v[118:121], v[130:133], v[184:187], v[118:121]
	v_mfma_f32_16x16x32_bf16 v[106:109], v[138:141], v[184:187], v[106:109]
	v_mfma_f32_16x16x32_bf16 v[102:105], v[130:133], v[206:209], v[102:105]
	v_mfma_f32_16x16x32_bf16 v[90:93], v[138:141], v[206:209], v[90:93]
	v_mfma_f32_16x16x32_bf16 v[86:89], v[130:133], v[214:217], v[86:89]
	v_mfma_f32_16x16x32_bf16 v[74:77], v[138:141], v[214:217], v[74:77]
	v_mfma_f32_16x16x32_bf16 v[126:129], v[134:137], v[180:183], v[126:129]
	v_mfma_f32_16x16x32_bf16 v[122:125], v[152:155], v[180:183], v[122:125]
	v_mfma_f32_16x16x32_bf16 v[118:121], v[134:137], v[188:191], v[118:121]
	v_mfma_f32_16x16x32_bf16 v[106:109], v[152:155], v[188:191], v[106:109]
	v_mfma_f32_16x16x32_bf16 v[102:105], v[134:137], v[210:213], v[102:105]
	v_mfma_f32_16x16x32_bf16 v[90:93], v[152:155], v[210:213], v[90:93]
	v_mfma_f32_16x16x32_bf16 v[86:89], v[134:137], v[218:221], v[86:89]
	v_mfma_f32_16x16x32_bf16 v[74:77], v[152:155], v[218:221], v[74:77]
	s_setprio 0
	s_setprio 1
	v_mfma_f32_16x16x32_bf16 v[114:117], v[156:159], v[176:179], v[114:117]
	v_mfma_f32_16x16x32_bf16 v[110:113], v[168:171], v[176:179], v[110:113]
	v_mfma_f32_16x16x32_bf16 v[98:101], v[156:159], v[184:187], v[98:101]
	v_mfma_f32_16x16x32_bf16 v[94:97], v[168:171], v[184:187], v[94:97]
	v_mfma_f32_16x16x32_bf16 v[82:85], v[156:159], v[206:209], v[82:85]
	v_mfma_f32_16x16x32_bf16 v[78:81], v[168:171], v[206:209], v[78:81]
	v_mfma_f32_16x16x32_bf16 v[70:73], v[156:159], v[214:217], v[70:73]
	v_mfma_f32_16x16x32_bf16 v[66:69], v[168:171], v[214:217], v[66:69]
	v_mfma_f32_16x16x32_bf16 v[114:117], v[164:167], v[180:183], v[114:117]
	v_mfma_f32_16x16x32_bf16 v[110:113], v[172:175], v[180:183], v[110:113]
	v_mfma_f32_16x16x32_bf16 v[98:101], v[164:167], v[188:191], v[98:101]
	v_mfma_f32_16x16x32_bf16 v[94:97], v[172:175], v[188:191], v[94:97]
	v_mfma_f32_16x16x32_bf16 v[82:85], v[164:167], v[210:213], v[82:85]
	v_mfma_f32_16x16x32_bf16 v[78:81], v[172:175], v[210:213], v[78:81]
	v_mfma_f32_16x16x32_bf16 v[70:73], v[164:167], v[218:221], v[70:73]
	v_mfma_f32_16x16x32_bf16 v[66:69], v[172:175], v[218:221], v[66:69]
	s_setprio 0
	s_barrier
	s_add_i32 s47, s47, s30
	v_lshl_add_u64 v[192:193], s[26:27], 0, v[0:1]
	s_mov_b32 m0, s47
	ds_read_b128 v[176:179], v163 offset:16384
	ds_read_b128 v[180:183], v163 offset:17408
	ds_read_b128 v[184:187], v163 offset:18432
	ds_read_b128 v[188:191], v163 offset:19456
	ds_read_b128 v[206:209], v163 offset:20480
	ds_read_b128 v[210:213], v163 offset:21504
	ds_read_b128 v[214:217], v163 offset:22528
	ds_read_b128 v[218:221], v163 offset:23552
	global_load_lds_dwordx4 v[192:193], off
	s_add_i32 m0, s47, 0x2000
	s_add_u32 s48, s26, 0x40000
	v_lshl_add_u64 v[222:223], s[26:27], 0, v[142:143]
	s_addc_u32 s49, s27, 0
	s_add_i32 s47, s50, s30
	global_load_lds_dwordx4 v[222:223], off
	v_lshl_add_u64 v[224:225], s[48:49], 0, v[0:1]
	s_mov_b32 m0, s47
	s_nop 0
	global_load_lds_dwordx4 v[224:225], off
	v_lshl_add_u64 v[224:225], s[48:49], 0, v[142:143]
	s_add_i32 m0, s47, 0x2000
	s_nop 0
	global_load_lds_dwordx4 v[224:225], off
	v_lshl_add_u64 v[224:225], s[28:29], 0, v[146:147]
	s_mov_b32 m0, s31
	s_nop 0
	global_load_lds_dwordx4 v[224:225], off
	v_lshl_add_u64 v[224:225], s[28:29], 0, v[144:145]
	s_mov_b32 m0, s34
	s_nop 0
	global_load_lds_dwordx4 v[224:225], off
	s_waitcnt vmcnt(8)
	s_waitcnt lgkmcnt(0)
	s_barrier
	s_setprio 1
	s_waitcnt lgkmcnt(0)
	v_mfma_f32_16x16x32_bf16 v[62:65], v[130:133], v[176:179], v[62:65]
	v_mfma_f32_16x16x32_bf16 v[58:61], v[138:141], v[176:179], v[58:61]
	v_mfma_f32_16x16x32_bf16 v[54:57], v[130:133], v[184:187], v[54:57]
	v_mfma_f32_16x16x32_bf16 v[42:45], v[138:141], v[184:187], v[42:45]
	v_mfma_f32_16x16x32_bf16 v[38:41], v[130:133], v[206:209], v[38:41]
	v_mfma_f32_16x16x32_bf16 v[26:29], v[138:141], v[206:209], v[26:29]
	v_mfma_f32_16x16x32_bf16 v[22:25], v[130:133], v[214:217], v[22:25]
	v_mfma_f32_16x16x32_bf16 v[10:13], v[138:141], v[214:217], v[10:13]
	v_mfma_f32_16x16x32_bf16 v[62:65], v[134:137], v[180:183], v[62:65]
	v_mfma_f32_16x16x32_bf16 v[58:61], v[152:155], v[180:183], v[58:61]
	v_mfma_f32_16x16x32_bf16 v[54:57], v[134:137], v[188:191], v[54:57]
	v_mfma_f32_16x16x32_bf16 v[42:45], v[152:155], v[188:191], v[42:45]
	v_mfma_f32_16x16x32_bf16 v[38:41], v[134:137], v[210:213], v[38:41]
	v_mfma_f32_16x16x32_bf16 v[26:29], v[152:155], v[210:213], v[26:29]
	v_mfma_f32_16x16x32_bf16 v[22:25], v[134:137], v[218:221], v[22:25]
	v_mfma_f32_16x16x32_bf16 v[10:13], v[152:155], v[218:221], v[10:13]
	s_setprio 0
	s_setprio 1
	v_mfma_f32_16x16x32_bf16 v[50:53], v[156:159], v[176:179], v[50:53]
	v_mfma_f32_16x16x32_bf16 v[46:49], v[168:171], v[176:179], v[46:49]
	v_mfma_f32_16x16x32_bf16 v[34:37], v[156:159], v[184:187], v[34:37]
	v_mfma_f32_16x16x32_bf16 v[30:33], v[168:171], v[184:187], v[30:33]
	v_mfma_f32_16x16x32_bf16 v[18:21], v[156:159], v[206:209], v[18:21]
	v_mfma_f32_16x16x32_bf16 v[14:17], v[168:171], v[206:209], v[14:17]
	v_mfma_f32_16x16x32_bf16 v[6:9], v[156:159], v[214:217], v[6:9]
	v_mfma_f32_16x16x32_bf16 v[2:5], v[168:171], v[214:217], v[2:5]
	v_mfma_f32_16x16x32_bf16 v[50:53], v[164:167], v[180:183], v[50:53]
	v_mfma_f32_16x16x32_bf16 v[46:49], v[172:175], v[180:183], v[46:49]
	v_mfma_f32_16x16x32_bf16 v[34:37], v[164:167], v[188:191], v[34:37]
	v_mfma_f32_16x16x32_bf16 v[30:33], v[172:175], v[188:191], v[30:33]
	v_mfma_f32_16x16x32_bf16 v[18:21], v[164:167], v[210:213], v[18:21]
	v_mfma_f32_16x16x32_bf16 v[14:17], v[172:175], v[210:213], v[14:17]
	v_mfma_f32_16x16x32_bf16 v[6:9], v[164:167], v[218:221], v[6:9]
	v_mfma_f32_16x16x32_bf16 v[2:5], v[172:175], v[218:221], v[2:5]
	s_setprio 0
	s_barrier
; #define PG8_STAGE(bufoff, gbase, voff) do { _Pragma("unroll") for (int _i = 0; _i < 2; ++_i) \
;         __builtin_amdgcn_global_load_lds((const unsigned*)((const char*)(gbase) + (voff)[_i]), (PG8_LAS unsigned*)(lds + (bufoff) + ldsw + _i * 8192), 16, 0, 0); } while (0)
; #define PG8_LDA(dst, b, h) do { _Pragma("unroll") for (int m = 0; m < 4; ++m) _Pragma("unroll") for (int k = 0; k < 2; ++k) dst[m][k] = *(const PG8_LAS bf16x8*)(lds + PG8_SA(b, h) + aoff + m * 2048 + k * 1024); } while (0)
; #define PG8_LDB(dst, b, h) do { _Pragma("unroll") for (int n = 0; n < 2; ++n) _Pragma("unroll") for (int k = 0; k < 2; ++k) dst[n][k] = *(const PG8_LAS bf16x8*)(lds + PG8_SB(b, h) + boff + n * 2048 + k * 1024); } while (0)
; #define PG8_MMA(ai, bj, At, Bt) do { __builtin_amdgcn_s_setprio(1); _Pragma("unroll") for (int m = 0; m < 4; ++m) _Pragma("unroll") for (int n = 0; n < 2; ++n) _Pragma("unroll") for (int k = 0; k < 2; ++k) \
;         acc[ai][bj][m][n] = __builtin_amdgcn_mfma_f32_16x16x32_bf16(Bt[n][k], At[m][k], acc[ai][bj][m][n], 0, 0, 0); __builtin_amdgcn_s_setprio(0); } while (0)
; #define PG8_WAIT_V(n) asm volatile("s_waitcnt vmcnt(" #n ")" ::: "memory")
; #define PG8_WAIT_L(n) asm volatile("s_waitcnt lgkmcnt(" #n ")" ::: "memory")
; #define PG8_BAR __builtin_amdgcn_s_barrier()
; #define PG8_SCHED __builtin_amdgcn_sched_barrier(0)
; template <class Epi, class Sched, bool ALIGN_EPI = false, bool SP2 = false>
; __device__ __forceinline__ void gemm_phase(PG8_LAS unsigned char* lds, const Gemm g, const Sched& S, const Epi& E) {
;     ...
;             PG8_LDB(B0, 1, 0); PG8_LDB(B1, 1, 1); PG8_SCHED; PG8_LDA(At, 1, 0); PG8_STAGE(PG8_SA(0, 1), a2 + hstepA, voffA);
;             PG8_WAIT_V(8); PG8_WAIT_L(0); PG8_BAR; PG8_MMA(0, 0, At, B0); PG8_MMA(0, 1, At, B1); PG8_BAR; PG8_SCHED;
	s_add_i32 s47, 0, 0x18000
	s_add_i32 s48, 0, 0x1c000
	v_add_u32_e32 v152, s47, v161
	v_add_u32_e32 v172, s48, v161
	ds_read_b128 v[130:133], v152
	ds_read_b128 v[134:137], v152 offset:1024
	ds_read_b128 v[138:141], v152 offset:2048
	ds_read_b128 v[152:155], v152 offset:3072
	ds_read_b128 v[156:159], v172
	ds_read_b128 v[164:167], v172 offset:1024
	ds_read_b128 v[168:171], v172 offset:2048
	ds_read_b128 v[172:175], v172 offset:3072
	s_add_u32 s28, s28, 0x4000
	s_addc_u32 s29, s29, 0
	s_mov_b32 m0, s35
	v_lshl_add_u64 v[224:225], s[28:29], 0, v[146:147]
	ds_read_b128 v[176:179], v163 offset:32768
	ds_read_b128 v[180:183], v163 offset:33792
	ds_read_b128 v[184:187], v163 offset:34816
	ds_read_b128 v[188:191], v163 offset:35840
	ds_read_b128 v[206:209], v163 offset:36864
	ds_read_b128 v[210:213], v163 offset:37888
	ds_read_b128 v[214:217], v163 offset:38912
	ds_read_b128 v[218:221], v163 offset:39936
	global_load_lds_dwordx4 v[224:225], off
	v_lshl_add_u64 v[224:225], s[28:29], 0, v[144:145]
	s_mov_b32 m0, s36
	s_nop 0
	global_load_lds_dwordx4 v[224:225], off
	s_waitcnt vmcnt(8)
	s_waitcnt lgkmcnt(0)
	s_barrier
	s_setprio 1
	s_waitcnt lgkmcnt(0)
	v_mfma_f32_16x16x32_bf16 v[126:129], v[130:133], v[176:179], v[126:129]
	v_mfma_f32_16x16x32_bf16 v[122:125], v[138:141], v[176:179], v[122:125]
	v_mfma_f32_16x16x32_bf16 v[118:121], v[130:133], v[184:187], v[118:121]
	v_mfma_f32_16x16x32_bf16 v[106:109], v[138:141], v[184:187], v[106:109]
	v_mfma_f32_16x16x32_bf16 v[102:105], v[130:133], v[206:209], v[102:105]
	v_mfma_f32_16x16x32_bf16 v[90:93], v[138:141], v[206:209], v[90:93]
	v_mfma_f32_16x16x32_bf16 v[86:89], v[130:133], v[214:217], v[86:89]
	v_mfma_f32_16x16x32_bf16 v[74:77], v[138:141], v[214:217], v[74:77]
	v_mfma_f32_16x16x32_bf16 v[126:129], v[134:137], v[180:183], v[126:129]
	v_mfma_f32_16x16x32_bf16 v[122:125], v[152:155], v[180:183], v[122:125]
	v_mfma_f32_16x16x32_bf16 v[118:121], v[134:137], v[188:191], v[118:121]
	v_mfma_f32_16x16x32_bf16 v[106:109], v[152:155], v[188:191], v[106:109]
	v_mfma_f32_16x16x32_bf16 v[102:105], v[134:137], v[210:213], v[102:105]
	v_mfma_f32_16x16x32_bf16 v[90:93], v[152:155], v[210:213], v[90:93]
	v_mfma_f32_16x16x32_bf16 v[86:89], v[134:137], v[218:221], v[86:89]
	v_mfma_f32_16x16x32_bf16 v[74:77], v[152:155], v[218:221], v[74:77]
	s_setprio 0
	s_setprio 1
	v_mfma_f32_16x16x32_bf16 v[114:117], v[156:159], v[176:179], v[114:117]
	v_mfma_f32_16x16x32_bf16 v[110:113], v[168:171], v[176:179], v[110:113]
	v_mfma_f32_16x16x32_bf16 v[98:101], v[156:159], v[184:187], v[98:101]
	v_mfma_f32_16x16x32_bf16 v[94:97], v[168:171], v[184:187], v[94:97]
	v_mfma_f32_16x16x32_bf16 v[82:85], v[156:159], v[206:209], v[82:85]
	v_mfma_f32_16x16x32_bf16 v[78:81], v[168:171], v[206:209], v[78:81]
	v_mfma_f32_16x16x32_bf16 v[70:73], v[156:159], v[214:217], v[70:73]
	v_mfma_f32_16x16x32_bf16 v[66:69], v[168:171], v[214:217], v[66:69]
	v_mfma_f32_16x16x32_bf16 v[114:117], v[164:167], v[180:183], v[114:117]
	v_mfma_f32_16x16x32_bf16 v[110:113], v[172:175], v[180:183], v[110:113]
	v_mfma_f32_16x16x32_bf16 v[98:101], v[164:167], v[188:191], v[98:101]
	v_mfma_f32_16x16x32_bf16 v[94:97], v[172:175], v[188:191], v[94:97]
	v_mfma_f32_16x16x32_bf16 v[82:85], v[164:167], v[210:213], v[82:85]
	v_mfma_f32_16x16x32_bf16 v[78:81], v[172:175], v[210:213], v[78:81]
	v_mfma_f32_16x16x32_bf16 v[70:73], v[164:167], v[218:221], v[70:73]
	v_mfma_f32_16x16x32_bf16 v[66:69], v[172:175], v[218:221], v[66:69]
	s_setprio 0
	s_barrier
; #define PG8_STAGE(bufoff, gbase, voff) do { _Pragma("unroll") for (int _i = 0; _i < 2; ++_i) \
;         __builtin_amdgcn_global_load_lds((const unsigned*)((const char*)(gbase) + (voff)[_i]), (PG8_LAS unsigned*)(lds + (bufoff) + ldsw + _i * 8192), 16, 0, 0); } while (0)
; #define PG8_LDA(dst, b, h) do { _Pragma("unroll") for (int m = 0; m < 4; ++m) _Pragma("unroll") for (int k = 0; k < 2; ++k) dst[m][k] = *(const PG8_LAS bf16x8*)(lds + PG8_SA(b, h) + aoff + m * 2048 + k * 1024); } while (0)
; #define PG8_LDB(dst, b, h) do { _Pragma("unroll") for (int n = 0; n < 2; ++n) _Pragma("unroll") for (int k = 0; k < 2; ++k) dst[n][k] = *(const PG8_LAS bf16x8*)(lds + PG8_SB(b, h) + boff + n * 2048 + k * 1024); } while (0)
; template <class Epi, class Sched, bool ALIGN_EPI = false, bool SP2 = false>
; __device__ __forceinline__ void gemm_phase(PG8_LAS unsigned char* lds, const Gemm g, const Sched& S, const Epi& E) {
;     ...
;         for (int t = 0; t < nt; t += 2) {
;             const bool last = (t == nt - 2);
;             const char* a1 = cA + (size_t)(t + 1) * kstepA;
;             const char* a2 = last ? nA : cA + (size_t)(t + 2) * kstepA; const char* b2 = last ? nB : cB + (size_t)(t + 2) * kstep;
;             const char* a3 = a2 + kstepA; const char* b3 = b2 + kstep;
;             if (last && has_next) S.a_ready(nxt);
;             if constexpr (SP2) {
;             PG8_LDB(B0, 0, 0); PG8_LDB(B1, 0, 1); PG8_SCHED; PG8_LDA(At, 0, 0); PG8_STAGE(PG8_SA(1, 1), a1 + hstepA, voffA);
;             PG8_WAIT_V(8); PG8_WAIT_L(0); PG8_BAR; PG8_MMA(0, 0, At, B0); PG8_MMA(0, 1, At, B1); PG8_BAR; PG8_SCHED;
;             PG8_LDA(At, 0, 1); PG8_STAGE(PG8_SB(0, 0), b2, voffB); PG8_STAGE(PG8_SB(0, 1), b2 + hstepB, voffB); PG8_STAGE(PG8_SA(0, 0), a2, voffA);
;             PG8_WAIT_V(8); PG8_WAIT_L(0); PG8_BAR; PG8_MMA(1, 0, At, B0); PG8_MMA(1, 1, At, B1); PG8_BAR; PG8_SCHED;
;             PG8_LDB(B0, 1, 0); PG8_LDB(B1, 1, 1); PG8_SCHED; PG8_LDA(At, 1, 0); PG8_STAGE(PG8_SA(0, 1), a2 + hstepA, voffA);
;             PG8_WAIT_V(8); PG8_WAIT_L(0); PG8_BAR; PG8_MMA(0, 0, At, B0); PG8_MMA(0, 1, At, B1); PG8_BAR; PG8_SCHED;
;             PG8_LDA(At, 1, 1); PG8_STAGE(PG8_SB(1, 0), b3, voffB); PG8_STAGE(PG8_SB(1, 1), b3 + hstepB, voffB); PG8_STAGE(PG8_SA(1, 0), a3, voffA);
;             PG8_WAIT_V(8); PG8_WAIT_L(0); PG8_BAR; PG8_MMA(1, 0, At, B0); PG8_MMA(1, 1, At, B1); PG8_BAR; PG8_SCHED;
	s_add_i32 s28, s47, s30
	v_lshl_add_u64 v[192:193], v[192:193], 0, s[78:79]
	s_mov_b32 m0, s28
	ds_read_b128 v[176:179], v163 offset:49152
	ds_read_b128 v[180:183], v163 offset:50176
	ds_read_b128 v[184:187], v163 offset:51200
	ds_read_b128 v[188:191], v163 offset:52224
	ds_read_b128 v[206:209], v163 offset:53248
	ds_read_b128 v[210:213], v163 offset:54272
	ds_read_b128 v[214:217], v163 offset:55296
	ds_read_b128 v[218:221], v163 offset:56320
	global_load_lds_dwordx4 v[192:193], off
	s_add_i32 m0, s28, 0x2000
	s_add_u32 s26, s26, 0x40080
	v_lshl_add_u64 v[192:193], v[222:223], 0, s[78:79]
	s_addc_u32 s27, s27, 0
	s_add_i32 s28, s48, s30
	global_load_lds_dwordx4 v[192:193], off
	v_lshl_add_u64 v[192:193], s[26:27], 0, v[0:1]
	s_mov_b32 m0, s28
	s_nop 0
	global_load_lds_dwordx4 v[192:193], off
	v_lshl_add_u64 v[192:193], s[26:27], 0, v[142:143]
	s_add_i32 m0, s28, 0x2000
	s_nop 0
	global_load_lds_dwordx4 v[192:193], off
	v_lshl_add_u64 v[192:193], s[24:25], 0, v[146:147]
	s_mov_b32 m0, s37
	s_nop 0
	global_load_lds_dwordx4 v[192:193], off
	v_lshl_add_u64 v[192:193], s[24:25], 0, v[144:145]
	s_mov_b32 m0, s38
	s_nop 0
	global_load_lds_dwordx4 v[192:193], off
	s_waitcnt vmcnt(8)
	s_waitcnt lgkmcnt(0)
	s_barrier
	s_setprio 1
	s_waitcnt lgkmcnt(0)
	v_mfma_f32_16x16x32_bf16 v[62:65], v[130:133], v[176:179], v[62:65]
	v_mfma_f32_16x16x32_bf16 v[58:61], v[138:141], v[176:179], v[58:61]
	v_mfma_f32_16x16x32_bf16 v[54:57], v[130:133], v[184:187], v[54:57]
	v_mfma_f32_16x16x32_bf16 v[42:45], v[138:141], v[184:187], v[42:45]
	v_mfma_f32_16x16x32_bf16 v[38:41], v[130:133], v[206:209], v[38:41]
	v_mfma_f32_16x16x32_bf16 v[26:29], v[138:141], v[206:209], v[26:29]
	v_mfma_f32_16x16x32_bf16 v[22:25], v[130:133], v[214:217], v[22:25]
	v_mfma_f32_16x16x32_bf16 v[10:13], v[138:141], v[214:217], v[10:13]
	v_mfma_f32_16x16x32_bf16 v[62:65], v[134:137], v[180:183], v[62:65]
	v_mfma_f32_16x16x32_bf16 v[58:61], v[152:155], v[180:183], v[58:61]
	v_mfma_f32_16x16x32_bf16 v[54:57], v[134:137], v[188:191], v[54:57]
	v_mfma_f32_16x16x32_bf16 v[42:45], v[152:155], v[188:191], v[42:45]
	v_mfma_f32_16x16x32_bf16 v[38:41], v[134:137], v[210:213], v[38:41]
	v_mfma_f32_16x16x32_bf16 v[26:29], v[152:155], v[210:213], v[26:29]
	v_mfma_f32_16x16x32_bf16 v[22:25], v[134:137], v[218:221], v[22:25]
	v_mfma_f32_16x16x32_bf16 v[10:13], v[152:155], v[218:221], v[10:13]
	s_setprio 0
	s_setprio 1
	v_mfma_f32_16x16x32_bf16 v[50:53], v[156:159], v[176:179], v[50:53]
	v_mfma_f32_16x16x32_bf16 v[46:49], v[168:171], v[176:179], v[46:49]
	v_mfma_f32_16x16x32_bf16 v[34:37], v[156:159], v[184:187], v[34:37]
	v_mfma_f32_16x16x32_bf16 v[30:33], v[168:171], v[184:187], v[30:33]
	v_mfma_f32_16x16x32_bf16 v[18:21], v[156:159], v[206:209], v[18:21]
	v_mfma_f32_16x16x32_bf16 v[14:17], v[168:171], v[206:209], v[14:17]
	v_mfma_f32_16x16x32_bf16 v[6:9], v[156:159], v[214:217], v[6:9]
	v_mfma_f32_16x16x32_bf16 v[2:5], v[168:171], v[214:217], v[2:5]
	v_mfma_f32_16x16x32_bf16 v[50:53], v[164:167], v[180:183], v[50:53]
	v_mfma_f32_16x16x32_bf16 v[46:49], v[172:175], v[180:183], v[46:49]
	v_mfma_f32_16x16x32_bf16 v[34:37], v[164:167], v[188:191], v[34:37]
	v_mfma_f32_16x16x32_bf16 v[30:33], v[172:175], v[188:191], v[30:33]
	v_mfma_f32_16x16x32_bf16 v[18:21], v[164:167], v[210:213], v[18:21]
	v_mfma_f32_16x16x32_bf16 v[14:17], v[172:175], v[210:213], v[14:17]
	v_mfma_f32_16x16x32_bf16 v[6:9], v[164:167], v[218:221], v[6:9]
	v_mfma_f32_16x16x32_bf16 v[2:5], v[172:175], v[218:221], v[2:5]
	s_setprio 0
	s_add_i32 s46, s46, 2
	s_add_u32 s22, s22, 0x400000
	s_addc_u32 s23, s23, 0
	s_add_u32 s44, s44, 0x100
	s_addc_u32 s45, s45, 0
	s_add_u32 s24, s22, 0x1fc000
	s_addc_u32 s25, s23, 0
	s_cmp_eq_u32 s46, 12
	s_cselect_b32 s28, s42, s24
	s_cselect_b32 s29, s17, s25
	s_cselect_b32 s26, s43, s44
	s_cselect_b32 s27, s15, s45
	s_add_u32 s24, s28, 0x200000
	s_addc_u32 s25, s29, 0
	s_add_i32 s47, 0, 0x10000
	s_add_i32 s50, 0, 0x14000
	s_cmp_gt_u32 s46, 13
	s_barrier
	s_cbranch_scc0 .LBB0_87
	s_and_b64 vcc, exec, s[12:13]
	s_cbranch_vccz .LBB0_90
	s_barrier

; #define PG8_STAGE(bufoff, gbase, voff) do { _Pragma("unroll") for (int _i = 0; _i < 2; ++_i) \
;         __builtin_amdgcn_global_load_lds((const unsigned*)((const char*)(gbase) + (voff)[_i]), (PG8_LAS unsigned*)(lds + (bufoff) + ldsw + _i * 8192), 16, 0, 0); } while (0)
; #define PG8_LDA(dst, b, h) do { _Pragma("unroll") for (int m = 0; m < 4; ++m) _Pragma("unroll") for (int k = 0; k < 2; ++k) dst[m][k] = *(const PG8_LAS bf16x8*)(lds + PG8_SA(b, h) + aoff + m * 2048 + k * 1024); } while (0)
; #define PG8_LDB(dst, b, h) do { _Pragma("unroll") for (int n = 0; n < 2; ++n) _Pragma("unroll") for (int k = 0; k < 2; ++k) dst[n][k] = *(const PG8_LAS bf16x8*)(lds + PG8_SB(b, h) + boff + n * 2048 + k * 1024); } while (0)
; #define PG8_WAIT_V(n) asm volatile("s_waitcnt vmcnt(" #n ")" ::: "memory")
; #define PG8_WAIT_L(n) asm volatile("s_waitcnt lgkmcnt(" #n ")" ::: "memory")
; #define PG8_BAR __builtin_amdgcn_s_barrier()
; #define PG8_SCHED __builtin_amdgcn_sched_barrier(0)
; template <class Epi, class Sched, bool ALIGN_EPI = false, bool SP2 = false>
; __device__ __forceinline__ void gemm_phase(PG8_LAS unsigned char* lds, const Gemm g, const Sched& S, const Epi& E) {
;     ...
;     for (;;) {
;         const bool has_next = S.next(ui + 1, nxt);
;         const char* nA = has_next ? (const char*)g.A + (size_t)nxt.pm * tstepA + (size_t)nxt.pn * pnoffA : cA; const char* nB = has_next ? (const char*)g.Bt + (size_t)nxt.pn * tstepB : cB;
;         for (int t = 0; t < nt; t += 2) {
;             const bool last = (t == nt - 2);
;             const char* a1 = cA + (size_t)(t + 1) * kstepA;
;             const char* a2 = last ? nA : cA + (size_t)(t + 2) * kstepA; const char* b2 = last ? nB : cB + (size_t)(t + 2) * kstep;
;             const char* a3 = a2 + kstepA; const char* b3 = b2 + kstep;
;             if (last && has_next) S.a_ready(nxt);
;             if constexpr (SP2) {
;             PG8_LDB(B0, 0, 0); PG8_LDB(B1, 0, 1); PG8_SCHED; PG8_LDA(At, 0, 0); PG8_STAGE(PG8_SA(1, 1), a1 + hstepA, voffA);
;             PG8_WAIT_V(8); PG8_WAIT_L(0); PG8_BAR; PG8_MMA(0, 0, At, B0); PG8_MMA(0, 1, At, B1); PG8_BAR; PG8_SCHED;
;             PG8_LDA(At, 0, 1); PG8_STAGE(PG8_SB(0, 0), b2, voffB); PG8_STAGE(PG8_SB(0, 1), b2 + hstepB, voffB); PG8_STAGE(PG8_SA(0, 0), a2, voffA);
;             PG8_WAIT_V(8); PG8_WAIT_L(0); PG8_BAR; PG8_MMA(1, 0, At, B0); PG8_MMA(1, 1, At, B1); PG8_BAR; PG8_SCHED;
.LBB0_332:
	s_ashr_i32 s13, s12, 31
	s_lshl_b64 s[14:15], s[12:13], 15
	s_add_u32 s14, s72, s14
	s_addc_u32 s15, s73, s15
	s_and_b64 s[16:17], s[4:5], exec
	s_cselect_b32 s13, s15, s7
	s_cselect_b32 s36, s14, s6
	s_ashr_i32 s11, s10, 31
	s_lshl_b64 s[16:17], s[10:11], 19
	v_readlane_b32 s20, v254, 7
	v_readlane_b32 s21, v254, 8
	s_add_u32 s16, s20, s16
	s_addc_u32 s17, s21, s17
	s_and_b64 s[20:21], s[4:5], exec
	s_cselect_b32 s11, s17, s19
	s_cselect_b32 s37, s16, s18
	s_add_u32 s38, s18, 0x100
	s_addc_u32 s39, s19, 0
	s_add_u32 s6, s6, 0x204000
	s_addc_u32 s7, s7, 0
	s_mov_b32 s40, -2
	s_add_u32 s18, s6, 0x1fc000
	s_addc_u32 s19, s7, 0
	s_cmp_eq_u32 s40, 12
	s_cselect_b32 s22, s36, s18
	s_cselect_b32 s23, s13, s19
	s_cselect_b32 s20, s37, s38
	s_cselect_b32 s21, s11, s39
	s_add_u32 s18, s22, 0x200000
	s_addc_u32 s19, s23, 0
	s_add_i32 s41, 0, 0x10000
	v_add_u32_e32 v0, s41, v149
	s_add_i32 s44, 0, 0x14000
	ds_read_b128 v[142:145], v0
	ds_read_b128 v[152:155], v0 offset:1024
	ds_read_b128 v[156:159], v0 offset:2048
	ds_read_b128 v[160:163], v0 offset:3072
	v_add_u32_e32 v0, s44, v149
	ds_read_b128 v[164:167], v0
	ds_read_b128 v[168:171], v0 offset:1024
	ds_read_b128 v[172:175], v0 offset:2048
	ds_read_b128 v[176:179], v0 offset:3072
	v_lshl_add_u64 v[146:147], s[6:7], 0, v[138:139]
	s_add_i32 m0, s25, 0xc000
	ds_read_b128 v[180:183], v151
	ds_read_b128 v[184:187], v151 offset:1024
	ds_read_b128 v[188:191], v151 offset:2048
	ds_read_b128 v[206:209], v151 offset:3072
	ds_read_b128 v[210:213], v151 offset:4096
	ds_read_b128 v[214:217], v151 offset:5120
	ds_read_b128 v[218:221], v151 offset:6144
	ds_read_b128 v[222:225], v151 offset:7168
	global_load_lds_dwordx4 v[146:147], off
	v_lshl_add_u64 v[146:147], s[6:7], 0, v[140:141]
	s_add_i32 m0, s25, 0xe000
	s_nop 0
	global_load_lds_dwordx4 v[146:147], off
	s_waitcnt vmcnt(8)
	s_waitcnt lgkmcnt(0)
	s_barrier
	s_setprio 1
	s_waitcnt lgkmcnt(0)
	v_mfma_f32_16x16x32_bf16 v[126:129], v[142:145], v[180:183], 0
	v_mfma_f32_16x16x32_bf16 v[122:125], v[156:159], v[180:183], 0
	v_mfma_f32_16x16x32_bf16 v[110:113], v[142:145], v[188:191], 0
	v_mfma_f32_16x16x32_bf16 v[106:109], v[156:159], v[188:191], 0
	v_mfma_f32_16x16x32_bf16 v[94:97], v[142:145], v[210:213], 0
	v_mfma_f32_16x16x32_bf16 v[90:93], v[156:159], v[210:213], 0
	v_mfma_f32_16x16x32_bf16 v[78:81], v[142:145], v[218:221], 0
	v_mfma_f32_16x16x32_bf16 v[74:77], v[156:159], v[218:221], 0
	v_mfma_f32_16x16x32_bf16 v[126:129], v[152:155], v[184:187], v[126:129]
	v_mfma_f32_16x16x32_bf16 v[122:125], v[160:163], v[184:187], v[122:125]
	v_mfma_f32_16x16x32_bf16 v[110:113], v[152:155], v[206:209], v[110:113]
	v_mfma_f32_16x16x32_bf16 v[106:109], v[160:163], v[206:209], v[106:109]
	v_mfma_f32_16x16x32_bf16 v[94:97], v[152:155], v[214:217], v[94:97]
	v_mfma_f32_16x16x32_bf16 v[90:93], v[160:163], v[214:217], v[90:93]
	v_mfma_f32_16x16x32_bf16 v[78:81], v[152:155], v[222:225], v[78:81]
	v_mfma_f32_16x16x32_bf16 v[74:77], v[160:163], v[222:225], v[74:77]
	s_setprio 0
	s_setprio 1
	v_mfma_f32_16x16x32_bf16 v[118:121], v[164:167], v[180:183], 0
	v_mfma_f32_16x16x32_bf16 v[114:117], v[172:175], v[180:183], 0
	v_mfma_f32_16x16x32_bf16 v[102:105], v[164:167], v[188:191], 0
	v_mfma_f32_16x16x32_bf16 v[98:101], v[172:175], v[188:191], 0
	v_mfma_f32_16x16x32_bf16 v[86:89], v[164:167], v[210:213], 0
	v_mfma_f32_16x16x32_bf16 v[82:85], v[172:175], v[210:213], 0
	v_mfma_f32_16x16x32_bf16 v[70:73], v[164:167], v[218:221], 0
	v_mfma_f32_16x16x32_bf16 v[66:69], v[172:175], v[218:221], 0
	v_mfma_f32_16x16x32_bf16 v[118:121], v[168:171], v[184:187], v[118:121]
	v_mfma_f32_16x16x32_bf16 v[114:117], v[176:179], v[184:187], v[114:117]
	v_mfma_f32_16x16x32_bf16 v[102:105], v[168:171], v[206:209], v[102:105]
	v_mfma_f32_16x16x32_bf16 v[98:101], v[176:179], v[206:209], v[98:101]
	v_mfma_f32_16x16x32_bf16 v[86:89], v[168:171], v[214:217], v[86:89]
	v_mfma_f32_16x16x32_bf16 v[82:85], v[176:179], v[214:217], v[82:85]
	v_mfma_f32_16x16x32_bf16 v[70:73], v[168:171], v[222:225], v[70:73]
	v_mfma_f32_16x16x32_bf16 v[66:69], v[176:179], v[222:225], v[66:69]
	s_setprio 0
	s_barrier
	s_add_i32 s41, s41, s24
	v_lshl_add_u64 v[146:147], s[20:21], 0, v[134:135]
	s_mov_b32 m0, s41
	ds_read_b128 v[180:183], v151 offset:16384
	ds_read_b128 v[184:187], v151 offset:17408
	ds_read_b128 v[188:191], v151 offset:18432
	ds_read_b128 v[206:209], v151 offset:19456
	ds_read_b128 v[210:213], v151 offset:20480
	ds_read_b128 v[214:217], v151 offset:21504
	ds_read_b128 v[218:221], v151 offset:22528
	ds_read_b128 v[222:225], v151 offset:23552
	global_load_lds_dwordx4 v[146:147], off
	s_add_i32 m0, s41, 0x2000
	s_add_u32 s42, s20, 0x40000
	v_lshl_add_u64 v[192:193], s[20:21], 0, v[130:131]
	s_addc_u32 s43, s21, 0
	s_add_i32 s41, s44, s24
	global_load_lds_dwordx4 v[192:193], off
	v_lshl_add_u64 v[226:227], s[42:43], 0, v[134:135]
	s_mov_b32 m0, s41
	s_nop 0
	global_load_lds_dwordx4 v[226:227], off
	v_lshl_add_u64 v[226:227], s[42:43], 0, v[130:131]
	s_add_i32 m0, s41, 0x2000
	s_nop 0
	global_load_lds_dwordx4 v[226:227], off
	v_lshl_add_u64 v[226:227], s[22:23], 0, v[136:137]
	s_mov_b32 m0, s25
	s_nop 0
	global_load_lds_dwordx4 v[226:227], off
	v_lshl_add_u64 v[226:227], s[22:23], 0, v[132:133]
	s_mov_b32 m0, s26
	s_nop 0
	global_load_lds_dwordx4 v[226:227], off
	s_waitcnt vmcnt(8)
	s_waitcnt lgkmcnt(0)
	s_barrier
; #define PG8_STAGE(bufoff, gbase, voff) do { _Pragma("unroll") for (int _i = 0; _i < 2; ++_i) \
;         __builtin_amdgcn_global_load_lds((const unsigned*)((const char*)(gbase) + (voff)[_i]), (PG8_LAS unsigned*)(lds + (bufoff) + ldsw + _i * 8192), 16, 0, 0); } while (0)
; #define PG8_LDA(dst, b, h) do { _Pragma("unroll") for (int m = 0; m < 4; ++m) _Pragma("unroll") for (int k = 0; k < 2; ++k) dst[m][k] = *(const PG8_LAS bf16x8*)(lds + PG8_SA(b, h) + aoff + m * 2048 + k * 1024); } while (0)
; #define PG8_LDB(dst, b, h) do { _Pragma("unroll") for (int n = 0; n < 2; ++n) _Pragma("unroll") for (int k = 0; k < 2; ++k) dst[n][k] = *(const PG8_LAS bf16x8*)(lds + PG8_SB(b, h) + boff + n * 2048 + k * 1024); } while (0)
; #define PG8_MMA(ai, bj, At, Bt) do { __builtin_amdgcn_s_setprio(1); _Pragma("unroll") for (int m = 0; m < 4; ++m) _Pragma("unroll") for (int n = 0; n < 2; ++n) _Pragma("unroll") for (int k = 0; k < 2; ++k) \
;         acc[ai][bj][m][n] = __builtin_amdgcn_mfma_f32_16x16x32_bf16(Bt[n][k], At[m][k], acc[ai][bj][m][n], 0, 0, 0); __builtin_amdgcn_s_setprio(0); } while (0)
; #define PG8_WAIT_V(n) asm volatile("s_waitcnt vmcnt(" #n ")" ::: "memory")
; #define PG8_WAIT_L(n) asm volatile("s_waitcnt lgkmcnt(" #n ")" ::: "memory")
; #define PG8_BAR __builtin_amdgcn_s_barrier()
; #define PG8_SCHED __builtin_amdgcn_sched_barrier(0)
; template <class Epi, class Sched, bool ALIGN_EPI = false, bool SP2 = false>
; __device__ __forceinline__ void gemm_phase(PG8_LAS unsigned char* lds, const Gemm g, const Sched& S, const Epi& E) {
;     ...
;             PG8_WAIT_V(8); PG8_WAIT_L(0); PG8_BAR; PG8_MMA(1, 0, At, B0); PG8_MMA(1, 1, At, B1); PG8_BAR; PG8_SCHED;
;             PG8_LDB(B0, 1, 0); PG8_LDB(B1, 1, 1); PG8_SCHED; PG8_LDA(At, 1, 0); PG8_STAGE(PG8_SA(0, 1), a2 + hstepA, voffA);
;             PG8_WAIT_V(8); PG8_WAIT_L(0); PG8_BAR; PG8_MMA(0, 0, At, B0); PG8_MMA(0, 1, At, B1); PG8_BAR; PG8_SCHED;
	s_setprio 1
	s_waitcnt lgkmcnt(0)
	v_mfma_f32_16x16x32_bf16 v[62:65], v[142:145], v[180:183], 0
	v_mfma_f32_16x16x32_bf16 v[58:61], v[156:159], v[180:183], 0
	v_mfma_f32_16x16x32_bf16 v[46:49], v[142:145], v[188:191], 0
	v_mfma_f32_16x16x32_bf16 v[42:45], v[156:159], v[188:191], 0
	v_mfma_f32_16x16x32_bf16 v[30:33], v[142:145], v[210:213], 0
	v_mfma_f32_16x16x32_bf16 v[26:29], v[156:159], v[210:213], 0
	v_mfma_f32_16x16x32_bf16 v[14:17], v[142:145], v[218:221], 0
	v_mfma_f32_16x16x32_bf16 v[10:13], v[156:159], v[218:221], 0
	v_mfma_f32_16x16x32_bf16 v[62:65], v[152:155], v[184:187], v[62:65]
	v_mfma_f32_16x16x32_bf16 v[58:61], v[160:163], v[184:187], v[58:61]
	v_mfma_f32_16x16x32_bf16 v[46:49], v[152:155], v[206:209], v[46:49]
	v_mfma_f32_16x16x32_bf16 v[42:45], v[160:163], v[206:209], v[42:45]
	v_mfma_f32_16x16x32_bf16 v[30:33], v[152:155], v[214:217], v[30:33]
	v_mfma_f32_16x16x32_bf16 v[26:29], v[160:163], v[214:217], v[26:29]
	v_mfma_f32_16x16x32_bf16 v[14:17], v[152:155], v[222:225], v[14:17]
	v_mfma_f32_16x16x32_bf16 v[10:13], v[160:163], v[222:225], v[10:13]
	s_setprio 0
	s_setprio 1
	v_mfma_f32_16x16x32_bf16 v[54:57], v[164:167], v[180:183], 0
	v_mfma_f32_16x16x32_bf16 v[50:53], v[172:175], v[180:183], 0
	v_mfma_f32_16x16x32_bf16 v[38:41], v[164:167], v[188:191], 0
	v_mfma_f32_16x16x32_bf16 v[34:37], v[172:175], v[188:191], 0
	v_mfma_f32_16x16x32_bf16 v[22:25], v[164:167], v[210:213], 0
	v_mfma_f32_16x16x32_bf16 v[18:21], v[172:175], v[210:213], 0
	v_mfma_f32_16x16x32_bf16 v[6:9], v[164:167], v[218:221], 0
	v_mfma_f32_16x16x32_bf16 v[2:5], v[172:175], v[218:221], 0
	v_mfma_f32_16x16x32_bf16 v[54:57], v[168:171], v[184:187], v[54:57]
	v_mfma_f32_16x16x32_bf16 v[50:53], v[176:179], v[184:187], v[50:53]
	v_mfma_f32_16x16x32_bf16 v[38:41], v[168:171], v[206:209], v[38:41]
	v_mfma_f32_16x16x32_bf16 v[34:37], v[176:179], v[206:209], v[34:37]
	v_mfma_f32_16x16x32_bf16 v[22:25], v[168:171], v[214:217], v[22:25]
	v_mfma_f32_16x16x32_bf16 v[18:21], v[176:179], v[214:217], v[18:21]
	v_mfma_f32_16x16x32_bf16 v[6:9], v[168:171], v[222:225], v[6:9]
	v_mfma_f32_16x16x32_bf16 v[2:5], v[176:179], v[222:225], v[2:5]
	s_setprio 0
	s_barrier
	s_add_i32 s41, 0, 0x18000
	v_add_u32_e32 v0, s41, v149
	s_add_i32 s42, 0, 0x1c000
	ds_read_b128 v[142:145], v0
	ds_read_b128 v[152:155], v0 offset:1024
	ds_read_b128 v[156:159], v0 offset:2048
	ds_read_b128 v[160:163], v0 offset:3072
	v_add_u32_e32 v0, s42, v149
	ds_read_b128 v[164:167], v0
	ds_read_b128 v[168:171], v0 offset:1024
	ds_read_b128 v[172:175], v0 offset:2048
	ds_read_b128 v[176:179], v0 offset:3072
	s_add_u32 s22, s22, 0x4000
	s_addc_u32 s23, s23, 0
	s_mov_b32 m0, s27
	v_lshl_add_u64 v[226:227], s[22:23], 0, v[136:137]
	ds_read_b128 v[180:183], v151 offset:32768
	ds_read_b128 v[184:187], v151 offset:33792
	ds_read_b128 v[188:191], v151 offset:34816
	ds_read_b128 v[206:209], v151 offset:35840
	ds_read_b128 v[210:213], v151 offset:36864
	ds_read_b128 v[214:217], v151 offset:37888
	ds_read_b128 v[218:221], v151 offset:38912
	ds_read_b128 v[222:225], v151 offset:39936
	global_load_lds_dwordx4 v[226:227], off
	v_lshl_add_u64 v[226:227], s[22:23], 0, v[132:133]
	s_mov_b32 m0, s28
	s_nop 0
	global_load_lds_dwordx4 v[226:227], off
	s_waitcnt vmcnt(8)
	s_waitcnt lgkmcnt(0)
	s_barrier
	s_setprio 1
	s_waitcnt lgkmcnt(0)
	v_mfma_f32_16x16x32_bf16 v[126:129], v[142:145], v[180:183], v[126:129]
	v_mfma_f32_16x16x32_bf16 v[122:125], v[156:159], v[180:183], v[122:125]
	v_mfma_f32_16x16x32_bf16 v[110:113], v[142:145], v[188:191], v[110:113]
	v_mfma_f32_16x16x32_bf16 v[106:109], v[156:159], v[188:191], v[106:109]
	v_mfma_f32_16x16x32_bf16 v[94:97], v[142:145], v[210:213], v[94:97]
	v_mfma_f32_16x16x32_bf16 v[90:93], v[156:159], v[210:213], v[90:93]
	v_mfma_f32_16x16x32_bf16 v[78:81], v[142:145], v[218:221], v[78:81]
	v_mfma_f32_16x16x32_bf16 v[74:77], v[156:159], v[218:221], v[74:77]
	v_mfma_f32_16x16x32_bf16 v[126:129], v[152:155], v[184:187], v[126:129]
	v_mfma_f32_16x16x32_bf16 v[122:125], v[160:163], v[184:187], v[122:125]
	v_mfma_f32_16x16x32_bf16 v[110:113], v[152:155], v[206:209], v[110:113]
	v_mfma_f32_16x16x32_bf16 v[106:109], v[160:163], v[206:209], v[106:109]
	v_mfma_f32_16x16x32_bf16 v[94:97], v[152:155], v[214:217], v[94:97]
	v_mfma_f32_16x16x32_bf16 v[90:93], v[160:163], v[214:217], v[90:93]
	v_mfma_f32_16x16x32_bf16 v[78:81], v[152:155], v[222:225], v[78:81]
	v_mfma_f32_16x16x32_bf16 v[74:77], v[160:163], v[222:225], v[74:77]
	s_setprio 0
	s_setprio 1
	v_mfma_f32_16x16x32_bf16 v[118:121], v[164:167], v[180:183], v[118:121]
	v_mfma_f32_16x16x32_bf16 v[114:117], v[172:175], v[180:183], v[114:117]
	v_mfma_f32_16x16x32_bf16 v[102:105], v[164:167], v[188:191], v[102:105]
	v_mfma_f32_16x16x32_bf16 v[98:101], v[172:175], v[188:191], v[98:101]
	v_mfma_f32_16x16x32_bf16 v[86:89], v[164:167], v[210:213], v[86:89]
	v_mfma_f32_16x16x32_bf16 v[82:85], v[172:175], v[210:213], v[82:85]
	v_mfma_f32_16x16x32_bf16 v[70:73], v[164:167], v[218:221], v[70:73]
	v_mfma_f32_16x16x32_bf16 v[66:69], v[172:175], v[218:221], v[66:69]
	v_mfma_f32_16x16x32_bf16 v[118:121], v[168:171], v[184:187], v[118:121]
	v_mfma_f32_16x16x32_bf16 v[114:117], v[176:179], v[184:187], v[114:117]
	v_mfma_f32_16x16x32_bf16 v[102:105], v[168:171], v[206:209], v[102:105]
	v_mfma_f32_16x16x32_bf16 v[98:101], v[176:179], v[206:209], v[98:101]
	v_mfma_f32_16x16x32_bf16 v[86:89], v[168:171], v[214:217], v[86:89]
	v_mfma_f32_16x16x32_bf16 v[82:85], v[176:179], v[214:217], v[82:85]
	v_mfma_f32_16x16x32_bf16 v[70:73], v[168:171], v[222:225], v[70:73]
	v_mfma_f32_16x16x32_bf16 v[66:69], v[176:179], v[222:225], v[66:69]
	s_setprio 0
	s_barrier
; #define PG8_STAGE(bufoff, gbase, voff) do { _Pragma("unroll") for (int _i = 0; _i < 2; ++_i) \
;         __builtin_amdgcn_global_load_lds((const unsigned*)((const char*)(gbase) + (voff)[_i]), (PG8_LAS unsigned*)(lds + (bufoff) + ldsw + _i * 8192), 16, 0, 0); } while (0)
; #define PG8_LDA(dst, b, h) do { _Pragma("unroll") for (int m = 0; m < 4; ++m) _Pragma("unroll") for (int k = 0; k < 2; ++k) dst[m][k] = *(const PG8_LAS bf16x8*)(lds + PG8_SA(b, h) + aoff + m * 2048 + k * 1024); } while (0)
; #define PG8_LDB(dst, b, h) do { _Pragma("unroll") for (int n = 0; n < 2; ++n) _Pragma("unroll") for (int k = 0; k < 2; ++k) dst[n][k] = *(const PG8_LAS bf16x8*)(lds + PG8_SB(b, h) + boff + n * 2048 + k * 1024); } while (0)
; template <class Epi, class Sched, bool ALIGN_EPI = false, bool SP2 = false>
; __device__ __forceinline__ void gemm_phase(PG8_LAS unsigned char* lds, const Gemm g, const Sched& S, const Epi& E) {
;     ...
;         for (int t = 0; t < nt; t += 2) {
;             const bool last = (t == nt - 2);
;             const char* a1 = cA + (size_t)(t + 1) * kstepA;
;             const char* a2 = last ? nA : cA + (size_t)(t + 2) * kstepA; const char* b2 = last ? nB : cB + (size_t)(t + 2) * kstep;
;             const char* a3 = a2 + kstepA; const char* b3 = b2 + kstep;
;             if (last && has_next) S.a_ready(nxt);
;             if constexpr (SP2) {
;             PG8_LDB(B0, 0, 0); PG8_LDB(B1, 0, 1); PG8_SCHED; PG8_LDA(At, 0, 0); PG8_STAGE(PG8_SA(1, 1), a1 + hstepA, voffA);
;             PG8_WAIT_V(8); PG8_WAIT_L(0); PG8_BAR; PG8_MMA(0, 0, At, B0); PG8_MMA(0, 1, At, B1); PG8_BAR; PG8_SCHED;
;             PG8_LDA(At, 0, 1); PG8_STAGE(PG8_SB(0, 0), b2, voffB); PG8_STAGE(PG8_SB(0, 1), b2 + hstepB, voffB); PG8_STAGE(PG8_SA(0, 0), a2, voffA);
;             PG8_WAIT_V(8); PG8_WAIT_L(0); PG8_BAR; PG8_MMA(1, 0, At, B0); PG8_MMA(1, 1, At, B1); PG8_BAR; PG8_SCHED;
;             PG8_LDB(B0, 1, 0); PG8_LDB(B1, 1, 1); PG8_SCHED; PG8_LDA(At, 1, 0); PG8_STAGE(PG8_SA(0, 1), a2 + hstepA, voffA);
;             PG8_WAIT_V(8); PG8_WAIT_L(0); PG8_BAR; PG8_MMA(0, 0, At, B0); PG8_MMA(0, 1, At, B1); PG8_BAR; PG8_SCHED;
;             PG8_LDA(At, 1, 1); PG8_STAGE(PG8_SB(1, 0), b3, voffB); PG8_STAGE(PG8_SB(1, 1), b3 + hstepB, voffB); PG8_STAGE(PG8_SA(1, 0), a3, voffA);
;             PG8_WAIT_V(8); PG8_WAIT_L(0); PG8_BAR; PG8_MMA(1, 0, At, B0); PG8_MMA(1, 1, At, B1); PG8_BAR; PG8_SCHED;
	s_add_i32 s22, s41, s24
	v_lshl_add_u64 v[146:147], v[146:147], 0, s[78:79]
	s_mov_b32 m0, s22
	ds_read_b128 v[180:183], v151 offset:49152
	ds_read_b128 v[184:187], v151 offset:50176
	ds_read_b128 v[188:191], v151 offset:51200
	ds_read_b128 v[206:209], v151 offset:52224
	ds_read_b128 v[210:213], v151 offset:53248
	ds_read_b128 v[214:217], v151 offset:54272
	ds_read_b128 v[218:221], v151 offset:55296
	ds_read_b128 v[222:225], v151 offset:56320
	global_load_lds_dwordx4 v[146:147], off
	s_add_i32 m0, s22, 0x2000
	s_add_u32 s20, s20, 0x40080
	v_lshl_add_u64 v[146:147], v[192:193], 0, s[78:79]
	s_addc_u32 s21, s21, 0
	s_add_i32 s22, s42, s24
	global_load_lds_dwordx4 v[146:147], off
	v_lshl_add_u64 v[146:147], s[20:21], 0, v[134:135]
	s_mov_b32 m0, s22
	s_nop 0
	global_load_lds_dwordx4 v[146:147], off
	v_lshl_add_u64 v[146:147], s[20:21], 0, v[130:131]
	s_add_i32 m0, s22, 0x2000
	s_nop 0
	global_load_lds_dwordx4 v[146:147], off
	v_lshl_add_u64 v[146:147], s[18:19], 0, v[136:137]
	s_mov_b32 m0, s29
	s_nop 0
	global_load_lds_dwordx4 v[146:147], off
	v_lshl_add_u64 v[146:147], s[18:19], 0, v[132:133]
	s_mov_b32 m0, s30
	s_nop 0
	global_load_lds_dwordx4 v[146:147], off
	s_waitcnt vmcnt(8)
	s_waitcnt lgkmcnt(0)
	s_barrier
	s_setprio 1
	s_waitcnt lgkmcnt(0)
	v_mfma_f32_16x16x32_bf16 v[62:65], v[142:145], v[180:183], v[62:65]
	v_mfma_f32_16x16x32_bf16 v[58:61], v[156:159], v[180:183], v[58:61]
	v_mfma_f32_16x16x32_bf16 v[46:49], v[142:145], v[188:191], v[46:49]
	v_mfma_f32_16x16x32_bf16 v[42:45], v[156:159], v[188:191], v[42:45]
	v_mfma_f32_16x16x32_bf16 v[30:33], v[142:145], v[210:213], v[30:33]
	v_mfma_f32_16x16x32_bf16 v[26:29], v[156:159], v[210:213], v[26:29]
	v_mfma_f32_16x16x32_bf16 v[14:17], v[142:145], v[218:221], v[14:17]
	v_mfma_f32_16x16x32_bf16 v[10:13], v[156:159], v[218:221], v[10:13]
	v_mfma_f32_16x16x32_bf16 v[62:65], v[152:155], v[184:187], v[62:65]
	v_mfma_f32_16x16x32_bf16 v[58:61], v[160:163], v[184:187], v[58:61]
	v_mfma_f32_16x16x32_bf16 v[46:49], v[152:155], v[206:209], v[46:49]
	v_mfma_f32_16x16x32_bf16 v[42:45], v[160:163], v[206:209], v[42:45]
	v_mfma_f32_16x16x32_bf16 v[30:33], v[152:155], v[214:217], v[30:33]
	v_mfma_f32_16x16x32_bf16 v[26:29], v[160:163], v[214:217], v[26:29]
	v_mfma_f32_16x16x32_bf16 v[14:17], v[152:155], v[222:225], v[14:17]
	v_mfma_f32_16x16x32_bf16 v[10:13], v[160:163], v[222:225], v[10:13]
	s_setprio 0
	s_setprio 1
	v_mfma_f32_16x16x32_bf16 v[54:57], v[164:167], v[180:183], v[54:57]
	v_mfma_f32_16x16x32_bf16 v[50:53], v[172:175], v[180:183], v[50:53]
	v_mfma_f32_16x16x32_bf16 v[38:41], v[164:167], v[188:191], v[38:41]
	v_mfma_f32_16x16x32_bf16 v[34:37], v[172:175], v[188:191], v[34:37]
	v_mfma_f32_16x16x32_bf16 v[22:25], v[164:167], v[210:213], v[22:25]
	v_mfma_f32_16x16x32_bf16 v[18:21], v[172:175], v[210:213], v[18:21]
	v_mfma_f32_16x16x32_bf16 v[6:9], v[164:167], v[218:221], v[6:9]
	v_mfma_f32_16x16x32_bf16 v[2:5], v[172:175], v[218:221], v[2:5]
	v_mfma_f32_16x16x32_bf16 v[54:57], v[168:171], v[184:187], v[54:57]
	v_mfma_f32_16x16x32_bf16 v[50:53], v[176:179], v[184:187], v[50:53]
	v_mfma_f32_16x16x32_bf16 v[38:41], v[168:171], v[206:209], v[38:41]
	v_mfma_f32_16x16x32_bf16 v[34:37], v[176:179], v[206:209], v[34:37]
	v_mfma_f32_16x16x32_bf16 v[22:25], v[168:171], v[214:217], v[22:25]
	v_mfma_f32_16x16x32_bf16 v[18:21], v[176:179], v[214:217], v[18:21]
	v_mfma_f32_16x16x32_bf16 v[6:9], v[168:171], v[222:225], v[6:9]
	v_mfma_f32_16x16x32_bf16 v[2:5], v[176:179], v[222:225], v[2:5]
	s_setprio 0
	s_add_i32 s40, s40, 2
	s_add_u32 s38, s38, 0x100
	s_addc_u32 s39, s39, 0
	s_add_u32 s6, s6, 0x400000
	s_addc_u32 s7, s7, 0
	s_add_u32 s18, s6, 0x1fc000
	s_addc_u32 s19, s7, 0
	s_cmp_eq_u32 s40, 12
	s_cselect_b32 s22, s36, s18
	s_cselect_b32 s23, s13, s19
	s_cselect_b32 s20, s37, s38
	s_cselect_b32 s21, s11, s39
	s_add_u32 s18, s22, 0x200000
	s_addc_u32 s19, s23, 0
	s_add_i32 s41, 0, 0x10000
	s_barrier
.LBB0_333:
	v_add_u32_e32 v0, s41, v149
	s_add_i32 s44, 0, 0x14000
	ds_read_b128 v[142:145], v0
	ds_read_b128 v[152:155], v0 offset:1024
	ds_read_b128 v[156:159], v0 offset:2048
	ds_read_b128 v[160:163], v0 offset:3072
	v_add_u32_e32 v0, s44, v149
	ds_read_b128 v[164:167], v0
	ds_read_b128 v[168:171], v0 offset:1024
	ds_read_b128 v[172:175], v0 offset:2048
	ds_read_b128 v[176:179], v0 offset:3072
	v_lshl_add_u64 v[146:147], s[6:7], 0, v[138:139]
	s_add_i32 m0, s25, 0xc000
	ds_read_b128 v[180:183], v151
	ds_read_b128 v[184:187], v151 offset:1024
	ds_read_b128 v[188:191], v151 offset:2048
	ds_read_b128 v[206:209], v151 offset:3072
	ds_read_b128 v[210:213], v151 offset:4096
	ds_read_b128 v[214:217], v151 offset:5120
	ds_read_b128 v[218:221], v151 offset:6144
	ds_read_b128 v[222:225], v151 offset:7168
	global_load_lds_dwordx4 v[146:147], off
	v_lshl_add_u64 v[146:147], s[6:7], 0, v[140:141]
	s_add_i32 m0, s25, 0xe000
	s_nop 0
	global_load_lds_dwordx4 v[146:147], off
	s_waitcnt vmcnt(8)
	s_waitcnt lgkmcnt(0)
	s_barrier
; #define PG8_STAGE(bufoff, gbase, voff) do { _Pragma("unroll") for (int _i = 0; _i < 2; ++_i) \
;         __builtin_amdgcn_global_load_lds((const unsigned*)((const char*)(gbase) + (voff)[_i]), (PG8_LAS unsigned*)(lds + (bufoff) + ldsw + _i * 8192), 16, 0, 0); } while (0)
; #define PG8_LDA(dst, b, h) do { _Pragma("unroll") for (int m = 0; m < 4; ++m) _Pragma("unroll") for (int k = 0; k < 2; ++k) dst[m][k] = *(const PG8_LAS bf16x8*)(lds + PG8_SA(b, h) + aoff + m * 2048 + k * 1024); } while (0)
; #define PG8_LDB(dst, b, h) do { _Pragma("unroll") for (int n = 0; n < 2; ++n) _Pragma("unroll") for (int k = 0; k < 2; ++k) dst[n][k] = *(const PG8_LAS bf16x8*)(lds + PG8_SB(b, h) + boff + n * 2048 + k * 1024); } while (0)
; #define PG8_MMA(ai, bj, At, Bt) do { __builtin_amdgcn_s_setprio(1); _Pragma("unroll") for (int m = 0; m < 4; ++m) _Pragma("unroll") for (int n = 0; n < 2; ++n) _Pragma("unroll") for (int k = 0; k < 2; ++k) \
;         acc[ai][bj][m][n] = __builtin_amdgcn_mfma_f32_16x16x32_bf16(Bt[n][k], At[m][k], acc[ai][bj][m][n], 0, 0, 0); __builtin_amdgcn_s_setprio(0); } while (0)
; #define PG8_WAIT_V(n) asm volatile("s_waitcnt vmcnt(" #n ")" ::: "memory")
; #define PG8_WAIT_L(n) asm volatile("s_waitcnt lgkmcnt(" #n ")" ::: "memory")
; #define PG8_BAR __builtin_amdgcn_s_barrier()
; #define PG8_SCHED __builtin_amdgcn_sched_barrier(0)
; template <class Epi, class Sched, bool ALIGN_EPI = false, bool SP2 = false>
; __device__ __forceinline__ void gemm_phase(PG8_LAS unsigned char* lds, const Gemm g, const Sched& S, const Epi& E) {
;     ...
;             PG8_LDB(B0, 0, 0); PG8_LDB(B1, 0, 1); PG8_SCHED; PG8_LDA(At, 0, 0); PG8_STAGE(PG8_SA(1, 1), a1 + hstepA, voffA);
;             PG8_WAIT_V(8); PG8_WAIT_L(0); PG8_BAR; PG8_MMA(0, 0, At, B0); PG8_MMA(0, 1, At, B1); PG8_BAR; PG8_SCHED;
;             PG8_LDA(At, 0, 1); PG8_STAGE(PG8_SB(0, 0), b2, voffB); PG8_STAGE(PG8_SB(0, 1), b2 + hstepB, voffB); PG8_STAGE(PG8_SA(0, 0), a2, voffA);
;             PG8_WAIT_V(8); PG8_WAIT_L(0); PG8_BAR; PG8_MMA(1, 0, At, B0); PG8_MMA(1, 1, At, B1); PG8_BAR; PG8_SCHED;
	s_setprio 1
	s_waitcnt lgkmcnt(0)
	v_mfma_f32_16x16x32_bf16 v[126:129], v[142:145], v[180:183], v[126:129]
	v_mfma_f32_16x16x32_bf16 v[122:125], v[156:159], v[180:183], v[122:125]
	v_mfma_f32_16x16x32_bf16 v[110:113], v[142:145], v[188:191], v[110:113]
	v_mfma_f32_16x16x32_bf16 v[106:109], v[156:159], v[188:191], v[106:109]
	v_mfma_f32_16x16x32_bf16 v[94:97], v[142:145], v[210:213], v[94:97]
	v_mfma_f32_16x16x32_bf16 v[90:93], v[156:159], v[210:213], v[90:93]
	v_mfma_f32_16x16x32_bf16 v[78:81], v[142:145], v[218:221], v[78:81]
	v_mfma_f32_16x16x32_bf16 v[74:77], v[156:159], v[218:221], v[74:77]
	v_mfma_f32_16x16x32_bf16 v[126:129], v[152:155], v[184:187], v[126:129]
	v_mfma_f32_16x16x32_bf16 v[122:125], v[160:163], v[184:187], v[122:125]
	v_mfma_f32_16x16x32_bf16 v[110:113], v[152:155], v[206:209], v[110:113]
	v_mfma_f32_16x16x32_bf16 v[106:109], v[160:163], v[206:209], v[106:109]
	v_mfma_f32_16x16x32_bf16 v[94:97], v[152:155], v[214:217], v[94:97]
	v_mfma_f32_16x16x32_bf16 v[90:93], v[160:163], v[214:217], v[90:93]
	v_mfma_f32_16x16x32_bf16 v[78:81], v[152:155], v[222:225], v[78:81]
	v_mfma_f32_16x16x32_bf16 v[74:77], v[160:163], v[222:225], v[74:77]
	s_setprio 0
	s_setprio 1
	v_mfma_f32_16x16x32_bf16 v[118:121], v[164:167], v[180:183], v[118:121]
	v_mfma_f32_16x16x32_bf16 v[114:117], v[172:175], v[180:183], v[114:117]
	v_mfma_f32_16x16x32_bf16 v[102:105], v[164:167], v[188:191], v[102:105]
	v_mfma_f32_16x16x32_bf16 v[98:101], v[172:175], v[188:191], v[98:101]
	v_mfma_f32_16x16x32_bf16 v[86:89], v[164:167], v[210:213], v[86:89]
	v_mfma_f32_16x16x32_bf16 v[82:85], v[172:175], v[210:213], v[82:85]
	v_mfma_f32_16x16x32_bf16 v[70:73], v[164:167], v[218:221], v[70:73]
	v_mfma_f32_16x16x32_bf16 v[66:69], v[172:175], v[218:221], v[66:69]
	v_mfma_f32_16x16x32_bf16 v[118:121], v[168:171], v[184:187], v[118:121]
	v_mfma_f32_16x16x32_bf16 v[114:117], v[176:179], v[184:187], v[114:117]
	v_mfma_f32_16x16x32_bf16 v[102:105], v[168:171], v[206:209], v[102:105]
	v_mfma_f32_16x16x32_bf16 v[98:101], v[176:179], v[206:209], v[98:101]
	v_mfma_f32_16x16x32_bf16 v[86:89], v[168:171], v[214:217], v[86:89]
	v_mfma_f32_16x16x32_bf16 v[82:85], v[176:179], v[214:217], v[82:85]
	v_mfma_f32_16x16x32_bf16 v[70:73], v[168:171], v[222:225], v[70:73]
	v_mfma_f32_16x16x32_bf16 v[66:69], v[176:179], v[222:225], v[66:69]
	s_setprio 0
	s_barrier
	s_add_i32 s41, s41, s24
	v_lshl_add_u64 v[146:147], s[20:21], 0, v[134:135]
	s_mov_b32 m0, s41
	ds_read_b128 v[180:183], v151 offset:16384
	ds_read_b128 v[184:187], v151 offset:17408
	ds_read_b128 v[188:191], v151 offset:18432
	ds_read_b128 v[206:209], v151 offset:19456
	ds_read_b128 v[210:213], v151 offset:20480
	ds_read_b128 v[214:217], v151 offset:21504
	ds_read_b128 v[218:221], v151 offset:22528
	ds_read_b128 v[222:225], v151 offset:23552
	global_load_lds_dwordx4 v[146:147], off
	s_add_i32 m0, s41, 0x2000
	s_add_u32 s42, s20, 0x40000
	v_lshl_add_u64 v[192:193], s[20:21], 0, v[130:131]
	s_addc_u32 s43, s21, 0
	s_add_i32 s41, s44, s24
	global_load_lds_dwordx4 v[192:193], off
	v_lshl_add_u64 v[226:227], s[42:43], 0, v[134:135]
	s_mov_b32 m0, s41
	s_nop 0
	global_load_lds_dwordx4 v[226:227], off
	v_lshl_add_u64 v[226:227], s[42:43], 0, v[130:131]
	s_add_i32 m0, s41, 0x2000
	s_nop 0
	global_load_lds_dwordx4 v[226:227], off
	v_lshl_add_u64 v[226:227], s[22:23], 0, v[136:137]
	s_mov_b32 m0, s25
	s_nop 0
	global_load_lds_dwordx4 v[226:227], off
	v_lshl_add_u64 v[226:227], s[22:23], 0, v[132:133]
	s_mov_b32 m0, s26
	s_nop 0
	global_load_lds_dwordx4 v[226:227], off
	s_waitcnt vmcnt(8)
	s_waitcnt lgkmcnt(0)
	s_barrier
	s_setprio 1
	s_waitcnt lgkmcnt(0)
	v_mfma_f32_16x16x32_bf16 v[62:65], v[142:145], v[180:183], v[62:65]
	v_mfma_f32_16x16x32_bf16 v[58:61], v[156:159], v[180:183], v[58:61]
	v_mfma_f32_16x16x32_bf16 v[46:49], v[142:145], v[188:191], v[46:49]
	v_mfma_f32_16x16x32_bf16 v[42:45], v[156:159], v[188:191], v[42:45]
	v_mfma_f32_16x16x32_bf16 v[30:33], v[142:145], v[210:213], v[30:33]
	v_mfma_f32_16x16x32_bf16 v[26:29], v[156:159], v[210:213], v[26:29]
	v_mfma_f32_16x16x32_bf16 v[14:17], v[142:145], v[218:221], v[14:17]
	v_mfma_f32_16x16x32_bf16 v[10:13], v[156:159], v[218:221], v[10:13]
	v_mfma_f32_16x16x32_bf16 v[62:65], v[152:155], v[184:187], v[62:65]
	v_mfma_f32_16x16x32_bf16 v[58:61], v[160:163], v[184:187], v[58:61]
	v_mfma_f32_16x16x32_bf16 v[46:49], v[152:155], v[206:209], v[46:49]
	v_mfma_f32_16x16x32_bf16 v[42:45], v[160:163], v[206:209], v[42:45]
	v_mfma_f32_16x16x32_bf16 v[30:33], v[152:155], v[214:217], v[30:33]
	v_mfma_f32_16x16x32_bf16 v[26:29], v[160:163], v[214:217], v[26:29]
	v_mfma_f32_16x16x32_bf16 v[14:17], v[152:155], v[222:225], v[14:17]
	v_mfma_f32_16x16x32_bf16 v[10:13], v[160:163], v[222:225], v[10:13]
	s_setprio 0
	s_setprio 1
	v_mfma_f32_16x16x32_bf16 v[54:57], v[164:167], v[180:183], v[54:57]
	v_mfma_f32_16x16x32_bf16 v[50:53], v[172:175], v[180:183], v[50:53]
	v_mfma_f32_16x16x32_bf16 v[38:41], v[164:167], v[188:191], v[38:41]
	v_mfma_f32_16x16x32_bf16 v[34:37], v[172:175], v[188:191], v[34:37]
	v_mfma_f32_16x16x32_bf16 v[22:25], v[164:167], v[210:213], v[22:25]
	v_mfma_f32_16x16x32_bf16 v[18:21], v[172:175], v[210:213], v[18:21]
	v_mfma_f32_16x16x32_bf16 v[6:9], v[164:167], v[218:221], v[6:9]
	v_mfma_f32_16x16x32_bf16 v[2:5], v[172:175], v[218:221], v[2:5]
	v_mfma_f32_16x16x32_bf16 v[54:57], v[168:171], v[184:187], v[54:57]
	v_mfma_f32_16x16x32_bf16 v[50:53], v[176:179], v[184:187], v[50:53]
	v_mfma_f32_16x16x32_bf16 v[38:41], v[168:171], v[206:209], v[38:41]
	v_mfma_f32_16x16x32_bf16 v[34:37], v[176:179], v[206:209], v[34:37]
	v_mfma_f32_16x16x32_bf16 v[22:25], v[168:171], v[214:217], v[22:25]
	v_mfma_f32_16x16x32_bf16 v[18:21], v[176:179], v[214:217], v[18:21]
	v_mfma_f32_16x16x32_bf16 v[6:9], v[168:171], v[222:225], v[6:9]
	v_mfma_f32_16x16x32_bf16 v[2:5], v[176:179], v[222:225], v[2:5]
	s_setprio 0
	s_barrier
; #define PG8_STAGE(bufoff, gbase, voff) do { _Pragma("unroll") for (int _i = 0; _i < 2; ++_i) \
;         __builtin_amdgcn_global_load_lds((const unsigned*)((const char*)(gbase) + (voff)[_i]), (PG8_LAS unsigned*)(lds + (bufoff) + ldsw + _i * 8192), 16, 0, 0); } while (0)
; #define PG8_LDA(dst, b, h) do { _Pragma("unroll") for (int m = 0; m < 4; ++m) _Pragma("unroll") for (int k = 0; k < 2; ++k) dst[m][k] = *(const PG8_LAS bf16x8*)(lds + PG8_SA(b, h) + aoff + m * 2048 + k * 1024); } while (0)
; #define PG8_LDB(dst, b, h) do { _Pragma("unroll") for (int n = 0; n < 2; ++n) _Pragma("unroll") for (int k = 0; k < 2; ++k) dst[n][k] = *(const PG8_LAS bf16x8*)(lds + PG8_SB(b, h) + boff + n * 2048 + k * 1024); } while (0)
; #define PG8_MMA(ai, bj, At, Bt) do { __builtin_amdgcn_s_setprio(1); _Pragma("unroll") for (int m = 0; m < 4; ++m) _Pragma("unroll") for (int n = 0; n < 2; ++n) _Pragma("unroll") for (int k = 0; k < 2; ++k) \
;         acc[ai][bj][m][n] = __builtin_amdgcn_mfma_f32_16x16x32_bf16(Bt[n][k], At[m][k], acc[ai][bj][m][n], 0, 0, 0); __builtin_amdgcn_s_setprio(0); } while (0)
; #define PG8_WAIT_V(n) asm volatile("s_waitcnt vmcnt(" #n ")" ::: "memory")
; #define PG8_WAIT_L(n) asm volatile("s_waitcnt lgkmcnt(" #n ")" ::: "memory")
; #define PG8_BAR __builtin_amdgcn_s_barrier()
; #define PG8_SCHED __builtin_amdgcn_sched_barrier(0)
; template <class Epi, class Sched, bool ALIGN_EPI = false, bool SP2 = false>
; __device__ __forceinline__ void gemm_phase(PG8_LAS unsigned char* lds, const Gemm g, const Sched& S, const Epi& E) {
;     ...
;             PG8_LDB(B0, 1, 0); PG8_LDB(B1, 1, 1); PG8_SCHED; PG8_LDA(At, 1, 0); PG8_STAGE(PG8_SA(0, 1), a2 + hstepA, voffA);
;             PG8_WAIT_V(8); PG8_WAIT_L(0); PG8_BAR; PG8_MMA(0, 0, At, B0); PG8_MMA(0, 1, At, B1); PG8_BAR; PG8_SCHED;
	s_add_i32 s41, 0, 0x18000
	v_add_u32_e32 v0, s41, v149
	s_add_i32 s42, 0, 0x1c000
	ds_read_b128 v[142:145], v0
	ds_read_b128 v[152:155], v0 offset:1024
	ds_read_b128 v[156:159], v0 offset:2048
	ds_read_b128 v[160:163], v0 offset:3072
	v_add_u32_e32 v0, s42, v149
	ds_read_b128 v[164:167], v0
	ds_read_b128 v[168:171], v0 offset:1024
	ds_read_b128 v[172:175], v0 offset:2048
	ds_read_b128 v[176:179], v0 offset:3072
	s_add_u32 s22, s22, 0x4000
	s_addc_u32 s23, s23, 0
	s_mov_b32 m0, s27
	v_lshl_add_u64 v[226:227], s[22:23], 0, v[136:137]
	ds_read_b128 v[180:183], v151 offset:32768
	ds_read_b128 v[184:187], v151 offset:33792
	ds_read_b128 v[188:191], v151 offset:34816
	ds_read_b128 v[206:209], v151 offset:35840
	ds_read_b128 v[210:213], v151 offset:36864
	ds_read_b128 v[214:217], v151 offset:37888
	ds_read_b128 v[218:221], v151 offset:38912
	ds_read_b128 v[222:225], v151 offset:39936
	global_load_lds_dwordx4 v[226:227], off
	v_lshl_add_u64 v[226:227], s[22:23], 0, v[132:133]
	s_mov_b32 m0, s28
	s_nop 0
	global_load_lds_dwordx4 v[226:227], off
	s_waitcnt vmcnt(8)
	s_waitcnt lgkmcnt(0)
	s_barrier
	s_setprio 1
	s_waitcnt lgkmcnt(0)
	v_mfma_f32_16x16x32_bf16 v[126:129], v[142:145], v[180:183], v[126:129]
	v_mfma_f32_16x16x32_bf16 v[122:125], v[156:159], v[180:183], v[122:125]
	v_mfma_f32_16x16x32_bf16 v[110:113], v[142:145], v[188:191], v[110:113]
	v_mfma_f32_16x16x32_bf16 v[106:109], v[156:159], v[188:191], v[106:109]
	v_mfma_f32_16x16x32_bf16 v[94:97], v[142:145], v[210:213], v[94:97]
	v_mfma_f32_16x16x32_bf16 v[90:93], v[156:159], v[210:213], v[90:93]
	v_mfma_f32_16x16x32_bf16 v[78:81], v[142:145], v[218:221], v[78:81]
	v_mfma_f32_16x16x32_bf16 v[74:77], v[156:159], v[218:221], v[74:77]
	v_mfma_f32_16x16x32_bf16 v[126:129], v[152:155], v[184:187], v[126:129]
	v_mfma_f32_16x16x32_bf16 v[122:125], v[160:163], v[184:187], v[122:125]
	v_mfma_f32_16x16x32_bf16 v[110:113], v[152:155], v[206:209], v[110:113]
	v_mfma_f32_16x16x32_bf16 v[106:109], v[160:163], v[206:209], v[106:109]
	v_mfma_f32_16x16x32_bf16 v[94:97], v[152:155], v[214:217], v[94:97]
	v_mfma_f32_16x16x32_bf16 v[90:93], v[160:163], v[214:217], v[90:93]
	v_mfma_f32_16x16x32_bf16 v[78:81], v[152:155], v[222:225], v[78:81]
	v_mfma_f32_16x16x32_bf16 v[74:77], v[160:163], v[222:225], v[74:77]
	s_setprio 0
	s_setprio 1
	v_mfma_f32_16x16x32_bf16 v[118:121], v[164:167], v[180:183], v[118:121]
	v_mfma_f32_16x16x32_bf16 v[114:117], v[172:175], v[180:183], v[114:117]
	v_mfma_f32_16x16x32_bf16 v[102:105], v[164:167], v[188:191], v[102:105]
	v_mfma_f32_16x16x32_bf16 v[98:101], v[172:175], v[188:191], v[98:101]
	v_mfma_f32_16x16x32_bf16 v[86:89], v[164:167], v[210:213], v[86:89]
	v_mfma_f32_16x16x32_bf16 v[82:85], v[172:175], v[210:213], v[82:85]
	v_mfma_f32_16x16x32_bf16 v[70:73], v[164:167], v[218:221], v[70:73]
	v_mfma_f32_16x16x32_bf16 v[66:69], v[172:175], v[218:221], v[66:69]
	v_mfma_f32_16x16x32_bf16 v[118:121], v[168:171], v[184:187], v[118:121]
	v_mfma_f32_16x16x32_bf16 v[114:117], v[176:179], v[184:187], v[114:117]
	v_mfma_f32_16x16x32_bf16 v[102:105], v[168:171], v[206:209], v[102:105]
	v_mfma_f32_16x16x32_bf16 v[98:101], v[176:179], v[206:209], v[98:101]
	v_mfma_f32_16x16x32_bf16 v[86:89], v[168:171], v[214:217], v[86:89]
	v_mfma_f32_16x16x32_bf16 v[82:85], v[176:179], v[214:217], v[82:85]
	v_mfma_f32_16x16x32_bf16 v[70:73], v[168:171], v[222:225], v[70:73]
	v_mfma_f32_16x16x32_bf16 v[66:69], v[176:179], v[222:225], v[66:69]
	s_setprio 0
	s_barrier
; #define PG8_STAGE(bufoff, gbase, voff) do { _Pragma("unroll") for (int _i = 0; _i < 2; ++_i) \
;         __builtin_amdgcn_global_load_lds((const unsigned*)((const char*)(gbase) + (voff)[_i]), (PG8_LAS unsigned*)(lds + (bufoff) + ldsw + _i * 8192), 16, 0, 0); } while (0)
; #define PG8_LDA(dst, b, h) do { _Pragma("unroll") for (int m = 0; m < 4; ++m) _Pragma("unroll") for (int k = 0; k < 2; ++k) dst[m][k] = *(const PG8_LAS bf16x8*)(lds + PG8_SA(b, h) + aoff + m * 2048 + k * 1024); } while (0)
; #define PG8_LDB(dst, b, h) do { _Pragma("unroll") for (int n = 0; n < 2; ++n) _Pragma("unroll") for (int k = 0; k < 2; ++k) dst[n][k] = *(const PG8_LAS bf16x8*)(lds + PG8_SB(b, h) + boff + n * 2048 + k * 1024); } while (0)
; template <class Epi, class Sched, bool ALIGN_EPI = false, bool SP2 = false>
; __device__ __forceinline__ void gemm_phase(PG8_LAS unsigned char* lds, const Gemm g, const Sched& S, const Epi& E) {
;     ...
;         for (int t = 0; t < nt; t += 2) {
;             const bool last = (t == nt - 2);
;             const char* a1 = cA + (size_t)(t + 1) * kstepA;
;             const char* a2 = last ? nA : cA + (size_t)(t + 2) * kstepA; const char* b2 = last ? nB : cB + (size_t)(t + 2) * kstep;
;             const char* a3 = a2 + kstepA; const char* b3 = b2 + kstep;
;             if (last && has_next) S.a_ready(nxt);
;             if constexpr (SP2) {
;             PG8_LDB(B0, 0, 0); PG8_LDB(B1, 0, 1); PG8_SCHED; PG8_LDA(At, 0, 0); PG8_STAGE(PG8_SA(1, 1), a1 + hstepA, voffA);
;             PG8_WAIT_V(8); PG8_WAIT_L(0); PG8_BAR; PG8_MMA(0, 0, At, B0); PG8_MMA(0, 1, At, B1); PG8_BAR; PG8_SCHED;
;             PG8_LDA(At, 0, 1); PG8_STAGE(PG8_SB(0, 0), b2, voffB); PG8_STAGE(PG8_SB(0, 1), b2 + hstepB, voffB); PG8_STAGE(PG8_SA(0, 0), a2, voffA);
;             PG8_WAIT_V(8); PG8_WAIT_L(0); PG8_BAR; PG8_MMA(1, 0, At, B0); PG8_MMA(1, 1, At, B1); PG8_BAR; PG8_SCHED;
;             PG8_LDB(B0, 1, 0); PG8_LDB(B1, 1, 1); PG8_SCHED; PG8_LDA(At, 1, 0); PG8_STAGE(PG8_SA(0, 1), a2 + hstepA, voffA);
;             PG8_WAIT_V(8); PG8_WAIT_L(0); PG8_BAR; PG8_MMA(0, 0, At, B0); PG8_MMA(0, 1, At, B1); PG8_BAR; PG8_SCHED;
;             PG8_LDA(At, 1, 1); PG8_STAGE(PG8_SB(1, 0), b3, voffB); PG8_STAGE(PG8_SB(1, 1), b3 + hstepB, voffB); PG8_STAGE(PG8_SA(1, 0), a3, voffA);
;             PG8_WAIT_V(8); PG8_WAIT_L(0); PG8_BAR; PG8_MMA(1, 0, At, B0); PG8_MMA(1, 1, At, B1); PG8_BAR; PG8_SCHED;
	s_add_i32 s22, s41, s24
	v_lshl_add_u64 v[146:147], v[146:147], 0, s[78:79]
	s_mov_b32 m0, s22
	ds_read_b128 v[180:183], v151 offset:49152
	ds_read_b128 v[184:187], v151 offset:50176
	ds_read_b128 v[188:191], v151 offset:51200
	ds_read_b128 v[206:209], v151 offset:52224
	ds_read_b128 v[210:213], v151 offset:53248
	ds_read_b128 v[214:217], v151 offset:54272
	ds_read_b128 v[218:221], v151 offset:55296
	ds_read_b128 v[222:225], v151 offset:56320
	global_load_lds_dwordx4 v[146:147], off
	s_add_i32 m0, s22, 0x2000
	s_add_u32 s20, s20, 0x40080
	v_lshl_add_u64 v[146:147], v[192:193], 0, s[78:79]
	s_addc_u32 s21, s21, 0
	s_add_i32 s22, s42, s24
	global_load_lds_dwordx4 v[146:147], off
	v_lshl_add_u64 v[146:147], s[20:21], 0, v[134:135]
	s_mov_b32 m0, s22
	s_nop 0
	global_load_lds_dwordx4 v[146:147], off
	v_lshl_add_u64 v[146:147], s[20:21], 0, v[130:131]
	s_add_i32 m0, s22, 0x2000
	s_nop 0
	global_load_lds_dwordx4 v[146:147], off
	v_lshl_add_u64 v[146:147], s[18:19], 0, v[136:137]
	s_mov_b32 m0, s29
	s_nop 0
	global_load_lds_dwordx4 v[146:147], off
	v_lshl_add_u64 v[146:147], s[18:19], 0, v[132:133]
	s_mov_b32 m0, s30
	s_nop 0
	global_load_lds_dwordx4 v[146:147], off
	s_waitcnt vmcnt(8)
	s_waitcnt lgkmcnt(0)
	s_barrier
	s_setprio 1
	s_waitcnt lgkmcnt(0)
	v_mfma_f32_16x16x32_bf16 v[62:65], v[142:145], v[180:183], v[62:65]
	v_mfma_f32_16x16x32_bf16 v[58:61], v[156:159], v[180:183], v[58:61]
	v_mfma_f32_16x16x32_bf16 v[46:49], v[142:145], v[188:191], v[46:49]
	v_mfma_f32_16x16x32_bf16 v[42:45], v[156:159], v[188:191], v[42:45]
	v_mfma_f32_16x16x32_bf16 v[30:33], v[142:145], v[210:213], v[30:33]
	v_mfma_f32_16x16x32_bf16 v[26:29], v[156:159], v[210:213], v[26:29]
	v_mfma_f32_16x16x32_bf16 v[14:17], v[142:145], v[218:221], v[14:17]
	v_mfma_f32_16x16x32_bf16 v[10:13], v[156:159], v[218:221], v[10:13]
	v_mfma_f32_16x16x32_bf16 v[62:65], v[152:155], v[184:187], v[62:65]
	v_mfma_f32_16x16x32_bf16 v[58:61], v[160:163], v[184:187], v[58:61]
	v_mfma_f32_16x16x32_bf16 v[46:49], v[152:155], v[206:209], v[46:49]
	v_mfma_f32_16x16x32_bf16 v[42:45], v[160:163], v[206:209], v[42:45]
	v_mfma_f32_16x16x32_bf16 v[30:33], v[152:155], v[214:217], v[30:33]
	v_mfma_f32_16x16x32_bf16 v[26:29], v[160:163], v[214:217], v[26:29]
	v_mfma_f32_16x16x32_bf16 v[14:17], v[152:155], v[222:225], v[14:17]
	v_mfma_f32_16x16x32_bf16 v[10:13], v[160:163], v[222:225], v[10:13]
	s_setprio 0
	s_setprio 1
	v_mfma_f32_16x16x32_bf16 v[54:57], v[164:167], v[180:183], v[54:57]
	v_mfma_f32_16x16x32_bf16 v[50:53], v[172:175], v[180:183], v[50:53]
	v_mfma_f32_16x16x32_bf16 v[38:41], v[164:167], v[188:191], v[38:41]
	v_mfma_f32_16x16x32_bf16 v[34:37], v[172:175], v[188:191], v[34:37]
	v_mfma_f32_16x16x32_bf16 v[22:25], v[164:167], v[210:213], v[22:25]
	v_mfma_f32_16x16x32_bf16 v[18:21], v[172:175], v[210:213], v[18:21]
	v_mfma_f32_16x16x32_bf16 v[6:9], v[164:167], v[218:221], v[6:9]
	v_mfma_f32_16x16x32_bf16 v[2:5], v[172:175], v[218:221], v[2:5]
	v_mfma_f32_16x16x32_bf16 v[54:57], v[168:171], v[184:187], v[54:57]
	v_mfma_f32_16x16x32_bf16 v[50:53], v[176:179], v[184:187], v[50:53]
	v_mfma_f32_16x16x32_bf16 v[38:41], v[168:171], v[206:209], v[38:41]
	v_mfma_f32_16x16x32_bf16 v[34:37], v[176:179], v[206:209], v[34:37]
	v_mfma_f32_16x16x32_bf16 v[22:25], v[168:171], v[214:217], v[22:25]
	v_mfma_f32_16x16x32_bf16 v[18:21], v[176:179], v[214:217], v[18:21]
	v_mfma_f32_16x16x32_bf16 v[6:9], v[168:171], v[222:225], v[6:9]
	v_mfma_f32_16x16x32_bf16 v[2:5], v[176:179], v[222:225], v[2:5]
	s_setprio 0
	s_add_i32 s40, s40, 2
	s_add_u32 s38, s38, 0x100
	s_addc_u32 s39, s39, 0
	s_add_u32 s6, s6, 0x400000
	s_addc_u32 s7, s7, 0
	s_add_u32 s18, s6, 0x1fc000
	s_addc_u32 s19, s7, 0
	s_cmp_eq_u32 s40, 12
	s_cselect_b32 s22, s36, s18
	s_cselect_b32 s23, s13, s19
	s_cselect_b32 s20, s37, s38
	s_cselect_b32 s21, s11, s39
	s_add_u32 s18, s22, 0x200000
	s_addc_u32 s19, s23, 0
	s_add_i32 s41, 0, 0x10000
	s_cmp_gt_u32 s40, 13
	s_barrier
	s_cbranch_scc0 .LBB0_333
	s_and_b64 vcc, exec, s[8:9]
	s_cbranch_vccz .LBB0_336
	s_barrier
